# mLSTM/GLA state and out phases: once-read 16-byte q/k/v/state tile loads issued nt
# speedup vs baseline: 1.0165x; 1.0075x over previous
; DEVI int otid() { int t = threadIdx.x; asm volatile("" : "+v"(t)); return t; }
; DEVI int obid() { int t = blockIdx.x; asm volatile("" : "+s"(t)); return t; }
; template <int KIND>
; DEVI void mix_state_phase(unsigned char* smem, const MixArgs a) {
;     const int tid = otid(), wid = tid >> 6, lane = tid & 63, fr = lane & 15, fq = lane >> 4;
;     float* fB = (float*)(smem + L_SM); float* fI = fB + 128; float* seg = fI + 256; float* gl = (float*)(smem + L_SM + 4096);
;     u16* VTF = (u16*)(smem + L_VTF); u16* KT = (u16*)(smem + L_KT); u16* RAWK = (u16*)(smem + L_RAWK);
;     u32x4 pvv[8], pkr[5]; float pg[4];
;     ...
;     if (obid() < 16 * NCH) ST_PREF(obid());
.LBB0_505:
	s_or_b64 exec, exec, s[2:3]
	v_readlane_b32 s0, v254, 5
	v_readlane_b32 s1, v254, 6
	s_mov_b64 s[2:3], -1
	s_and_b64 vcc, exec, s[0:1]
	s_waitcnt lgkmcnt(0)
	s_barrier
	s_cbranch_vccz .LBB0_520
	v_mov_b32_e32 v50, v154
	s_mov_b32 s0, s33
	v_and_b32_e32 v82, 15, v50
	v_ashrrev_i32_e32 v54, 5, v50
	v_add_u32_e32 v0, 0x200, v50
	v_add_u32_e32 v1, 0x400, v50
	v_add_u32_e32 v2, 0x600, v50
	v_add_u32_e32 v3, 0x800, v50
	v_add_u32_e32 v4, 0xa00, v50
	v_add_u32_e32 v5, 0xc00, v50
	v_add_u32_e32 v6, 0xe00, v50
	v_ashrrev_i32_e32 v56, 4, v50
	s_cmpk_gt_i32 s0, 0x3ff
	v_lshlrev_b32_e32 v83, 4, v50
	v_lshlrev_b32_e32 v52, 2, v82
	v_ashrrev_i32_e32 v55, 31, v54
	v_ashrrev_i32_e32 v58, 5, v0
	v_ashrrev_i32_e32 v60, 5, v1
	v_ashrrev_i32_e32 v62, 5, v2
	v_ashrrev_i32_e32 v64, 5, v3
	v_ashrrev_i32_e32 v66, 5, v4
	v_ashrrev_i32_e32 v68, 5, v5
	v_ashrrev_i32_e32 v70, 5, v6
	v_ashrrev_i32_e32 v57, 31, v56
	v_ashrrev_i32_e32 v72, 4, v0
	v_ashrrev_i32_e32 v74, 4, v1
	v_ashrrev_i32_e32 v76, 4, v2
	s_cbranch_scc1 .LBB0_508
	s_mov_b32 s0, s33
	s_ashr_i32 s1, s0, 31
	s_lshr_b32 s1, s1, 26
	s_add_i32 s1, s0, s1
	s_and_b32 s1, s1, 0x1ffffc0
	s_sub_i32 s2, s0, s1
	s_mov_b32 s0, s33
	s_ashr_i32 s1, s0, 31
	s_lshr_b32 s1, s1, 26
	s_add_i32 s0, s0, s1
	s_bfe_u32 s4, s0, 0x20006
	s_ashr_i32 s0, s0, 8
	s_ashr_i32 s1, s0, 31
	s_lshl_b32 s2, s2, 7
	s_lshl_b64 s[0:1], s[0:1], 13
	s_ashr_i32 s3, s2, 31
	s_add_u32 s2, s0, s2
	s_addc_u32 s3, s1, s3
	v_lshl_add_u64 v[0:1], s[2:3], 0, v[54:55]
	v_mov_b64_e32 v[46:47], s[28:29]
	v_ashrrev_i32_e32 v61, 31, v60
	v_ashrrev_i32_e32 v65, 31, v64
	v_ashrrev_i32_e32 v69, 31, v68
	v_mad_u64_u32 v[2:3], s[0:1], v0, s95, v[46:47]
	v_lshl_add_u64 v[10:11], s[2:3], 0, v[60:61]
	v_lshl_add_u64 v[18:19], s[2:3], 0, v[64:65]
	v_lshl_add_u64 v[26:27], s[2:3], 0, v[68:69]
	s_lshl_b32 s66, s4, 8
	s_lshl_b32 s0, s4, 9
	v_mad_u64_u32 v[12:13], s[4:5], v10, s95, v[46:47]
	v_mad_u64_u32 v[20:21], s[4:5], v18, s95, v[46:47]
	v_mad_u64_u32 v[28:29], s[4:5], v26, s95, v[46:47]
	v_mad_i32_i24 v3, v1, s95, v3
	s_mov_b32 s1, s67
	v_ashrrev_i32_e32 v59, 31, v58
	v_mad_i32_i24 v13, v11, s95, v13
	v_ashrrev_i32_e32 v63, 31, v62
	v_mad_i32_i24 v21, v19, s95, v21
	v_ashrrev_i32_e32 v67, 31, v66
	v_mad_i32_i24 v29, v27, s95, v29
	v_ashrrev_i32_e32 v71, 31, v70
	v_lshl_add_u64 v[0:1], v[2:3], 0, s[0:1]
	v_lshl_add_u64 v[2:3], s[2:3], 0, v[58:59]
	v_lshl_add_u64 v[10:11], v[12:13], 0, s[0:1]
	v_lshl_add_u64 v[12:13], s[2:3], 0, v[62:63]
	v_lshl_add_u64 v[18:19], v[20:21], 0, s[0:1]
	v_lshl_add_u64 v[20:21], s[2:3], 0, v[66:67]
	v_lshl_add_u64 v[26:27], v[28:29], 0, s[0:1]
	v_lshl_add_u64 v[28:29], s[2:3], 0, v[70:71]
	v_mad_u64_u32 v[4:5], s[4:5], v2, s95, v[46:47]
	v_mad_u64_u32 v[14:15], s[4:5], v12, s95, v[46:47]
	v_mad_u64_u32 v[22:23], s[4:5], v20, s95, v[46:47]
	v_mad_u64_u32 v[30:31], s[4:5], v28, s95, v[46:47]
	v_mad_i32_i24 v5, v3, s95, v5
	v_mad_i32_i24 v15, v13, s95, v15
	v_mad_i32_i24 v23, v21, s95, v23
	v_mad_i32_i24 v31, v29, s95, v31
	v_lshl_add_u64 v[34:35], s[2:3], 0, v[56:57]
	v_lshl_add_u64 v[2:3], v[4:5], 0, s[0:1]
	v_lshl_add_u64 v[12:13], v[14:15], 0, s[0:1]
	v_lshl_add_u64 v[20:21], v[22:23], 0, s[0:1]
	v_lshl_add_u64 v[28:29], v[30:31], 0, s[0:1]
	v_mad_u64_u32 v[36:37], s[0:1], v34, s95, v[46:47]
	v_and_b32_e32 v8, 0x1f0, v83
	v_mov_b32_e32 v53, v9
	v_mad_i32_i24 v37, v35, s95, v37
	v_lshl_add_u64 v[0:1], v[0:1], 0, v[8:9]
	v_lshl_add_u64 v[4:5], v[2:3], 0, v[8:9]
	v_lshl_add_u64 v[10:11], v[10:11], 0, v[8:9]
	v_lshl_add_u64 v[14:15], v[12:13], 0, v[8:9]
	v_lshl_add_u64 v[18:19], v[18:19], 0, v[8:9]
	v_lshl_add_u64 v[22:23], v[20:21], 0, v[8:9]
	v_lshl_add_u64 v[26:27], v[26:27], 0, v[8:9]
	v_lshl_add_u64 v[30:31], v[28:29], 0, v[8:9]
	v_lshl_add_u64 v[48:49], s[58:59], 0, v[52:53]
	v_lshl_add_u64 v[36:37], v[36:37], 0, s[66:67]
	v_lshlrev_b32_e32 v8, 4, v82
	v_lshlrev_b64 v[34:35], 6, v[34:35]
	v_lshl_add_u64 v[36:37], v[36:37], 0, v[8:9]
	v_lshl_add_u64 v[38:39], v[48:49], 0, v[34:35]
	v_ashrrev_i32_e32 v73, 31, v72
	global_load_dwordx4 v[0:3], v[0:1], off offset:2048 nt
	s_nop 0
	global_load_dwordx4 v[4:7], v[4:5], off offset:2048 nt
	s_nop 0
	global_load_dwordx4 v[10:13], v[10:11], off offset:2048 nt
	s_nop 0
	global_load_dwordx4 v[14:17], v[14:15], off offset:2048 nt
	s_nop 0
	global_load_dwordx4 v[18:21], v[18:19], off offset:2048 nt
	s_nop 0
	global_load_dwordx4 v[22:25], v[22:23], off offset:2048 nt
	s_nop 0
	global_load_dwordx4 v[26:29], v[26:27], off offset:2048 nt
	s_nop 0
	global_load_dwordx4 v[30:33], v[30:31], off offset:2048 nt
	s_nop 0
	global_load_dwordx4 v[34:37], v[36:37], off offset:1024 nt
	s_nop 0
	global_load_dword v85, v[38:39], off
	v_lshl_add_u64 v[38:39], s[2:3], 0, v[72:73]
	v_mad_u64_u32 v[40:41], s[0:1], v38, s95, v[46:47]
	v_mad_i32_i24 v41, v39, s95, v41
	v_lshl_add_u64 v[40:41], v[40:41], 0, s[66:67]
	v_lshlrev_b64 v[38:39], 6, v[38:39]
	v_lshl_add_u64 v[40:41], v[40:41], 0, v[8:9]
	v_lshl_add_u64 v[42:43], v[48:49], 0, v[38:39]
	v_ashrrev_i32_e32 v75, 31, v74
	global_load_dwordx4 v[38:41], v[40:41], off offset:1024 nt
	s_nop 0
	global_load_dword v97, v[42:43], off
	v_lshl_add_u64 v[42:43], s[2:3], 0, v[74:75]
	v_mad_u64_u32 v[44:45], s[0:1], v42, s95, v[46:47]
	v_mad_i32_i24 v45, v43, s95, v45
	v_lshl_add_u64 v[44:45], v[44:45], 0, s[66:67]
	v_lshlrev_b64 v[42:43], 6, v[42:43]
	v_lshl_add_u64 v[44:45], v[44:45], 0, v[8:9]
	v_lshl_add_u64 v[78:79], v[48:49], 0, v[42:43]
	v_ashrrev_i32_e32 v77, 31, v76
	global_load_dwordx4 v[42:45], v[44:45], off offset:1024 nt
	s_nop 0
	global_load_dword v98, v[78:79], off
	v_lshl_add_u64 v[78:79], s[2:3], 0, v[76:77]
	v_mad_u64_u32 v[46:47], s[0:1], v78, s95, v[46:47]
	v_mad_i32_i24 v47, v79, s95, v47
	v_lshl_add_u64 v[46:47], v[46:47], 0, s[66:67]
	v_lshl_add_u64 v[46:47], v[46:47], 0, v[8:9]
	v_lshlrev_b64 v[78:79], 6, v[78:79]
	v_lshl_add_u64 v[78:79], v[48:49], 0, v[78:79]
	global_load_dwordx4 v[46:49], v[46:47], off offset:1024 nt
	s_nop 0
	global_load_dword v87, v[78:79], off

; DEVI float logsigf_(float x) { return fminf(x, 0.f) - __logf(1.f + __expf(-fabsf(x))); }
; DEVI float gla_la(const float* gl, int t, const float* w2r, float gb) { float x = gb;
; #pragma unroll
;     for (int r = 0; r < 16; ++r) x += gl[t * 16 + r] * w2r[r];
;     return logsigf_(x) * (1.f / 16.f); }
; template <int KIND>
; DEVI void mix_state_phase(unsigned char* smem, const MixArgs a) {
;     ...
;             for (int t = sg * 32; t < sg * 32 + 32; ++t) ssum += gla_la(gl, t, w2r, gb);
.LBB0_514:
	v_add_u32_e32 v123, s0, v99
	ds_read_b128 v[124:127], v123
	ds_read_b128 v[128:131], v123 offset:16
	ds_read_b128 v[132:135], v123 offset:32
	ds_read_b128 v[136:139], v123 offset:48
	ds_read_b128 v[176:179], v123 offset:64
	ds_read_b128 v[180:183], v123 offset:80
	ds_read_b128 v[184:187], v123 offset:96
	ds_read_b128 v[188:191], v123 offset:112
	s_addk_i32 s0, 0x80
	s_waitcnt vmcnt(1) lgkmcnt(7)
	v_fma_f32 v140, v119, v124, v8
	v_fmac_f32_e32 v140, v120, v125
	v_fmac_f32_e32 v140, v116, v126
	v_fmac_f32_e32 v140, v121, v127
	s_waitcnt lgkmcnt(6)
	v_fmac_f32_e32 v140, v117, v128
	v_fmac_f32_e32 v140, v118, v129
	v_pk_mul_f32 v[124:125], v[50:51], v[130:131]
	v_add_f32_e32 v124, v140, v124
	v_add_f32_e32 v126, v124, v125
	s_waitcnt lgkmcnt(5)
	v_pk_mul_f32 v[124:125], v[52:53], v[132:133]
	s_nop 0
	v_add_f32_e32 v124, v126, v124
	v_add_f32_e32 v126, v124, v125
	v_pk_mul_f32 v[124:125], v[88:89], v[134:135]
	s_nop 0
	v_add_f32_e32 v124, v126, v124
	v_add_f32_e32 v126, v124, v125
	s_waitcnt lgkmcnt(4)
	v_pk_mul_f32 v[124:125], v[90:91], v[136:137]
	s_nop 0
	v_add_f32_e32 v124, v126, v124
	v_add_f32_e32 v126, v124, v125
	s_waitcnt vmcnt(0)
	v_pk_mul_f32 v[124:125], v[92:93], v[138:139]
	s_nop 0
	v_add_f32_e32 v124, v126, v124
	v_add_f32_e32 v124, v124, v125
	v_min_f32_e32 v125, 0, v124
	v_mul_f32_e64 v124, |v124|, s73
	v_exp_f32_e32 v124, v124
	s_nop 0
	v_add_f32_e32 v124, 1.0, v124
	v_cmp_gt_f32_e32 vcc, s94, v124
	s_nop 1
	v_cndmask_b32_e64 v126, 0, 32, vcc
	v_ldexp_f32 v124, v124, v126
	v_log_f32_e32 v124, v124
	s_nop 0
	v_mul_f32_e32 v126, 0x3f317217, v124
	v_fma_f32 v126, v124, s97, -v126
	v_fmac_f32_e32 v126, 0x3377d1cf, v124
	v_fmac_f32_e32 v126, 0x3f317217, v124
	v_cmp_lt_f32_e64 s[12:13], |v124|, s23
	s_nop 1
	v_cndmask_b32_e64 v124, v124, v126, s[12:13]
	v_cndmask_b32_e32 v126, 0, v211, vcc
	v_sub_f32_e32 v124, v124, v126
	v_sub_f32_e32 v124, v125, v124
	v_fmac_f32_e32 v122, 0x3d800000, v124
	v_mov_b32_e32 v192, v124
	s_waitcnt lgkmcnt(0)
	v_fma_f32 v128, v119, v176, v8
	v_fmac_f32_e32 v128, v120, v177
	v_fmac_f32_e32 v128, v116, v178
	v_fmac_f32_e32 v128, v121, v179
	v_fmac_f32_e32 v128, v117, v180
	v_fmac_f32_e32 v128, v118, v181
	v_pk_mul_f32 v[124:125], v[50:51], v[182:183]
	s_nop 0
	v_add_f32_e32 v124, v128, v124
	v_add_f32_e32 v128, v124, v125
	v_pk_mul_f32 v[124:125], v[52:53], v[184:185]
	s_nop 0
	v_add_f32_e32 v124, v128, v124
	v_add_f32_e32 v128, v124, v125
	v_pk_mul_f32 v[124:125], v[88:89], v[186:187]
	s_nop 0
	v_add_f32_e32 v124, v128, v124
	v_add_f32_e32 v128, v124, v125
	v_pk_mul_f32 v[124:125], v[90:91], v[188:189]
	s_nop 0
	v_add_f32_e32 v123, v128, v124
	v_add_f32_e32 v123, v123, v125
	v_pk_mul_f32 v[124:125], v[92:93], v[190:191]
	s_nop 0
	v_add_f32_e32 v123, v123, v124
	v_add_f32_e32 v123, v123, v125
	v_min_f32_e32 v124, 0, v123
	v_mul_f32_e64 v123, |v123|, s73
	v_exp_f32_e32 v123, v123
	s_nop 0
	v_add_f32_e32 v123, 1.0, v123
	v_cmp_gt_f32_e32 vcc, s94, v123
	s_nop 1
	v_cndmask_b32_e64 v125, 0, 32, vcc
	v_ldexp_f32 v123, v123, v125
	v_log_f32_e32 v123, v123
	s_nop 0
	v_mul_f32_e32 v125, 0x3f317217, v123
	v_fma_f32 v125, v123, s97, -v125
	v_fmac_f32_e32 v125, 0x3377d1cf, v123
	v_fmac_f32_e32 v125, 0x3f317217, v123
	v_cmp_lt_f32_e64 s[12:13], |v123|, s23
	s_nop 1
	v_cndmask_b32_e64 v123, v123, v125, s[12:13]
	v_cndmask_b32_e32 v125, 0, v211, vcc
	v_sub_f32_e32 v123, v123, v125
	v_sub_f32_e32 v123, v124, v123
	v_fmac_f32_e32 v122, 0x3d800000, v123
	v_mov_b32_e32 v193, v123
	v_add_u32_e32 v123, s0, v99
	ds_read_b128 v[124:127], v123
	ds_read_b128 v[128:131], v123 offset:16
	ds_read_b128 v[132:135], v123 offset:32
	ds_read_b128 v[136:139], v123 offset:48
	ds_read_b128 v[176:179], v123 offset:64
	ds_read_b128 v[180:183], v123 offset:80
	ds_read_b128 v[184:187], v123 offset:96
	ds_read_b128 v[188:191], v123 offset:112
	s_addk_i32 s0, 0x80
	s_waitcnt vmcnt(1) lgkmcnt(7)
	v_fma_f32 v140, v119, v124, v8
	v_fmac_f32_e32 v140, v120, v125
	v_fmac_f32_e32 v140, v116, v126
	v_fmac_f32_e32 v140, v121, v127
	s_waitcnt lgkmcnt(6)
	v_fmac_f32_e32 v140, v117, v128
	v_fmac_f32_e32 v140, v118, v129
	v_pk_mul_f32 v[124:125], v[50:51], v[130:131]
	v_add_f32_e32 v124, v140, v124
	v_add_f32_e32 v126, v124, v125
	s_waitcnt lgkmcnt(5)
	v_pk_mul_f32 v[124:125], v[52:53], v[132:133]
	s_nop 0
	v_add_f32_e32 v124, v126, v124
	v_add_f32_e32 v126, v124, v125
	v_pk_mul_f32 v[124:125], v[88:89], v[134:135]
	s_nop 0
	v_add_f32_e32 v124, v126, v124
	v_add_f32_e32 v126, v124, v125
	s_waitcnt lgkmcnt(4)
	v_pk_mul_f32 v[124:125], v[90:91], v[136:137]
	s_nop 0
	v_add_f32_e32 v124, v126, v124
	v_add_f32_e32 v126, v124, v125
	s_waitcnt vmcnt(0)
	v_pk_mul_f32 v[124:125], v[92:93], v[138:139]
	s_nop 0
	v_add_f32_e32 v124, v126, v124
	v_add_f32_e32 v124, v124, v125
	v_min_f32_e32 v125, 0, v124
	v_mul_f32_e64 v124, |v124|, s73
	v_exp_f32_e32 v124, v124
	s_nop 0
	v_add_f32_e32 v124, 1.0, v124
	v_cmp_gt_f32_e32 vcc, s94, v124
	s_nop 1
	v_cndmask_b32_e64 v126, 0, 32, vcc
	v_ldexp_f32 v124, v124, v126
	v_log_f32_e32 v124, v124
	s_nop 0
	v_mul_f32_e32 v126, 0x3f317217, v124
	v_fma_f32 v126, v124, s97, -v126
	v_fmac_f32_e32 v126, 0x3377d1cf, v124
	v_fmac_f32_e32 v126, 0x3f317217, v124
	v_cmp_lt_f32_e64 s[12:13], |v124|, s23
	s_nop 1
	v_cndmask_b32_e64 v124, v124, v126, s[12:13]
	v_cndmask_b32_e32 v126, 0, v211, vcc
	v_sub_f32_e32 v124, v124, v126
	v_sub_f32_e32 v124, v125, v124
	v_fmac_f32_e32 v122, 0x3d800000, v124
	v_mov_b32_e32 v194, v124
	s_waitcnt lgkmcnt(0)
; DEVI float logsigf_(float x) { return fminf(x, 0.f) - __logf(1.f + __expf(-fabsf(x))); }
; DEVI float gla_la(const float* gl, int t, const float* w2r, float gb) { float x = gb;
; #pragma unroll
;     for (int r = 0; r < 16; ++r) x += gl[t * 16 + r] * w2r[r];
;     return logsigf_(x) * (1.f / 16.f); }
; template <int KIND>
; DEVI void mix_state_phase(unsigned char* smem, const MixArgs a) {
;     ...
;             for (int t = sg * 32; t < sg * 32 + 32; ++t) ssum += gla_la(gl, t, w2r, gb);
	v_fma_f32 v128, v119, v176, v8
	v_fmac_f32_e32 v128, v120, v177
	v_fmac_f32_e32 v128, v116, v178
	v_fmac_f32_e32 v128, v121, v179
	v_fmac_f32_e32 v128, v117, v180
	v_fmac_f32_e32 v128, v118, v181
	v_pk_mul_f32 v[124:125], v[50:51], v[182:183]
	s_nop 0
	v_add_f32_e32 v124, v128, v124
	v_add_f32_e32 v128, v124, v125
	v_pk_mul_f32 v[124:125], v[52:53], v[184:185]
	s_nop 0
	v_add_f32_e32 v124, v128, v124
	v_add_f32_e32 v128, v124, v125
	v_pk_mul_f32 v[124:125], v[88:89], v[186:187]
	s_nop 0
	v_add_f32_e32 v124, v128, v124
	v_add_f32_e32 v128, v124, v125
	v_pk_mul_f32 v[124:125], v[90:91], v[188:189]
	s_nop 0
	v_add_f32_e32 v123, v128, v124
	v_add_f32_e32 v123, v123, v125
	v_pk_mul_f32 v[124:125], v[92:93], v[190:191]
	s_nop 0
	v_add_f32_e32 v123, v123, v124
	v_add_f32_e32 v123, v123, v125
	v_min_f32_e32 v124, 0, v123
	v_mul_f32_e64 v123, |v123|, s73
	v_exp_f32_e32 v123, v123
	s_nop 0
	v_add_f32_e32 v123, 1.0, v123
	v_cmp_gt_f32_e32 vcc, s94, v123
	s_nop 1
	v_cndmask_b32_e64 v125, 0, 32, vcc
	v_ldexp_f32 v123, v123, v125
	v_log_f32_e32 v123, v123
	s_nop 0
	v_mul_f32_e32 v125, 0x3f317217, v123
	v_fma_f32 v125, v123, s97, -v125
	v_fmac_f32_e32 v125, 0x3377d1cf, v123
	v_fmac_f32_e32 v125, 0x3f317217, v123
	v_cmp_lt_f32_e64 s[12:13], |v123|, s23
	s_nop 1
	v_cndmask_b32_e64 v123, v123, v125, s[12:13]
	v_cndmask_b32_e32 v125, 0, v211, vcc
	v_sub_f32_e32 v123, v123, v125
	v_sub_f32_e32 v123, v124, v123
	v_fmac_f32_e32 v122, 0x3d800000, v123
	v_mov_b32_e32 v195, v123
	v_add_u32_e32 v123, s0, v99
	ds_read_b128 v[124:127], v123
	ds_read_b128 v[128:131], v123 offset:16
	ds_read_b128 v[132:135], v123 offset:32
	ds_read_b128 v[136:139], v123 offset:48
	ds_read_b128 v[176:179], v123 offset:64
	ds_read_b128 v[180:183], v123 offset:80
	ds_read_b128 v[184:187], v123 offset:96
	ds_read_b128 v[188:191], v123 offset:112
	s_addk_i32 s0, 0x80
	s_waitcnt vmcnt(1) lgkmcnt(7)
	v_fma_f32 v140, v119, v124, v8
	v_fmac_f32_e32 v140, v120, v125
	v_fmac_f32_e32 v140, v116, v126
	v_fmac_f32_e32 v140, v121, v127
	s_waitcnt lgkmcnt(6)
	v_fmac_f32_e32 v140, v117, v128
	v_fmac_f32_e32 v140, v118, v129
	v_pk_mul_f32 v[124:125], v[50:51], v[130:131]
	v_add_f32_e32 v124, v140, v124
	v_add_f32_e32 v126, v124, v125
	s_waitcnt lgkmcnt(5)
	v_pk_mul_f32 v[124:125], v[52:53], v[132:133]
	s_nop 0
	v_add_f32_e32 v124, v126, v124
	v_add_f32_e32 v126, v124, v125
	v_pk_mul_f32 v[124:125], v[88:89], v[134:135]
	s_nop 0
	v_add_f32_e32 v124, v126, v124
	v_add_f32_e32 v126, v124, v125
	s_waitcnt lgkmcnt(4)
	v_pk_mul_f32 v[124:125], v[90:91], v[136:137]
	s_nop 0
	v_add_f32_e32 v124, v126, v124
	v_add_f32_e32 v126, v124, v125
	s_waitcnt vmcnt(0)
	v_pk_mul_f32 v[124:125], v[92:93], v[138:139]
	s_nop 0
	v_add_f32_e32 v124, v126, v124
	v_add_f32_e32 v124, v124, v125
	v_min_f32_e32 v125, 0, v124
	v_mul_f32_e64 v124, |v124|, s73
	v_exp_f32_e32 v124, v124
	s_nop 0
	v_add_f32_e32 v124, 1.0, v124
	v_cmp_gt_f32_e32 vcc, s94, v124
	s_nop 1
	v_cndmask_b32_e64 v126, 0, 32, vcc
	v_ldexp_f32 v124, v124, v126
	v_log_f32_e32 v124, v124
	s_nop 0
	v_mul_f32_e32 v126, 0x3f317217, v124
	v_fma_f32 v126, v124, s97, -v126
	v_fmac_f32_e32 v126, 0x3377d1cf, v124
	v_fmac_f32_e32 v126, 0x3f317217, v124
	v_cmp_lt_f32_e64 s[12:13], |v124|, s23
	s_nop 1
	v_cndmask_b32_e64 v124, v124, v126, s[12:13]
	v_cndmask_b32_e32 v126, 0, v211, vcc
	v_sub_f32_e32 v124, v124, v126
	v_sub_f32_e32 v124, v125, v124
	v_fmac_f32_e32 v122, 0x3d800000, v124
	v_mov_b32_e32 v196, v124
	s_waitcnt lgkmcnt(0)
	v_fma_f32 v128, v119, v176, v8
	v_fmac_f32_e32 v128, v120, v177
	v_fmac_f32_e32 v128, v116, v178
	v_fmac_f32_e32 v128, v121, v179
	v_fmac_f32_e32 v128, v117, v180
	v_fmac_f32_e32 v128, v118, v181
	v_pk_mul_f32 v[124:125], v[50:51], v[182:183]
	s_nop 0
	v_add_f32_e32 v124, v128, v124
	v_add_f32_e32 v128, v124, v125
	v_pk_mul_f32 v[124:125], v[52:53], v[184:185]
	s_nop 0
	v_add_f32_e32 v124, v128, v124
	v_add_f32_e32 v128, v124, v125
	v_pk_mul_f32 v[124:125], v[88:89], v[186:187]
	s_nop 0
	v_add_f32_e32 v124, v128, v124
	v_add_f32_e32 v128, v124, v125
	v_pk_mul_f32 v[124:125], v[90:91], v[188:189]
	s_nop 0
	v_add_f32_e32 v123, v128, v124
	v_add_f32_e32 v123, v123, v125
	v_pk_mul_f32 v[124:125], v[92:93], v[190:191]
	s_nop 0
	v_add_f32_e32 v123, v123, v124
	v_add_f32_e32 v123, v123, v125
	v_min_f32_e32 v124, 0, v123
	v_mul_f32_e64 v123, |v123|, s73
	v_exp_f32_e32 v123, v123
	s_nop 0
	v_add_f32_e32 v123, 1.0, v123
	v_cmp_gt_f32_e32 vcc, s94, v123
	s_nop 1
	v_cndmask_b32_e64 v125, 0, 32, vcc
	v_ldexp_f32 v123, v123, v125
	v_log_f32_e32 v123, v123
	s_nop 0
	v_mul_f32_e32 v125, 0x3f317217, v123
	v_fma_f32 v125, v123, s97, -v125
	v_fmac_f32_e32 v125, 0x3377d1cf, v123
	v_fmac_f32_e32 v125, 0x3f317217, v123
	v_cmp_lt_f32_e64 s[12:13], |v123|, s23
	s_nop 1
	v_cndmask_b32_e64 v123, v123, v125, s[12:13]
	v_cndmask_b32_e32 v125, 0, v211, vcc
	v_sub_f32_e32 v123, v123, v125
	v_sub_f32_e32 v123, v124, v123
	v_fmac_f32_e32 v122, 0x3d800000, v123
	v_mov_b32_e32 v197, v123
	v_add_u32_e32 v123, s0, v99
	ds_read_b128 v[124:127], v123
	ds_read_b128 v[128:131], v123 offset:16
	ds_read_b128 v[132:135], v123 offset:32
	ds_read_b128 v[136:139], v123 offset:48
	ds_read_b128 v[176:179], v123 offset:64
	ds_read_b128 v[180:183], v123 offset:80
	ds_read_b128 v[184:187], v123 offset:96
	ds_read_b128 v[188:191], v123 offset:112
	s_addk_i32 s0, 0x80
	s_waitcnt vmcnt(1) lgkmcnt(7)
	v_fma_f32 v140, v119, v124, v8
	v_fmac_f32_e32 v140, v120, v125
	v_fmac_f32_e32 v140, v116, v126
	v_fmac_f32_e32 v140, v121, v127
	s_waitcnt lgkmcnt(6)
	v_fmac_f32_e32 v140, v117, v128
	v_fmac_f32_e32 v140, v118, v129
	v_pk_mul_f32 v[124:125], v[50:51], v[130:131]
	v_add_f32_e32 v124, v140, v124
	v_add_f32_e32 v126, v124, v125
	s_waitcnt lgkmcnt(5)
; DEVI float logsigf_(float x) { return fminf(x, 0.f) - __logf(1.f + __expf(-fabsf(x))); }
; DEVI float gla_la(const float* gl, int t, const float* w2r, float gb) { float x = gb;
; #pragma unroll
;     for (int r = 0; r < 16; ++r) x += gl[t * 16 + r] * w2r[r];
;     return logsigf_(x) * (1.f / 16.f); }
; template <int KIND>
; DEVI void mix_state_phase(unsigned char* smem, const MixArgs a) {
;     ...
;             for (int t = sg * 32; t < sg * 32 + 32; ++t) ssum += gla_la(gl, t, w2r, gb);
	v_pk_mul_f32 v[124:125], v[52:53], v[132:133]
	s_nop 0
	v_add_f32_e32 v124, v126, v124
	v_add_f32_e32 v126, v124, v125
	v_pk_mul_f32 v[124:125], v[88:89], v[134:135]
	s_nop 0
	v_add_f32_e32 v124, v126, v124
	v_add_f32_e32 v126, v124, v125
	s_waitcnt lgkmcnt(4)
	v_pk_mul_f32 v[124:125], v[90:91], v[136:137]
	s_nop 0
	v_add_f32_e32 v124, v126, v124
	v_add_f32_e32 v126, v124, v125
	s_waitcnt vmcnt(0)
	v_pk_mul_f32 v[124:125], v[92:93], v[138:139]
	s_nop 0
	v_add_f32_e32 v124, v126, v124
	v_add_f32_e32 v124, v124, v125
	v_min_f32_e32 v125, 0, v124
	v_mul_f32_e64 v124, |v124|, s73
	v_exp_f32_e32 v124, v124
	s_nop 0
	v_add_f32_e32 v124, 1.0, v124
	v_cmp_gt_f32_e32 vcc, s94, v124
	s_nop 1
	v_cndmask_b32_e64 v126, 0, 32, vcc
	v_ldexp_f32 v124, v124, v126
	v_log_f32_e32 v124, v124
	s_nop 0
	v_mul_f32_e32 v126, 0x3f317217, v124
	v_fma_f32 v126, v124, s97, -v126
	v_fmac_f32_e32 v126, 0x3377d1cf, v124
	v_fmac_f32_e32 v126, 0x3f317217, v124
	v_cmp_lt_f32_e64 s[12:13], |v124|, s23
	s_nop 1
	v_cndmask_b32_e64 v124, v124, v126, s[12:13]
	v_cndmask_b32_e32 v126, 0, v211, vcc
	v_sub_f32_e32 v124, v124, v126
	v_sub_f32_e32 v124, v125, v124
	v_fmac_f32_e32 v122, 0x3d800000, v124
	v_mov_b32_e32 v198, v124
	s_waitcnt lgkmcnt(0)
	v_fma_f32 v128, v119, v176, v8
	v_fmac_f32_e32 v128, v120, v177
	v_fmac_f32_e32 v128, v116, v178
	v_fmac_f32_e32 v128, v121, v179
	v_fmac_f32_e32 v128, v117, v180
	v_fmac_f32_e32 v128, v118, v181
	v_pk_mul_f32 v[124:125], v[50:51], v[182:183]
	s_nop 0
	v_add_f32_e32 v124, v128, v124
	v_add_f32_e32 v128, v124, v125
	v_pk_mul_f32 v[124:125], v[52:53], v[184:185]
	s_nop 0
	v_add_f32_e32 v124, v128, v124
	v_add_f32_e32 v128, v124, v125
	v_pk_mul_f32 v[124:125], v[88:89], v[186:187]
	s_nop 0
	v_add_f32_e32 v124, v128, v124
	v_add_f32_e32 v128, v124, v125
	v_pk_mul_f32 v[124:125], v[90:91], v[188:189]
	s_nop 0
	v_add_f32_e32 v123, v128, v124
	v_add_f32_e32 v123, v123, v125
	v_pk_mul_f32 v[124:125], v[92:93], v[190:191]
	s_nop 0
	v_add_f32_e32 v123, v123, v124
	v_add_f32_e32 v123, v123, v125
	v_min_f32_e32 v124, 0, v123
	v_mul_f32_e64 v123, |v123|, s73
	v_exp_f32_e32 v123, v123
	s_nop 0
	v_add_f32_e32 v123, 1.0, v123
	v_cmp_gt_f32_e32 vcc, s94, v123
	s_nop 1
	v_cndmask_b32_e64 v125, 0, 32, vcc
	v_ldexp_f32 v123, v123, v125
	v_log_f32_e32 v123, v123
	s_nop 0
	v_mul_f32_e32 v125, 0x3f317217, v123
	v_fma_f32 v125, v123, s97, -v125
	v_fmac_f32_e32 v125, 0x3377d1cf, v123
	v_fmac_f32_e32 v125, 0x3f317217, v123
	v_cmp_lt_f32_e64 s[12:13], |v123|, s23
	s_nop 1
	v_cndmask_b32_e64 v123, v123, v125, s[12:13]
	v_cndmask_b32_e32 v125, 0, v211, vcc
	v_sub_f32_e32 v123, v123, v125
	v_sub_f32_e32 v123, v124, v123
	v_fmac_f32_e32 v122, 0x3d800000, v123
	v_mov_b32_e32 v199, v123
	v_add_u32_e32 v123, s0, v99
	ds_read_b128 v[124:127], v123
	ds_read_b128 v[128:131], v123 offset:16
	ds_read_b128 v[132:135], v123 offset:32
	ds_read_b128 v[136:139], v123 offset:48
	ds_read_b128 v[176:179], v123 offset:64
	ds_read_b128 v[180:183], v123 offset:80
	ds_read_b128 v[184:187], v123 offset:96
	ds_read_b128 v[188:191], v123 offset:112
	s_addk_i32 s0, 0x80
	s_waitcnt vmcnt(1) lgkmcnt(7)
	v_fma_f32 v140, v119, v124, v8
	v_fmac_f32_e32 v140, v120, v125
	v_fmac_f32_e32 v140, v116, v126
	v_fmac_f32_e32 v140, v121, v127
	s_waitcnt lgkmcnt(6)
	v_fmac_f32_e32 v140, v117, v128
	v_fmac_f32_e32 v140, v118, v129
	v_pk_mul_f32 v[124:125], v[50:51], v[130:131]
	v_add_f32_e32 v124, v140, v124
	v_add_f32_e32 v126, v124, v125
	s_waitcnt lgkmcnt(5)
	v_pk_mul_f32 v[124:125], v[52:53], v[132:133]
	s_nop 0
	v_add_f32_e32 v124, v126, v124
	v_add_f32_e32 v126, v124, v125
	v_pk_mul_f32 v[124:125], v[88:89], v[134:135]
	s_nop 0
	v_add_f32_e32 v124, v126, v124
	v_add_f32_e32 v126, v124, v125
	s_waitcnt lgkmcnt(4)
	v_pk_mul_f32 v[124:125], v[90:91], v[136:137]
	s_nop 0
	v_add_f32_e32 v124, v126, v124
	v_add_f32_e32 v126, v124, v125
	s_waitcnt vmcnt(0)
	v_pk_mul_f32 v[124:125], v[92:93], v[138:139]
	s_nop 0
	v_add_f32_e32 v124, v126, v124
	v_add_f32_e32 v124, v124, v125
	v_min_f32_e32 v125, 0, v124
	v_mul_f32_e64 v124, |v124|, s73
	v_exp_f32_e32 v124, v124
	s_nop 0
	v_add_f32_e32 v124, 1.0, v124
	v_cmp_gt_f32_e32 vcc, s94, v124
	s_nop 1
	v_cndmask_b32_e64 v126, 0, 32, vcc
	v_ldexp_f32 v124, v124, v126
	v_log_f32_e32 v124, v124
	s_nop 0
	v_mul_f32_e32 v126, 0x3f317217, v124
	v_fma_f32 v126, v124, s97, -v126
	v_fmac_f32_e32 v126, 0x3377d1cf, v124
	v_fmac_f32_e32 v126, 0x3f317217, v124
	v_cmp_lt_f32_e64 s[12:13], |v124|, s23
	s_nop 1
	v_cndmask_b32_e64 v124, v124, v126, s[12:13]
	v_cndmask_b32_e32 v126, 0, v211, vcc
	v_sub_f32_e32 v124, v124, v126
	v_sub_f32_e32 v124, v125, v124
	v_fmac_f32_e32 v122, 0x3d800000, v124
	v_mov_b32_e32 v200, v124
	s_waitcnt lgkmcnt(0)
	v_fma_f32 v128, v119, v176, v8
	v_fmac_f32_e32 v128, v120, v177
	v_fmac_f32_e32 v128, v116, v178
	v_fmac_f32_e32 v128, v121, v179
	v_fmac_f32_e32 v128, v117, v180
	v_fmac_f32_e32 v128, v118, v181
	v_pk_mul_f32 v[124:125], v[50:51], v[182:183]
	s_nop 0
	v_add_f32_e32 v124, v128, v124
	v_add_f32_e32 v128, v124, v125
	v_pk_mul_f32 v[124:125], v[52:53], v[184:185]
	s_nop 0
	v_add_f32_e32 v124, v128, v124
	v_add_f32_e32 v128, v124, v125
	v_pk_mul_f32 v[124:125], v[88:89], v[186:187]
	s_nop 0
	v_add_f32_e32 v124, v128, v124
	v_add_f32_e32 v128, v124, v125
	v_pk_mul_f32 v[124:125], v[90:91], v[188:189]
	s_nop 0
	v_add_f32_e32 v123, v128, v124
	v_add_f32_e32 v123, v123, v125
	v_pk_mul_f32 v[124:125], v[92:93], v[190:191]
	s_nop 0
	v_add_f32_e32 v123, v123, v124
	v_add_f32_e32 v123, v123, v125
	v_min_f32_e32 v124, 0, v123
	v_mul_f32_e64 v123, |v123|, s73
	v_exp_f32_e32 v123, v123
	s_nop 0
	v_add_f32_e32 v123, 1.0, v123
	v_cmp_gt_f32_e32 vcc, s94, v123
	s_nop 1
	v_cndmask_b32_e64 v125, 0, 32, vcc
	v_ldexp_f32 v123, v123, v125
	v_log_f32_e32 v123, v123
	s_nop 0
	v_mul_f32_e32 v125, 0x3f317217, v123
	v_fma_f32 v125, v123, s97, -v125
	v_fmac_f32_e32 v125, 0x3377d1cf, v123
	v_fmac_f32_e32 v125, 0x3f317217, v123
	v_cmp_lt_f32_e64 s[12:13], |v123|, s23
	s_nop 1
	v_cndmask_b32_e64 v123, v123, v125, s[12:13]
	v_cndmask_b32_e32 v125, 0, v211, vcc
	v_sub_f32_e32 v123, v123, v125
	v_sub_f32_e32 v123, v124, v123
	v_fmac_f32_e32 v122, 0x3d800000, v123
	v_mov_b32_e32 v201, v123
	v_add_u32_e32 v123, s0, v99
	ds_read_b128 v[124:127], v123
	ds_read_b128 v[128:131], v123 offset:16
	ds_read_b128 v[132:135], v123 offset:32
	ds_read_b128 v[136:139], v123 offset:48
	ds_read_b128 v[176:179], v123 offset:64
	ds_read_b128 v[180:183], v123 offset:80
	ds_read_b128 v[184:187], v123 offset:96
	ds_read_b128 v[188:191], v123 offset:112
	s_addk_i32 s0, 0x80
	s_waitcnt vmcnt(1) lgkmcnt(7)
; DEVI float logsigf_(float x) { return fminf(x, 0.f) - __logf(1.f + __expf(-fabsf(x))); }
; DEVI float gla_la(const float* gl, int t, const float* w2r, float gb) { float x = gb;
; #pragma unroll
;     for (int r = 0; r < 16; ++r) x += gl[t * 16 + r] * w2r[r];
;     return logsigf_(x) * (1.f / 16.f); }
; template <int KIND>
; DEVI void mix_state_phase(unsigned char* smem, const MixArgs a) {
;     ...
;             for (int t = sg * 32; t < sg * 32 + 32; ++t) ssum += gla_la(gl, t, w2r, gb);
	v_fma_f32 v140, v119, v124, v8
	v_fmac_f32_e32 v140, v120, v125
	v_fmac_f32_e32 v140, v116, v126
	v_fmac_f32_e32 v140, v121, v127
	s_waitcnt lgkmcnt(6)
	v_fmac_f32_e32 v140, v117, v128
	v_fmac_f32_e32 v140, v118, v129
	v_pk_mul_f32 v[124:125], v[50:51], v[130:131]
	v_add_f32_e32 v124, v140, v124
	v_add_f32_e32 v126, v124, v125
	s_waitcnt lgkmcnt(5)
	v_pk_mul_f32 v[124:125], v[52:53], v[132:133]
	s_nop 0
	v_add_f32_e32 v124, v126, v124
	v_add_f32_e32 v126, v124, v125
	v_pk_mul_f32 v[124:125], v[88:89], v[134:135]
	s_nop 0
	v_add_f32_e32 v124, v126, v124
	v_add_f32_e32 v126, v124, v125
	s_waitcnt lgkmcnt(4)
	v_pk_mul_f32 v[124:125], v[90:91], v[136:137]
	s_nop 0
	v_add_f32_e32 v124, v126, v124
	v_add_f32_e32 v126, v124, v125
	s_waitcnt vmcnt(0)
	v_pk_mul_f32 v[124:125], v[92:93], v[138:139]
	s_nop 0
	v_add_f32_e32 v124, v126, v124
	v_add_f32_e32 v124, v124, v125
	v_min_f32_e32 v125, 0, v124
	v_mul_f32_e64 v124, |v124|, s73
	v_exp_f32_e32 v124, v124
	s_nop 0
	v_add_f32_e32 v124, 1.0, v124
	v_cmp_gt_f32_e32 vcc, s94, v124
	s_nop 1
	v_cndmask_b32_e64 v126, 0, 32, vcc
	v_ldexp_f32 v124, v124, v126
	v_log_f32_e32 v124, v124
	s_nop 0
	v_mul_f32_e32 v126, 0x3f317217, v124
	v_fma_f32 v126, v124, s97, -v126
	v_fmac_f32_e32 v126, 0x3377d1cf, v124
	v_fmac_f32_e32 v126, 0x3f317217, v124
	v_cmp_lt_f32_e64 s[12:13], |v124|, s23
	s_nop 1
	v_cndmask_b32_e64 v124, v124, v126, s[12:13]
	v_cndmask_b32_e32 v126, 0, v211, vcc
	v_sub_f32_e32 v124, v124, v126
	v_sub_f32_e32 v124, v125, v124
	v_fmac_f32_e32 v122, 0x3d800000, v124
	v_mov_b32_e32 v202, v124
	s_waitcnt lgkmcnt(0)
	v_fma_f32 v128, v119, v176, v8
	v_fmac_f32_e32 v128, v120, v177
	v_fmac_f32_e32 v128, v116, v178
	v_fmac_f32_e32 v128, v121, v179
	v_fmac_f32_e32 v128, v117, v180
	v_fmac_f32_e32 v128, v118, v181
	v_pk_mul_f32 v[124:125], v[50:51], v[182:183]
	s_nop 0
	v_add_f32_e32 v124, v128, v124
	v_add_f32_e32 v128, v124, v125
	v_pk_mul_f32 v[124:125], v[52:53], v[184:185]
	s_nop 0
	v_add_f32_e32 v124, v128, v124
	v_add_f32_e32 v128, v124, v125
	v_pk_mul_f32 v[124:125], v[88:89], v[186:187]
	s_nop 0
	v_add_f32_e32 v124, v128, v124
	v_add_f32_e32 v128, v124, v125
	v_pk_mul_f32 v[124:125], v[90:91], v[188:189]
	s_nop 0
	v_add_f32_e32 v123, v128, v124
	v_add_f32_e32 v123, v123, v125
	v_pk_mul_f32 v[124:125], v[92:93], v[190:191]
	s_nop 0
	v_add_f32_e32 v123, v123, v124
	v_add_f32_e32 v123, v123, v125
	v_min_f32_e32 v124, 0, v123
	v_mul_f32_e64 v123, |v123|, s73
	v_exp_f32_e32 v123, v123
	s_nop 0
	v_add_f32_e32 v123, 1.0, v123
	v_cmp_gt_f32_e32 vcc, s94, v123
	s_nop 1
	v_cndmask_b32_e64 v125, 0, 32, vcc
	v_ldexp_f32 v123, v123, v125
	v_log_f32_e32 v123, v123
	s_nop 0
	v_mul_f32_e32 v125, 0x3f317217, v123
	v_fma_f32 v125, v123, s97, -v125
	v_fmac_f32_e32 v125, 0x3377d1cf, v123
	v_fmac_f32_e32 v125, 0x3f317217, v123
	v_cmp_lt_f32_e64 s[12:13], |v123|, s23
	s_nop 1
	v_cndmask_b32_e64 v123, v123, v125, s[12:13]
	v_cndmask_b32_e32 v125, 0, v211, vcc
	v_sub_f32_e32 v123, v123, v125
	v_sub_f32_e32 v123, v124, v123
	v_fmac_f32_e32 v122, 0x3d800000, v123
	v_mov_b32_e32 v203, v123
	v_add_u32_e32 v123, s0, v99
	ds_read_b128 v[124:127], v123
	ds_read_b128 v[128:131], v123 offset:16
	ds_read_b128 v[132:135], v123 offset:32
	ds_read_b128 v[136:139], v123 offset:48
	ds_read_b128 v[176:179], v123 offset:64
	ds_read_b128 v[180:183], v123 offset:80
	ds_read_b128 v[184:187], v123 offset:96
	ds_read_b128 v[188:191], v123 offset:112
	s_addk_i32 s0, 0x80
	s_waitcnt vmcnt(1) lgkmcnt(7)
	v_fma_f32 v140, v119, v124, v8
	v_fmac_f32_e32 v140, v120, v125
	v_fmac_f32_e32 v140, v116, v126
	v_fmac_f32_e32 v140, v121, v127
	s_waitcnt lgkmcnt(6)
	v_fmac_f32_e32 v140, v117, v128
	v_fmac_f32_e32 v140, v118, v129
	v_pk_mul_f32 v[124:125], v[50:51], v[130:131]
	v_add_f32_e32 v124, v140, v124
	v_add_f32_e32 v126, v124, v125
	s_waitcnt lgkmcnt(5)
	v_pk_mul_f32 v[124:125], v[52:53], v[132:133]
	s_nop 0
	v_add_f32_e32 v124, v126, v124
	v_add_f32_e32 v126, v124, v125
	v_pk_mul_f32 v[124:125], v[88:89], v[134:135]
	s_nop 0
	v_add_f32_e32 v124, v126, v124
	v_add_f32_e32 v126, v124, v125
	s_waitcnt lgkmcnt(4)
	v_pk_mul_f32 v[124:125], v[90:91], v[136:137]
	s_nop 0
	v_add_f32_e32 v124, v126, v124
	v_add_f32_e32 v126, v124, v125
	s_waitcnt vmcnt(0)
	v_pk_mul_f32 v[124:125], v[92:93], v[138:139]
	s_nop 0
	v_add_f32_e32 v124, v126, v124
	v_add_f32_e32 v124, v124, v125
	v_min_f32_e32 v125, 0, v124
	v_mul_f32_e64 v124, |v124|, s73
	v_exp_f32_e32 v124, v124
	s_nop 0
	v_add_f32_e32 v124, 1.0, v124
	v_cmp_gt_f32_e32 vcc, s94, v124
	s_nop 1
	v_cndmask_b32_e64 v126, 0, 32, vcc
	v_ldexp_f32 v124, v124, v126
	v_log_f32_e32 v124, v124
	s_nop 0
	v_mul_f32_e32 v126, 0x3f317217, v124
	v_fma_f32 v126, v124, s97, -v126
	v_fmac_f32_e32 v126, 0x3377d1cf, v124
	v_fmac_f32_e32 v126, 0x3f317217, v124
	v_cmp_lt_f32_e64 s[12:13], |v124|, s23
	s_nop 1
	v_cndmask_b32_e64 v124, v124, v126, s[12:13]
	v_cndmask_b32_e32 v126, 0, v211, vcc
	v_sub_f32_e32 v124, v124, v126
	v_sub_f32_e32 v124, v125, v124
	v_fmac_f32_e32 v122, 0x3d800000, v124
	v_mov_b32_e32 v204, v124
	s_waitcnt lgkmcnt(0)
; DEVI float logsigf_(float x) { return fminf(x, 0.f) - __logf(1.f + __expf(-fabsf(x))); }
; DEVI float gla_la(const float* gl, int t, const float* w2r, float gb) { float x = gb;
; #pragma unroll
;     for (int r = 0; r < 16; ++r) x += gl[t * 16 + r] * w2r[r];
;     return logsigf_(x) * (1.f / 16.f); }
; template <int KIND>
; DEVI void mix_state_phase(unsigned char* smem, const MixArgs a) {
;     ...
;             for (int t = sg * 32; t < sg * 32 + 32; ++t) ssum += gla_la(gl, t, w2r, gb);
	v_fma_f32 v128, v119, v176, v8
	v_fmac_f32_e32 v128, v120, v177
	v_fmac_f32_e32 v128, v116, v178
	v_fmac_f32_e32 v128, v121, v179
	v_fmac_f32_e32 v128, v117, v180
	v_fmac_f32_e32 v128, v118, v181
	v_pk_mul_f32 v[124:125], v[50:51], v[182:183]
	s_nop 0
	v_add_f32_e32 v124, v128, v124
	v_add_f32_e32 v128, v124, v125
	v_pk_mul_f32 v[124:125], v[52:53], v[184:185]
	s_nop 0
	v_add_f32_e32 v124, v128, v124
	v_add_f32_e32 v128, v124, v125
	v_pk_mul_f32 v[124:125], v[88:89], v[186:187]
	s_nop 0
	v_add_f32_e32 v124, v128, v124
	v_add_f32_e32 v128, v124, v125
	v_pk_mul_f32 v[124:125], v[90:91], v[188:189]
	s_nop 0
	v_add_f32_e32 v123, v128, v124
	v_add_f32_e32 v123, v123, v125
	v_pk_mul_f32 v[124:125], v[92:93], v[190:191]
	s_nop 0
	v_add_f32_e32 v123, v123, v124
	v_add_f32_e32 v123, v123, v125
	v_min_f32_e32 v124, 0, v123
	v_mul_f32_e64 v123, |v123|, s73
	v_exp_f32_e32 v123, v123
	s_nop 0
	v_add_f32_e32 v123, 1.0, v123
	v_cmp_gt_f32_e32 vcc, s94, v123
	s_nop 1
	v_cndmask_b32_e64 v125, 0, 32, vcc
	v_ldexp_f32 v123, v123, v125
	v_log_f32_e32 v123, v123
	s_nop 0
	v_mul_f32_e32 v125, 0x3f317217, v123
	v_fma_f32 v125, v123, s97, -v125
	v_fmac_f32_e32 v125, 0x3377d1cf, v123
	v_fmac_f32_e32 v125, 0x3f317217, v123
	v_cmp_lt_f32_e64 s[12:13], |v123|, s23
	s_nop 1
	v_cndmask_b32_e64 v123, v123, v125, s[12:13]
	v_cndmask_b32_e32 v125, 0, v211, vcc
	v_sub_f32_e32 v123, v123, v125
	v_sub_f32_e32 v123, v124, v123
	v_fmac_f32_e32 v122, 0x3d800000, v123
	v_mov_b32_e32 v205, v123
	v_add_u32_e32 v123, s0, v99
	ds_read_b128 v[124:127], v123
	ds_read_b128 v[128:131], v123 offset:16
	ds_read_b128 v[132:135], v123 offset:32
	ds_read_b128 v[136:139], v123 offset:48
	ds_read_b128 v[176:179], v123 offset:64
	ds_read_b128 v[180:183], v123 offset:80
	ds_read_b128 v[184:187], v123 offset:96
	ds_read_b128 v[188:191], v123 offset:112
	s_addk_i32 s0, 0x80
	s_waitcnt vmcnt(1) lgkmcnt(7)
	v_fma_f32 v140, v119, v124, v8
	v_fmac_f32_e32 v140, v120, v125
	v_fmac_f32_e32 v140, v116, v126
	v_fmac_f32_e32 v140, v121, v127
	s_waitcnt lgkmcnt(6)
	v_fmac_f32_e32 v140, v117, v128
	v_fmac_f32_e32 v140, v118, v129
	v_pk_mul_f32 v[124:125], v[50:51], v[130:131]
	v_add_f32_e32 v124, v140, v124
	v_add_f32_e32 v126, v124, v125
	s_waitcnt lgkmcnt(5)
	v_pk_mul_f32 v[124:125], v[52:53], v[132:133]
	s_nop 0
	v_add_f32_e32 v124, v126, v124
	v_add_f32_e32 v126, v124, v125
	v_pk_mul_f32 v[124:125], v[88:89], v[134:135]
	s_nop 0
	v_add_f32_e32 v124, v126, v124
	v_add_f32_e32 v126, v124, v125
	s_waitcnt lgkmcnt(4)
	v_pk_mul_f32 v[124:125], v[90:91], v[136:137]
	s_nop 0
	v_add_f32_e32 v124, v126, v124
	v_add_f32_e32 v126, v124, v125
	s_waitcnt vmcnt(0)
	v_pk_mul_f32 v[124:125], v[92:93], v[138:139]
	s_nop 0
	v_add_f32_e32 v124, v126, v124
	v_add_f32_e32 v124, v124, v125
	v_min_f32_e32 v125, 0, v124
	v_mul_f32_e64 v124, |v124|, s73
	v_exp_f32_e32 v124, v124
	s_nop 0
	v_add_f32_e32 v124, 1.0, v124
	v_cmp_gt_f32_e32 vcc, s94, v124
	s_nop 1
	v_cndmask_b32_e64 v126, 0, 32, vcc
	v_ldexp_f32 v124, v124, v126
	v_log_f32_e32 v124, v124
	s_nop 0
	v_mul_f32_e32 v126, 0x3f317217, v124
	v_fma_f32 v126, v124, s97, -v126
	v_fmac_f32_e32 v126, 0x3377d1cf, v124
	v_fmac_f32_e32 v126, 0x3f317217, v124
	v_cmp_lt_f32_e64 s[12:13], |v124|, s23
	s_nop 1
	v_cndmask_b32_e64 v124, v124, v126, s[12:13]
	v_cndmask_b32_e32 v126, 0, v211, vcc
	v_sub_f32_e32 v124, v124, v126
	v_sub_f32_e32 v124, v125, v124
	v_fmac_f32_e32 v122, 0x3d800000, v124
	v_mov_b32_e32 v206, v124
	s_waitcnt lgkmcnt(0)
	v_fma_f32 v128, v119, v176, v8
	v_fmac_f32_e32 v128, v120, v177
	v_fmac_f32_e32 v128, v116, v178
	v_fmac_f32_e32 v128, v121, v179
	v_fmac_f32_e32 v128, v117, v180
	v_fmac_f32_e32 v128, v118, v181
	v_pk_mul_f32 v[124:125], v[50:51], v[182:183]
	s_nop 0
	v_add_f32_e32 v124, v128, v124
	v_add_f32_e32 v128, v124, v125
	v_pk_mul_f32 v[124:125], v[52:53], v[184:185]
	s_nop 0
	v_add_f32_e32 v124, v128, v124
	v_add_f32_e32 v128, v124, v125
	v_pk_mul_f32 v[124:125], v[88:89], v[186:187]
	s_nop 0
	v_add_f32_e32 v124, v128, v124
	v_add_f32_e32 v128, v124, v125
	v_pk_mul_f32 v[124:125], v[90:91], v[188:189]
	s_nop 0
	v_add_f32_e32 v123, v128, v124
	v_add_f32_e32 v123, v123, v125
	v_pk_mul_f32 v[124:125], v[92:93], v[190:191]
	s_nop 0
	v_add_f32_e32 v123, v123, v124
	v_add_f32_e32 v123, v123, v125
	v_min_f32_e32 v124, 0, v123
	v_mul_f32_e64 v123, |v123|, s73
	v_exp_f32_e32 v123, v123
	s_nop 0
	v_add_f32_e32 v123, 1.0, v123
	v_cmp_gt_f32_e32 vcc, s94, v123
	s_nop 1
	v_cndmask_b32_e64 v125, 0, 32, vcc
	v_ldexp_f32 v123, v123, v125
	v_log_f32_e32 v123, v123
	s_nop 0
	v_mul_f32_e32 v125, 0x3f317217, v123
	v_fma_f32 v125, v123, s97, -v125
	v_fmac_f32_e32 v125, 0x3377d1cf, v123
	v_fmac_f32_e32 v125, 0x3f317217, v123
	v_cmp_lt_f32_e64 s[12:13], |v123|, s23
	s_nop 1
	v_cndmask_b32_e64 v123, v123, v125, s[12:13]
	v_cndmask_b32_e32 v125, 0, v211, vcc
	v_sub_f32_e32 v123, v123, v125
	v_sub_f32_e32 v123, v124, v123
	v_fmac_f32_e32 v122, 0x3d800000, v123
	v_mov_b32_e32 v207, v123
	v_add_u32_e32 v123, s0, v99
	ds_read_b128 v[124:127], v123
	ds_read_b128 v[128:131], v123 offset:16
	ds_read_b128 v[132:135], v123 offset:32
	ds_read_b128 v[136:139], v123 offset:48
	ds_read_b128 v[176:179], v123 offset:64
	ds_read_b128 v[180:183], v123 offset:80
	ds_read_b128 v[184:187], v123 offset:96
	ds_read_b128 v[188:191], v123 offset:112
	s_addk_i32 s0, 0x80
	s_waitcnt vmcnt(1) lgkmcnt(7)
	v_fma_f32 v140, v119, v124, v8
	v_fmac_f32_e32 v140, v120, v125
	v_fmac_f32_e32 v140, v116, v126
	v_fmac_f32_e32 v140, v121, v127
	s_waitcnt lgkmcnt(6)
	v_fmac_f32_e32 v140, v117, v128
	v_fmac_f32_e32 v140, v118, v129
	v_pk_mul_f32 v[124:125], v[50:51], v[130:131]
	v_add_f32_e32 v124, v140, v124
	v_add_f32_e32 v126, v124, v125
	s_waitcnt lgkmcnt(5)
; DEVI float logsigf_(float x) { return fminf(x, 0.f) - __logf(1.f + __expf(-fabsf(x))); }
; DEVI float gla_la(const float* gl, int t, const float* w2r, float gb) { float x = gb;
; #pragma unroll
;     for (int r = 0; r < 16; ++r) x += gl[t * 16 + r] * w2r[r];
;     return logsigf_(x) * (1.f / 16.f); }
; template <int KIND>
; DEVI void mix_state_phase(unsigned char* smem, const MixArgs a) {
;     ...
;             for (int t = sg * 32; t < sg * 32 + 32; ++t) ssum += gla_la(gl, t, w2r, gb);
	v_pk_mul_f32 v[124:125], v[52:53], v[132:133]
	s_nop 0
	v_add_f32_e32 v124, v126, v124
	v_add_f32_e32 v126, v124, v125
	v_pk_mul_f32 v[124:125], v[88:89], v[134:135]
	s_nop 0
	v_add_f32_e32 v124, v126, v124
	v_add_f32_e32 v126, v124, v125
	s_waitcnt lgkmcnt(4)
	v_pk_mul_f32 v[124:125], v[90:91], v[136:137]
	s_nop 0
	v_add_f32_e32 v124, v126, v124
	v_add_f32_e32 v126, v124, v125
	s_waitcnt vmcnt(0)
	v_pk_mul_f32 v[124:125], v[92:93], v[138:139]
	s_nop 0
	v_add_f32_e32 v124, v126, v124
	v_add_f32_e32 v124, v124, v125
	v_min_f32_e32 v125, 0, v124
	v_mul_f32_e64 v124, |v124|, s73
	v_exp_f32_e32 v124, v124
	s_nop 0
	v_add_f32_e32 v124, 1.0, v124
	v_cmp_gt_f32_e32 vcc, s94, v124
	s_nop 1
	v_cndmask_b32_e64 v126, 0, 32, vcc
	v_ldexp_f32 v124, v124, v126
	v_log_f32_e32 v124, v124
	s_nop 0
	v_mul_f32_e32 v126, 0x3f317217, v124
	v_fma_f32 v126, v124, s97, -v126
	v_fmac_f32_e32 v126, 0x3377d1cf, v124
	v_fmac_f32_e32 v126, 0x3f317217, v124
	v_cmp_lt_f32_e64 s[12:13], |v124|, s23
	s_nop 1
	v_cndmask_b32_e64 v124, v124, v126, s[12:13]
	v_cndmask_b32_e32 v126, 0, v211, vcc
	v_sub_f32_e32 v124, v124, v126
	v_sub_f32_e32 v124, v125, v124
	v_fmac_f32_e32 v122, 0x3d800000, v124
	v_mov_b32_e32 v213, v124
	s_waitcnt lgkmcnt(0)
	v_fma_f32 v128, v119, v176, v8
	v_fmac_f32_e32 v128, v120, v177
	v_fmac_f32_e32 v128, v116, v178
	v_fmac_f32_e32 v128, v121, v179
	v_fmac_f32_e32 v128, v117, v180
	v_fmac_f32_e32 v128, v118, v181
	v_pk_mul_f32 v[124:125], v[50:51], v[182:183]
	s_nop 0
	v_add_f32_e32 v124, v128, v124
	v_add_f32_e32 v128, v124, v125
	v_pk_mul_f32 v[124:125], v[52:53], v[184:185]
	s_nop 0
	v_add_f32_e32 v124, v128, v124
	v_add_f32_e32 v128, v124, v125
	v_pk_mul_f32 v[124:125], v[88:89], v[186:187]
	s_nop 0
	v_add_f32_e32 v124, v128, v124
	v_add_f32_e32 v128, v124, v125
	v_pk_mul_f32 v[124:125], v[90:91], v[188:189]
	s_nop 0
	v_add_f32_e32 v123, v128, v124
	v_add_f32_e32 v123, v123, v125
	v_pk_mul_f32 v[124:125], v[92:93], v[190:191]
	s_nop 0
	v_add_f32_e32 v123, v123, v124
	v_add_f32_e32 v123, v123, v125
	v_min_f32_e32 v124, 0, v123
	v_mul_f32_e64 v123, |v123|, s73
	v_exp_f32_e32 v123, v123
	s_nop 0
	v_add_f32_e32 v123, 1.0, v123
	v_cmp_gt_f32_e32 vcc, s94, v123
	s_nop 1
	v_cndmask_b32_e64 v125, 0, 32, vcc
	v_ldexp_f32 v123, v123, v125
	v_log_f32_e32 v123, v123
	s_nop 0
	v_mul_f32_e32 v125, 0x3f317217, v123
	v_fma_f32 v125, v123, s97, -v125
	v_fmac_f32_e32 v125, 0x3377d1cf, v123
	v_fmac_f32_e32 v125, 0x3f317217, v123
	v_cmp_lt_f32_e64 s[12:13], |v123|, s23
	s_nop 1
	v_cndmask_b32_e64 v123, v123, v125, s[12:13]
	v_cndmask_b32_e32 v125, 0, v211, vcc
	v_sub_f32_e32 v123, v123, v125
	v_sub_f32_e32 v123, v124, v123
	v_fmac_f32_e32 v122, 0x3d800000, v123
	v_mov_b32_e32 v214, v123
	v_add_u32_e32 v123, s0, v99
	ds_read_b128 v[124:127], v123
	ds_read_b128 v[128:131], v123 offset:16
	ds_read_b128 v[132:135], v123 offset:32
	ds_read_b128 v[136:139], v123 offset:48
	ds_read_b128 v[176:179], v123 offset:64
	ds_read_b128 v[180:183], v123 offset:80
	ds_read_b128 v[184:187], v123 offset:96
	ds_read_b128 v[188:191], v123 offset:112
	s_addk_i32 s0, 0x80
	s_waitcnt vmcnt(1) lgkmcnt(7)
	v_fma_f32 v140, v119, v124, v8
	v_fmac_f32_e32 v140, v120, v125
	v_fmac_f32_e32 v140, v116, v126
	v_fmac_f32_e32 v140, v121, v127
	s_waitcnt lgkmcnt(6)
	v_fmac_f32_e32 v140, v117, v128
	v_fmac_f32_e32 v140, v118, v129
	v_pk_mul_f32 v[124:125], v[50:51], v[130:131]
	v_add_f32_e32 v124, v140, v124
	v_add_f32_e32 v126, v124, v125
	s_waitcnt lgkmcnt(5)
	v_pk_mul_f32 v[124:125], v[52:53], v[132:133]
	s_nop 0
	v_add_f32_e32 v124, v126, v124
	v_add_f32_e32 v126, v124, v125
	v_pk_mul_f32 v[124:125], v[88:89], v[134:135]
	s_nop 0
	v_add_f32_e32 v124, v126, v124
	v_add_f32_e32 v126, v124, v125
	s_waitcnt lgkmcnt(4)
	v_pk_mul_f32 v[124:125], v[90:91], v[136:137]
	s_nop 0
	v_add_f32_e32 v124, v126, v124
	v_add_f32_e32 v126, v124, v125
	s_waitcnt vmcnt(0)
	v_pk_mul_f32 v[124:125], v[92:93], v[138:139]
	s_nop 0
	v_add_f32_e32 v124, v126, v124
	v_add_f32_e32 v124, v124, v125
	v_min_f32_e32 v125, 0, v124
	v_mul_f32_e64 v124, |v124|, s73
	v_exp_f32_e32 v124, v124
	s_nop 0
	v_add_f32_e32 v124, 1.0, v124
	v_cmp_gt_f32_e32 vcc, s94, v124
	s_nop 1
	v_cndmask_b32_e64 v126, 0, 32, vcc
	v_ldexp_f32 v124, v124, v126
	v_log_f32_e32 v124, v124
	s_nop 0
	v_mul_f32_e32 v126, 0x3f317217, v124
	v_fma_f32 v126, v124, s97, -v126
	v_fmac_f32_e32 v126, 0x3377d1cf, v124
	v_fmac_f32_e32 v126, 0x3f317217, v124
	v_cmp_lt_f32_e64 s[12:13], |v124|, s23
	s_nop 1
	v_cndmask_b32_e64 v124, v124, v126, s[12:13]
	v_cndmask_b32_e32 v126, 0, v211, vcc
	v_sub_f32_e32 v124, v124, v126
	v_sub_f32_e32 v124, v125, v124
	v_fmac_f32_e32 v122, 0x3d800000, v124
	v_mov_b32_e32 v215, v124
	s_waitcnt lgkmcnt(0)
	v_fma_f32 v128, v119, v176, v8
	v_fmac_f32_e32 v128, v120, v177
	v_fmac_f32_e32 v128, v116, v178
	v_fmac_f32_e32 v128, v121, v179
	v_fmac_f32_e32 v128, v117, v180
	v_fmac_f32_e32 v128, v118, v181
	v_pk_mul_f32 v[124:125], v[50:51], v[182:183]
	s_nop 0
	v_add_f32_e32 v124, v128, v124
	v_add_f32_e32 v128, v124, v125
	v_pk_mul_f32 v[124:125], v[52:53], v[184:185]
	s_nop 0
	v_add_f32_e32 v124, v128, v124
	v_add_f32_e32 v128, v124, v125
	v_pk_mul_f32 v[124:125], v[88:89], v[186:187]
	s_nop 0
	v_add_f32_e32 v124, v128, v124
	v_add_f32_e32 v128, v124, v125
	v_pk_mul_f32 v[124:125], v[90:91], v[188:189]
	s_nop 0
	v_add_f32_e32 v123, v128, v124
	v_add_f32_e32 v123, v123, v125
	v_pk_mul_f32 v[124:125], v[92:93], v[190:191]
	s_nop 0
	v_add_f32_e32 v123, v123, v124
	v_add_f32_e32 v123, v123, v125
	v_min_f32_e32 v124, 0, v123
	v_mul_f32_e64 v123, |v123|, s73
	v_exp_f32_e32 v123, v123
	s_nop 0
	v_add_f32_e32 v123, 1.0, v123
	v_cmp_gt_f32_e32 vcc, s94, v123
	s_nop 1
	v_cndmask_b32_e64 v125, 0, 32, vcc
	v_ldexp_f32 v123, v123, v125
	v_log_f32_e32 v123, v123
	s_nop 0
	v_mul_f32_e32 v125, 0x3f317217, v123
	v_fma_f32 v125, v123, s97, -v125
	v_fmac_f32_e32 v125, 0x3377d1cf, v123
	v_fmac_f32_e32 v125, 0x3f317217, v123
	v_cmp_lt_f32_e64 s[12:13], |v123|, s23
	s_nop 1
	v_cndmask_b32_e64 v123, v123, v125, s[12:13]
	v_cndmask_b32_e32 v125, 0, v211, vcc
	v_sub_f32_e32 v123, v123, v125
	v_sub_f32_e32 v123, v124, v123
	v_fmac_f32_e32 v122, 0x3d800000, v123
	v_mov_b32_e32 v216, v123
	v_add_u32_e32 v123, s0, v99
	ds_read_b128 v[124:127], v123
	ds_read_b128 v[128:131], v123 offset:16
	ds_read_b128 v[132:135], v123 offset:32
	ds_read_b128 v[136:139], v123 offset:48
	ds_read_b128 v[176:179], v123 offset:64
	ds_read_b128 v[180:183], v123 offset:80
	ds_read_b128 v[184:187], v123 offset:96
	ds_read_b128 v[188:191], v123 offset:112
	s_addk_i32 s0, 0x80
	s_waitcnt vmcnt(1) lgkmcnt(7)
; DEVI float logsigf_(float x) { return fminf(x, 0.f) - __logf(1.f + __expf(-fabsf(x))); }
; DEVI float gla_la(const float* gl, int t, const float* w2r, float gb) { float x = gb;
; #pragma unroll
;     for (int r = 0; r < 16; ++r) x += gl[t * 16 + r] * w2r[r];
;     return logsigf_(x) * (1.f / 16.f); }
; template <int KIND>
; DEVI void mix_state_phase(unsigned char* smem, const MixArgs a) {
;     ...
;             for (int t = sg * 32; t < sg * 32 + 32; ++t) ssum += gla_la(gl, t, w2r, gb);
	v_fma_f32 v140, v119, v124, v8
	v_fmac_f32_e32 v140, v120, v125
	v_fmac_f32_e32 v140, v116, v126
	v_fmac_f32_e32 v140, v121, v127
	s_waitcnt lgkmcnt(6)
	v_fmac_f32_e32 v140, v117, v128
	v_fmac_f32_e32 v140, v118, v129
	v_pk_mul_f32 v[124:125], v[50:51], v[130:131]
	v_add_f32_e32 v124, v140, v124
	v_add_f32_e32 v126, v124, v125
	s_waitcnt lgkmcnt(5)
	v_pk_mul_f32 v[124:125], v[52:53], v[132:133]
	s_nop 0
	v_add_f32_e32 v124, v126, v124
	v_add_f32_e32 v126, v124, v125
	v_pk_mul_f32 v[124:125], v[88:89], v[134:135]
	s_nop 0
	v_add_f32_e32 v124, v126, v124
	v_add_f32_e32 v126, v124, v125
	s_waitcnt lgkmcnt(4)
	v_pk_mul_f32 v[124:125], v[90:91], v[136:137]
	s_nop 0
	v_add_f32_e32 v124, v126, v124
	v_add_f32_e32 v126, v124, v125
	s_waitcnt vmcnt(0)
	v_pk_mul_f32 v[124:125], v[92:93], v[138:139]
	s_nop 0
	v_add_f32_e32 v124, v126, v124
	v_add_f32_e32 v124, v124, v125
	v_min_f32_e32 v125, 0, v124
	v_mul_f32_e64 v124, |v124|, s73
	v_exp_f32_e32 v124, v124
	s_nop 0
	v_add_f32_e32 v124, 1.0, v124
	v_cmp_gt_f32_e32 vcc, s94, v124
	s_nop 1
	v_cndmask_b32_e64 v126, 0, 32, vcc
	v_ldexp_f32 v124, v124, v126
	v_log_f32_e32 v124, v124
	s_nop 0
	v_mul_f32_e32 v126, 0x3f317217, v124
	v_fma_f32 v126, v124, s97, -v126
	v_fmac_f32_e32 v126, 0x3377d1cf, v124
	v_fmac_f32_e32 v126, 0x3f317217, v124
	v_cmp_lt_f32_e64 s[12:13], |v124|, s23
	s_nop 1
	v_cndmask_b32_e64 v124, v124, v126, s[12:13]
	v_cndmask_b32_e32 v126, 0, v211, vcc
	v_sub_f32_e32 v124, v124, v126
	v_sub_f32_e32 v124, v125, v124
	v_fmac_f32_e32 v122, 0x3d800000, v124
	v_mov_b32_e32 v217, v124
	s_waitcnt lgkmcnt(0)
	v_fma_f32 v128, v119, v176, v8
	v_fmac_f32_e32 v128, v120, v177
	v_fmac_f32_e32 v128, v116, v178
	v_fmac_f32_e32 v128, v121, v179
	v_fmac_f32_e32 v128, v117, v180
	v_fmac_f32_e32 v128, v118, v181
	v_pk_mul_f32 v[124:125], v[50:51], v[182:183]
	s_nop 0
	v_add_f32_e32 v124, v128, v124
	v_add_f32_e32 v128, v124, v125
	v_pk_mul_f32 v[124:125], v[52:53], v[184:185]
	s_nop 0
	v_add_f32_e32 v124, v128, v124
	v_add_f32_e32 v128, v124, v125
	v_pk_mul_f32 v[124:125], v[88:89], v[186:187]
	s_nop 0
	v_add_f32_e32 v124, v128, v124
	v_add_f32_e32 v128, v124, v125
	v_pk_mul_f32 v[124:125], v[90:91], v[188:189]
	s_nop 0
	v_add_f32_e32 v123, v128, v124
	v_add_f32_e32 v123, v123, v125
	v_pk_mul_f32 v[124:125], v[92:93], v[190:191]
	s_nop 0
	v_add_f32_e32 v123, v123, v124
	v_add_f32_e32 v123, v123, v125
	v_min_f32_e32 v124, 0, v123
	v_mul_f32_e64 v123, |v123|, s73
	v_exp_f32_e32 v123, v123
	s_nop 0
	v_add_f32_e32 v123, 1.0, v123
	v_cmp_gt_f32_e32 vcc, s94, v123
	s_nop 1
	v_cndmask_b32_e64 v125, 0, 32, vcc
	v_ldexp_f32 v123, v123, v125
	v_log_f32_e32 v123, v123
	s_nop 0
	v_mul_f32_e32 v125, 0x3f317217, v123
	v_fma_f32 v125, v123, s97, -v125
	v_fmac_f32_e32 v125, 0x3377d1cf, v123
	v_fmac_f32_e32 v125, 0x3f317217, v123
	v_cmp_lt_f32_e64 s[12:13], |v123|, s23
	s_nop 1
	v_cndmask_b32_e64 v123, v123, v125, s[12:13]
	v_cndmask_b32_e32 v125, 0, v211, vcc
	v_sub_f32_e32 v123, v123, v125
	v_sub_f32_e32 v123, v124, v123
	v_fmac_f32_e32 v122, 0x3d800000, v123
	v_mov_b32_e32 v218, v123
	v_add_u32_e32 v123, s0, v99
	ds_read_b128 v[124:127], v123
	ds_read_b128 v[128:131], v123 offset:16
	ds_read_b128 v[132:135], v123 offset:32
	ds_read_b128 v[136:139], v123 offset:48
	ds_read_b128 v[176:179], v123 offset:64
	ds_read_b128 v[180:183], v123 offset:80
	ds_read_b128 v[184:187], v123 offset:96
	ds_read_b128 v[188:191], v123 offset:112
	s_addk_i32 s0, 0x80
	s_waitcnt vmcnt(1) lgkmcnt(7)
	v_fma_f32 v140, v119, v124, v8
	v_fmac_f32_e32 v140, v120, v125
	v_fmac_f32_e32 v140, v116, v126
	v_fmac_f32_e32 v140, v121, v127
	s_waitcnt lgkmcnt(6)
	v_fmac_f32_e32 v140, v117, v128
	v_fmac_f32_e32 v140, v118, v129
	v_pk_mul_f32 v[124:125], v[50:51], v[130:131]
	v_add_f32_e32 v124, v140, v124
	v_add_f32_e32 v126, v124, v125
	s_waitcnt lgkmcnt(5)
	v_pk_mul_f32 v[124:125], v[52:53], v[132:133]
	s_nop 0
	v_add_f32_e32 v124, v126, v124
	v_add_f32_e32 v126, v124, v125
	v_pk_mul_f32 v[124:125], v[88:89], v[134:135]
	s_nop 0
	v_add_f32_e32 v124, v126, v124
	v_add_f32_e32 v126, v124, v125
	s_waitcnt lgkmcnt(4)
	v_pk_mul_f32 v[124:125], v[90:91], v[136:137]
	s_nop 0
	v_add_f32_e32 v124, v126, v124
	v_add_f32_e32 v126, v124, v125
	s_waitcnt vmcnt(0)
	v_pk_mul_f32 v[124:125], v[92:93], v[138:139]
	s_nop 0
	v_add_f32_e32 v124, v126, v124
	v_add_f32_e32 v124, v124, v125
	v_min_f32_e32 v125, 0, v124
	v_mul_f32_e64 v124, |v124|, s73
	v_exp_f32_e32 v124, v124
	s_nop 0
	v_add_f32_e32 v124, 1.0, v124
	v_cmp_gt_f32_e32 vcc, s94, v124
	s_nop 1
	v_cndmask_b32_e64 v126, 0, 32, vcc
	v_ldexp_f32 v124, v124, v126
	v_log_f32_e32 v124, v124
	s_nop 0
	v_mul_f32_e32 v126, 0x3f317217, v124
	v_fma_f32 v126, v124, s97, -v126
	v_fmac_f32_e32 v126, 0x3377d1cf, v124
	v_fmac_f32_e32 v126, 0x3f317217, v124
	v_cmp_lt_f32_e64 s[12:13], |v124|, s23
	s_nop 1
	v_cndmask_b32_e64 v124, v124, v126, s[12:13]
	v_cndmask_b32_e32 v126, 0, v211, vcc
	v_sub_f32_e32 v124, v124, v126
	v_sub_f32_e32 v124, v125, v124
	v_fmac_f32_e32 v122, 0x3d800000, v124
	v_mov_b32_e32 v219, v124
	s_waitcnt lgkmcnt(0)
; DEVI float logsigf_(float x) { return fminf(x, 0.f) - __logf(1.f + __expf(-fabsf(x))); }
; DEVI float gla_la(const float* gl, int t, const float* w2r, float gb) { float x = gb;
; #pragma unroll
;     for (int r = 0; r < 16; ++r) x += gl[t * 16 + r] * w2r[r];
;     return logsigf_(x) * (1.f / 16.f); }
; template <int KIND>
; DEVI void mix_state_phase(unsigned char* smem, const MixArgs a) {
;     ...
;             for (int t = sg * 32; t < sg * 32 + 32; ++t) ssum += gla_la(gl, t, w2r, gb);
	v_fma_f32 v128, v119, v176, v8
	v_fmac_f32_e32 v128, v120, v177
	v_fmac_f32_e32 v128, v116, v178
	v_fmac_f32_e32 v128, v121, v179
	v_fmac_f32_e32 v128, v117, v180
	v_fmac_f32_e32 v128, v118, v181
	v_pk_mul_f32 v[124:125], v[50:51], v[182:183]
	s_nop 0
	v_add_f32_e32 v124, v128, v124
	v_add_f32_e32 v128, v124, v125
	v_pk_mul_f32 v[124:125], v[52:53], v[184:185]
	s_nop 0
	v_add_f32_e32 v124, v128, v124
	v_add_f32_e32 v128, v124, v125
	v_pk_mul_f32 v[124:125], v[88:89], v[186:187]
	s_nop 0
	v_add_f32_e32 v124, v128, v124
	v_add_f32_e32 v128, v124, v125
	v_pk_mul_f32 v[124:125], v[90:91], v[188:189]
	s_nop 0
	v_add_f32_e32 v123, v128, v124
	v_add_f32_e32 v123, v123, v125
	v_pk_mul_f32 v[124:125], v[92:93], v[190:191]
	s_nop 0
	v_add_f32_e32 v123, v123, v124
	v_add_f32_e32 v123, v123, v125
	v_min_f32_e32 v124, 0, v123
	v_mul_f32_e64 v123, |v123|, s73
	v_exp_f32_e32 v123, v123
	s_nop 0
	v_add_f32_e32 v123, 1.0, v123
	v_cmp_gt_f32_e32 vcc, s94, v123
	s_nop 1
	v_cndmask_b32_e64 v125, 0, 32, vcc
	v_ldexp_f32 v123, v123, v125
	v_log_f32_e32 v123, v123
	s_nop 0
	v_mul_f32_e32 v125, 0x3f317217, v123
	v_fma_f32 v125, v123, s97, -v125
	v_fmac_f32_e32 v125, 0x3377d1cf, v123
	v_fmac_f32_e32 v125, 0x3f317217, v123
	v_cmp_lt_f32_e64 s[12:13], |v123|, s23
	s_nop 1
	v_cndmask_b32_e64 v123, v123, v125, s[12:13]
	v_cndmask_b32_e32 v125, 0, v211, vcc
	v_sub_f32_e32 v123, v123, v125
	v_sub_f32_e32 v123, v124, v123
	v_fmac_f32_e32 v122, 0x3d800000, v123
	v_mov_b32_e32 v220, v123
	v_add_u32_e32 v123, s0, v99
	ds_read_b128 v[124:127], v123
	ds_read_b128 v[128:131], v123 offset:16
	ds_read_b128 v[132:135], v123 offset:32
	ds_read_b128 v[136:139], v123 offset:48
	ds_read_b128 v[176:179], v123 offset:64
	ds_read_b128 v[180:183], v123 offset:80
	ds_read_b128 v[184:187], v123 offset:96
	ds_read_b128 v[188:191], v123 offset:112
	s_addk_i32 s0, 0x80
	s_waitcnt vmcnt(1) lgkmcnt(7)
	v_fma_f32 v140, v119, v124, v8
	v_fmac_f32_e32 v140, v120, v125
	v_fmac_f32_e32 v140, v116, v126
	v_fmac_f32_e32 v140, v121, v127
	s_waitcnt lgkmcnt(6)
	v_fmac_f32_e32 v140, v117, v128
	v_fmac_f32_e32 v140, v118, v129
	v_pk_mul_f32 v[124:125], v[50:51], v[130:131]
	v_add_f32_e32 v124, v140, v124
	v_add_f32_e32 v126, v124, v125
	s_waitcnt lgkmcnt(5)
	v_pk_mul_f32 v[124:125], v[52:53], v[132:133]
	s_nop 0
	v_add_f32_e32 v124, v126, v124
	v_add_f32_e32 v126, v124, v125
	v_pk_mul_f32 v[124:125], v[88:89], v[134:135]
	s_nop 0
	v_add_f32_e32 v124, v126, v124
	v_add_f32_e32 v126, v124, v125
	s_waitcnt lgkmcnt(4)
	v_pk_mul_f32 v[124:125], v[90:91], v[136:137]
	s_nop 0
	v_add_f32_e32 v124, v126, v124
	v_add_f32_e32 v126, v124, v125
	s_waitcnt vmcnt(0)
	v_pk_mul_f32 v[124:125], v[92:93], v[138:139]
	s_nop 0
	v_add_f32_e32 v124, v126, v124
	v_add_f32_e32 v124, v124, v125
	v_min_f32_e32 v125, 0, v124
	v_mul_f32_e64 v124, |v124|, s73
	v_exp_f32_e32 v124, v124
	s_nop 0
	v_add_f32_e32 v124, 1.0, v124
	v_cmp_gt_f32_e32 vcc, s94, v124
	s_nop 1
	v_cndmask_b32_e64 v126, 0, 32, vcc
	v_ldexp_f32 v124, v124, v126
	v_log_f32_e32 v124, v124
	s_nop 0
	v_mul_f32_e32 v126, 0x3f317217, v124
	v_fma_f32 v126, v124, s97, -v126
	v_fmac_f32_e32 v126, 0x3377d1cf, v124
	v_fmac_f32_e32 v126, 0x3f317217, v124
	v_cmp_lt_f32_e64 s[12:13], |v124|, s23
	s_nop 1
	v_cndmask_b32_e64 v124, v124, v126, s[12:13]
	v_cndmask_b32_e32 v126, 0, v211, vcc
	v_sub_f32_e32 v124, v124, v126
	v_sub_f32_e32 v124, v125, v124
	v_fmac_f32_e32 v122, 0x3d800000, v124
	v_mov_b32_e32 v221, v124
	s_waitcnt lgkmcnt(0)
	v_fma_f32 v128, v119, v176, v8
	v_fmac_f32_e32 v128, v120, v177
	v_fmac_f32_e32 v128, v116, v178
	v_fmac_f32_e32 v128, v121, v179
	v_fmac_f32_e32 v128, v117, v180
	v_fmac_f32_e32 v128, v118, v181
	v_pk_mul_f32 v[124:125], v[50:51], v[182:183]
	s_nop 0
	v_add_f32_e32 v124, v128, v124
	v_add_f32_e32 v128, v124, v125
	v_pk_mul_f32 v[124:125], v[52:53], v[184:185]
	s_nop 0
	v_add_f32_e32 v124, v128, v124
	v_add_f32_e32 v128, v124, v125
	v_pk_mul_f32 v[124:125], v[88:89], v[186:187]
	s_nop 0
	v_add_f32_e32 v124, v128, v124
	v_add_f32_e32 v128, v124, v125
	v_pk_mul_f32 v[124:125], v[90:91], v[188:189]
	s_nop 0
	v_add_f32_e32 v123, v128, v124
	v_add_f32_e32 v123, v123, v125
	v_pk_mul_f32 v[124:125], v[92:93], v[190:191]
	s_nop 0
	v_add_f32_e32 v123, v123, v124
	v_add_f32_e32 v123, v123, v125
	v_min_f32_e32 v124, 0, v123
	v_mul_f32_e64 v123, |v123|, s73
	v_exp_f32_e32 v123, v123
	s_nop 0
	v_add_f32_e32 v123, 1.0, v123
	v_cmp_gt_f32_e32 vcc, s94, v123
	s_nop 1
	v_cndmask_b32_e64 v125, 0, 32, vcc
	v_ldexp_f32 v123, v123, v125
	v_log_f32_e32 v123, v123
	s_nop 0
	v_mul_f32_e32 v125, 0x3f317217, v123
	v_fma_f32 v125, v123, s97, -v125
	v_fmac_f32_e32 v125, 0x3377d1cf, v123
	v_fmac_f32_e32 v125, 0x3f317217, v123
	v_cmp_lt_f32_e64 s[12:13], |v123|, s23
	s_nop 1
	v_cndmask_b32_e64 v123, v123, v125, s[12:13]
	v_cndmask_b32_e32 v125, 0, v211, vcc
	v_sub_f32_e32 v123, v123, v125
	v_sub_f32_e32 v123, v124, v123
	v_fmac_f32_e32 v122, 0x3d800000, v123
	v_mov_b32_e32 v222, v123
	v_add_u32_e32 v123, s0, v99
	ds_read_b128 v[124:127], v123
	ds_read_b128 v[128:131], v123 offset:16
	ds_read_b128 v[132:135], v123 offset:32
	ds_read_b128 v[136:139], v123 offset:48
	ds_read_b128 v[176:179], v123 offset:64
	ds_read_b128 v[180:183], v123 offset:80
	ds_read_b128 v[184:187], v123 offset:96
	ds_read_b128 v[188:191], v123 offset:112
	s_addk_i32 s0, 0x80
	s_waitcnt vmcnt(1) lgkmcnt(7)
	v_fma_f32 v140, v119, v124, v8
	v_fmac_f32_e32 v140, v120, v125
	v_fmac_f32_e32 v140, v116, v126
	v_fmac_f32_e32 v140, v121, v127
	s_waitcnt lgkmcnt(6)
	v_fmac_f32_e32 v140, v117, v128
	v_fmac_f32_e32 v140, v118, v129
	v_pk_mul_f32 v[124:125], v[50:51], v[130:131]
	v_add_f32_e32 v124, v140, v124
	v_add_f32_e32 v126, v124, v125
	s_waitcnt lgkmcnt(5)
; DEVI float logsigf_(float x) { return fminf(x, 0.f) - __logf(1.f + __expf(-fabsf(x))); }
; DEVI float gla_la(const float* gl, int t, const float* w2r, float gb) { float x = gb;
; #pragma unroll
;     for (int r = 0; r < 16; ++r) x += gl[t * 16 + r] * w2r[r];
;     return logsigf_(x) * (1.f / 16.f); }
; template <int KIND>
; DEVI void mix_state_phase(unsigned char* smem, const MixArgs a) {
;     ...
;             for (int t = sg * 32; t < sg * 32 + 32; ++t) ssum += gla_la(gl, t, w2r, gb);
	v_pk_mul_f32 v[124:125], v[52:53], v[132:133]
	s_nop 0
	v_add_f32_e32 v124, v126, v124
	v_add_f32_e32 v126, v124, v125
	v_pk_mul_f32 v[124:125], v[88:89], v[134:135]
	s_nop 0
	v_add_f32_e32 v124, v126, v124
	v_add_f32_e32 v126, v124, v125
	s_waitcnt lgkmcnt(4)
	v_pk_mul_f32 v[124:125], v[90:91], v[136:137]
	s_nop 0
	v_add_f32_e32 v124, v126, v124
	v_add_f32_e32 v126, v124, v125
	s_waitcnt vmcnt(0)
	v_pk_mul_f32 v[124:125], v[92:93], v[138:139]
	s_nop 0
	v_add_f32_e32 v124, v126, v124
	v_add_f32_e32 v124, v124, v125
	v_min_f32_e32 v125, 0, v124
	v_mul_f32_e64 v124, |v124|, s73
	v_exp_f32_e32 v124, v124
	s_nop 0
	v_add_f32_e32 v124, 1.0, v124
	v_cmp_gt_f32_e32 vcc, s94, v124
	s_nop 1
	v_cndmask_b32_e64 v126, 0, 32, vcc
	v_ldexp_f32 v124, v124, v126
	v_log_f32_e32 v124, v124
	s_nop 0
	v_mul_f32_e32 v126, 0x3f317217, v124
	v_fma_f32 v126, v124, s97, -v126
	v_fmac_f32_e32 v126, 0x3377d1cf, v124
	v_fmac_f32_e32 v126, 0x3f317217, v124
	v_cmp_lt_f32_e64 s[12:13], |v124|, s23
	s_nop 1
	v_cndmask_b32_e64 v124, v124, v126, s[12:13]
	v_cndmask_b32_e32 v126, 0, v211, vcc
	v_sub_f32_e32 v124, v124, v126
	v_sub_f32_e32 v124, v125, v124
	v_fmac_f32_e32 v122, 0x3d800000, v124
	v_mov_b32_e32 v223, v124
	s_waitcnt lgkmcnt(0)
	v_fma_f32 v128, v119, v176, v8
	v_fmac_f32_e32 v128, v120, v177
	v_fmac_f32_e32 v128, v116, v178
	v_fmac_f32_e32 v128, v121, v179
	v_fmac_f32_e32 v128, v117, v180
	v_fmac_f32_e32 v128, v118, v181
	v_pk_mul_f32 v[124:125], v[50:51], v[182:183]
	s_nop 0
	v_add_f32_e32 v124, v128, v124
	v_add_f32_e32 v128, v124, v125
	v_pk_mul_f32 v[124:125], v[52:53], v[184:185]
	s_nop 0
	v_add_f32_e32 v124, v128, v124
	v_add_f32_e32 v128, v124, v125
	v_pk_mul_f32 v[124:125], v[88:89], v[186:187]
	s_nop 0
	v_add_f32_e32 v124, v128, v124
	v_add_f32_e32 v128, v124, v125
	v_pk_mul_f32 v[124:125], v[90:91], v[188:189]
	s_nop 0
	v_add_f32_e32 v123, v128, v124
	v_add_f32_e32 v123, v123, v125
	v_pk_mul_f32 v[124:125], v[92:93], v[190:191]
	s_nop 0
	v_add_f32_e32 v123, v123, v124
	v_add_f32_e32 v123, v123, v125
	v_min_f32_e32 v124, 0, v123
	v_mul_f32_e64 v123, |v123|, s73
	v_exp_f32_e32 v123, v123
	s_nop 0
	v_add_f32_e32 v123, 1.0, v123
	v_cmp_gt_f32_e32 vcc, s94, v123
	s_nop 1
	v_cndmask_b32_e64 v125, 0, 32, vcc
	v_ldexp_f32 v123, v123, v125
	v_log_f32_e32 v123, v123
	s_nop 0
	v_mul_f32_e32 v125, 0x3f317217, v123
	v_fma_f32 v125, v123, s97, -v125
	v_fmac_f32_e32 v125, 0x3377d1cf, v123
	v_fmac_f32_e32 v125, 0x3f317217, v123
	v_cmp_lt_f32_e64 s[12:13], |v123|, s23
	s_nop 1
	v_cndmask_b32_e64 v123, v123, v125, s[12:13]
	v_cndmask_b32_e32 v125, 0, v211, vcc
	v_sub_f32_e32 v123, v123, v125
	v_sub_f32_e32 v123, v124, v123
	v_fmac_f32_e32 v122, 0x3d800000, v123
	v_mov_b32_e32 v224, v123
	v_add_u32_e32 v123, s0, v99
	ds_read_b128 v[124:127], v123
	ds_read_b128 v[128:131], v123 offset:16
	ds_read_b128 v[132:135], v123 offset:32
	ds_read_b128 v[136:139], v123 offset:48
	ds_read_b128 v[176:179], v123 offset:64
	ds_read_b128 v[180:183], v123 offset:80
	ds_read_b128 v[184:187], v123 offset:96
	ds_read_b128 v[188:191], v123 offset:112
	s_addk_i32 s0, 0x80
	s_waitcnt vmcnt(1) lgkmcnt(7)
	v_fma_f32 v140, v119, v124, v8
	v_fmac_f32_e32 v140, v120, v125
	v_fmac_f32_e32 v140, v116, v126
	v_fmac_f32_e32 v140, v121, v127
	s_waitcnt lgkmcnt(6)
	v_fmac_f32_e32 v140, v117, v128
	v_fmac_f32_e32 v140, v118, v129
	v_pk_mul_f32 v[124:125], v[50:51], v[130:131]
	v_add_f32_e32 v124, v140, v124
	v_add_f32_e32 v126, v124, v125
	s_waitcnt lgkmcnt(5)
	v_pk_mul_f32 v[124:125], v[52:53], v[132:133]
	s_nop 0
	v_add_f32_e32 v124, v126, v124
	v_add_f32_e32 v126, v124, v125
	v_pk_mul_f32 v[124:125], v[88:89], v[134:135]
	s_nop 0
	v_add_f32_e32 v124, v126, v124
	v_add_f32_e32 v126, v124, v125
	s_waitcnt lgkmcnt(4)
	v_pk_mul_f32 v[124:125], v[90:91], v[136:137]
	s_nop 0
	v_add_f32_e32 v124, v126, v124
	v_add_f32_e32 v126, v124, v125
	s_waitcnt vmcnt(0)
	v_pk_mul_f32 v[124:125], v[92:93], v[138:139]
	s_nop 0
	v_add_f32_e32 v124, v126, v124
	v_add_f32_e32 v124, v124, v125
	v_min_f32_e32 v125, 0, v124
	v_mul_f32_e64 v124, |v124|, s73
	v_exp_f32_e32 v124, v124
	s_nop 0
	v_add_f32_e32 v124, 1.0, v124
	v_cmp_gt_f32_e32 vcc, s94, v124
	s_nop 1
	v_cndmask_b32_e64 v126, 0, 32, vcc
	v_ldexp_f32 v124, v124, v126
	v_log_f32_e32 v124, v124
	s_nop 0
	v_mul_f32_e32 v126, 0x3f317217, v124
	v_fma_f32 v126, v124, s97, -v126
	v_fmac_f32_e32 v126, 0x3377d1cf, v124
	v_fmac_f32_e32 v126, 0x3f317217, v124
	v_cmp_lt_f32_e64 s[12:13], |v124|, s23
	s_nop 1
	v_cndmask_b32_e64 v124, v124, v126, s[12:13]
	v_cndmask_b32_e32 v126, 0, v211, vcc
	v_sub_f32_e32 v124, v124, v126
	v_sub_f32_e32 v124, v125, v124
	v_fmac_f32_e32 v122, 0x3d800000, v124
	v_mov_b32_e32 v225, v124
	s_waitcnt lgkmcnt(0)
	v_fma_f32 v128, v119, v176, v8
	v_fmac_f32_e32 v128, v120, v177
	v_fmac_f32_e32 v128, v116, v178
	v_fmac_f32_e32 v128, v121, v179
	v_fmac_f32_e32 v128, v117, v180
	v_fmac_f32_e32 v128, v118, v181
	v_pk_mul_f32 v[124:125], v[50:51], v[182:183]
	s_nop 0
	v_add_f32_e32 v124, v128, v124
	v_add_f32_e32 v128, v124, v125
	v_pk_mul_f32 v[124:125], v[52:53], v[184:185]
	s_nop 0
	v_add_f32_e32 v124, v128, v124
	v_add_f32_e32 v128, v124, v125
	v_pk_mul_f32 v[124:125], v[88:89], v[186:187]
	s_nop 0
	v_add_f32_e32 v124, v128, v124
	v_add_f32_e32 v128, v124, v125
	v_pk_mul_f32 v[124:125], v[90:91], v[188:189]
	s_nop 0
	v_add_f32_e32 v123, v128, v124
	v_add_f32_e32 v123, v123, v125
	v_pk_mul_f32 v[124:125], v[92:93], v[190:191]
	s_nop 0
	v_add_f32_e32 v123, v123, v124
	v_add_f32_e32 v123, v123, v125
	v_min_f32_e32 v124, 0, v123
	v_mul_f32_e64 v123, |v123|, s73
	v_exp_f32_e32 v123, v123
	s_nop 0
	v_add_f32_e32 v123, 1.0, v123
	v_cmp_gt_f32_e32 vcc, s94, v123
	s_nop 1
	v_cndmask_b32_e64 v125, 0, 32, vcc
	v_ldexp_f32 v123, v123, v125
	v_log_f32_e32 v123, v123
	s_nop 0
	v_mul_f32_e32 v125, 0x3f317217, v123
	v_fma_f32 v125, v123, s97, -v125
	v_fmac_f32_e32 v125, 0x3377d1cf, v123
	v_fmac_f32_e32 v125, 0x3f317217, v123
	v_cmp_lt_f32_e64 s[12:13], |v123|, s23
	s_nop 1
	v_cndmask_b32_e64 v123, v123, v125, s[12:13]
	v_cndmask_b32_e32 v125, 0, v211, vcc
	v_sub_f32_e32 v123, v123, v125
	v_sub_f32_e32 v123, v124, v123
	v_fmac_f32_e32 v122, 0x3d800000, v123
	v_mov_b32_e32 v226, v123
	v_add_u32_e32 v123, s0, v99
	ds_read_b128 v[124:127], v123
	ds_read_b128 v[128:131], v123 offset:16
	ds_read_b128 v[132:135], v123 offset:32
	ds_read_b128 v[136:139], v123 offset:48
	ds_read_b128 v[176:179], v123 offset:64
	ds_read_b128 v[180:183], v123 offset:80
	ds_read_b128 v[184:187], v123 offset:96
	ds_read_b128 v[188:191], v123 offset:112
	s_addk_i32 s0, 0x80
	s_waitcnt vmcnt(1) lgkmcnt(7)
; DEVI float logsigf_(float x) { return fminf(x, 0.f) - __logf(1.f + __expf(-fabsf(x))); }
; DEVI float gla_la(const float* gl, int t, const float* w2r, float gb) { float x = gb;
; #pragma unroll
;     for (int r = 0; r < 16; ++r) x += gl[t * 16 + r] * w2r[r];
;     return logsigf_(x) * (1.f / 16.f); }
; template <int KIND>
; DEVI void mix_state_phase(unsigned char* smem, const MixArgs a) {
;     ...
;         if (item + (int)gridDim.x < 16 * NCH) ST_PREF(item + (int)gridDim.x);
;     ...
;             for (int t = sg * 32; t < sg * 32 + 32; ++t) ssum += gla_la(gl, t, w2r, gb);
	v_fma_f32 v140, v119, v124, v8
	v_fmac_f32_e32 v140, v120, v125
	v_fmac_f32_e32 v140, v116, v126
	v_fmac_f32_e32 v140, v121, v127
	s_waitcnt lgkmcnt(6)
	v_fmac_f32_e32 v140, v117, v128
	v_fmac_f32_e32 v140, v118, v129
	v_pk_mul_f32 v[124:125], v[50:51], v[130:131]
	v_add_f32_e32 v124, v140, v124
	v_add_f32_e32 v126, v124, v125
	s_waitcnt lgkmcnt(5)
	v_pk_mul_f32 v[124:125], v[52:53], v[132:133]
	s_nop 0
	v_add_f32_e32 v124, v126, v124
	v_add_f32_e32 v126, v124, v125
	v_pk_mul_f32 v[124:125], v[88:89], v[134:135]
	s_nop 0
	v_add_f32_e32 v124, v126, v124
	v_add_f32_e32 v126, v124, v125
	s_waitcnt lgkmcnt(4)
	v_pk_mul_f32 v[124:125], v[90:91], v[136:137]
	s_nop 0
	v_add_f32_e32 v124, v126, v124
	v_add_f32_e32 v126, v124, v125
	s_waitcnt vmcnt(0)
	v_pk_mul_f32 v[124:125], v[92:93], v[138:139]
	s_nop 0
	v_add_f32_e32 v124, v126, v124
	v_add_f32_e32 v124, v124, v125
	v_min_f32_e32 v125, 0, v124
	v_mul_f32_e64 v124, |v124|, s73
	v_exp_f32_e32 v124, v124
	s_nop 0
	v_add_f32_e32 v124, 1.0, v124
	v_cmp_gt_f32_e32 vcc, s94, v124
	s_nop 1
	v_cndmask_b32_e64 v126, 0, 32, vcc
	v_ldexp_f32 v124, v124, v126
	v_log_f32_e32 v124, v124
	s_nop 0
	v_mul_f32_e32 v126, 0x3f317217, v124
	v_fma_f32 v126, v124, s97, -v126
	v_fmac_f32_e32 v126, 0x3377d1cf, v124
	v_fmac_f32_e32 v126, 0x3f317217, v124
	v_cmp_lt_f32_e64 s[12:13], |v124|, s23
	s_nop 1
	v_cndmask_b32_e64 v124, v124, v126, s[12:13]
	v_cndmask_b32_e32 v126, 0, v211, vcc
	v_sub_f32_e32 v124, v124, v126
	v_sub_f32_e32 v124, v125, v124
	v_fmac_f32_e32 v122, 0x3d800000, v124
	v_mov_b32_e32 v227, v124
	s_waitcnt lgkmcnt(0)
	v_fma_f32 v128, v119, v176, v8
	v_fmac_f32_e32 v128, v120, v177
	v_fmac_f32_e32 v128, v116, v178
	v_fmac_f32_e32 v128, v121, v179
	v_fmac_f32_e32 v128, v117, v180
	v_fmac_f32_e32 v128, v118, v181
	v_pk_mul_f32 v[124:125], v[50:51], v[182:183]
	s_nop 0
	v_add_f32_e32 v124, v128, v124
	v_add_f32_e32 v128, v124, v125
	v_pk_mul_f32 v[124:125], v[52:53], v[184:185]
	s_nop 0
	v_add_f32_e32 v124, v128, v124
	v_add_f32_e32 v128, v124, v125
	v_pk_mul_f32 v[124:125], v[88:89], v[186:187]
	s_nop 0
	v_add_f32_e32 v124, v128, v124
	v_add_f32_e32 v128, v124, v125
	v_pk_mul_f32 v[124:125], v[90:91], v[188:189]
	s_nop 0
	v_add_f32_e32 v123, v128, v124
	v_add_f32_e32 v123, v123, v125
	v_pk_mul_f32 v[124:125], v[92:93], v[190:191]
	s_nop 0
	v_add_f32_e32 v123, v123, v124
	v_add_f32_e32 v123, v123, v125
	v_min_f32_e32 v124, 0, v123
	v_mul_f32_e64 v123, |v123|, s73
	v_exp_f32_e32 v123, v123
	s_nop 0
	v_add_f32_e32 v123, 1.0, v123
	v_cmp_gt_f32_e32 vcc, s94, v123
	s_nop 1
	v_cndmask_b32_e64 v125, 0, 32, vcc
	v_ldexp_f32 v123, v123, v125
	v_log_f32_e32 v123, v123
	s_nop 0
	v_mul_f32_e32 v125, 0x3f317217, v123
	v_fma_f32 v125, v123, s97, -v125
	v_fmac_f32_e32 v125, 0x3377d1cf, v123
	v_fmac_f32_e32 v125, 0x3f317217, v123
	v_cmp_lt_f32_e64 s[12:13], |v123|, s23
	s_nop 1
	v_cndmask_b32_e64 v123, v123, v125, s[12:13]
	v_cndmask_b32_e32 v125, 0, v211, vcc
	v_sub_f32_e32 v123, v123, v125
	v_sub_f32_e32 v123, v124, v123
	v_fmac_f32_e32 v122, 0x3d800000, v123
	v_mov_b32_e32 v228, v123
	s_cmpk_gt_i32 s46, 0x3ff
	s_cselect_b64 s[16:17], -1, 0
	s_and_b64 vcc, exec, s[16:17]
	s_cbranch_vccnz .Lpfm_st
	s_ashr_i32 s0, s46, 31
	s_lshr_b32 s0, s0, 26
	s_add_i32 s0, s46, s0
	s_and_b32 s1, s0, 0x1ffffc0
	s_sub_i32 s12, s46, s1
	s_bfe_u32 s15, s0, 0x20006
	s_ashr_i32 s0, s0, 8
	s_ashr_i32 s1, s0, 31
	s_lshl_b32 s12, s12, 7
	s_lshl_b64 s[0:1], s[0:1], 13
	s_ashr_i32 s13, s12, 31
	s_add_u32 s12, s0, s12
	s_addc_u32 s13, s1, s13
	v_lshl_add_u64 v[0:1], s[12:13], 0, v[54:55]
	v_mov_b64_e32 v[46:47], s[28:29]
	v_lshl_add_u64 v[10:11], s[12:13], 0, v[60:61]
	v_lshl_add_u64 v[18:19], s[12:13], 0, v[64:65]
	v_lshl_add_u64 v[26:27], s[12:13], 0, v[68:69]
	v_mad_u64_u32 v[2:3], s[0:1], v0, s95, v[46:47]
	v_mad_u64_u32 v[12:13], s[18:19], v10, s95, v[46:47]
	v_mad_u64_u32 v[20:21], s[18:19], v18, s95, v[46:47]
	v_mad_u64_u32 v[28:29], s[18:19], v26, s95, v[46:47]
	v_mad_i32_i24 v3, v1, s95, v3
	s_lshl_b32 s0, s15, 9
	s_mov_b32 s1, s67
	v_mad_i32_i24 v13, v11, s95, v13
	v_mad_i32_i24 v21, v19, s95, v21
	v_mad_i32_i24 v29, v27, s95, v29
	v_lshl_add_u64 v[0:1], v[2:3], 0, s[0:1]
	v_lshl_add_u64 v[2:3], s[12:13], 0, v[58:59]
	v_lshl_add_u64 v[10:11], v[12:13], 0, s[0:1]
	v_lshl_add_u64 v[12:13], s[12:13], 0, v[62:63]
	v_lshl_add_u64 v[18:19], v[20:21], 0, s[0:1]
	v_lshl_add_u64 v[20:21], s[12:13], 0, v[66:67]
	v_lshl_add_u64 v[26:27], v[28:29], 0, s[0:1]
	v_lshl_add_u64 v[28:29], s[12:13], 0, v[70:71]
	v_mad_u64_u32 v[4:5], s[18:19], v2, s95, v[46:47]
	v_mad_u64_u32 v[14:15], s[18:19], v12, s95, v[46:47]
	v_mad_u64_u32 v[22:23], s[18:19], v20, s95, v[46:47]
	v_mad_u64_u32 v[30:31], s[18:19], v28, s95, v[46:47]
	v_mad_i32_i24 v5, v3, s95, v5
	v_mad_i32_i24 v15, v13, s95, v15
	v_mad_i32_i24 v23, v21, s95, v23
	v_mad_i32_i24 v31, v29, s95, v31
	v_lshl_add_u64 v[34:35], s[12:13], 0, v[56:57]
	v_lshl_add_u64 v[2:3], v[4:5], 0, s[0:1]
	v_lshl_add_u64 v[12:13], v[14:15], 0, s[0:1]
	v_lshl_add_u64 v[20:21], v[22:23], 0, s[0:1]
	v_lshl_add_u64 v[28:29], v[30:31], 0, s[0:1]
	v_mad_u64_u32 v[36:37], s[0:1], v34, s95, v[46:47]
	s_lshl_b32 s66, s15, 8
	v_mad_i32_i24 v37, v35, s95, v37
	v_mov_b32_e32 v85, v9
	v_lshl_add_u64 v[36:37], v[36:37], 0, s[66:67]
	v_mov_b32_e32 v87, v9
	v_lshlrev_b64 v[34:35], 6, v[34:35]
	v_lshl_add_u64 v[0:1], v[0:1], 0, v[84:85]
	v_lshl_add_u64 v[4:5], v[2:3], 0, v[84:85]
	v_lshl_add_u64 v[10:11], v[10:11], 0, v[84:85]
	v_lshl_add_u64 v[14:15], v[12:13], 0, v[84:85]
	v_lshl_add_u64 v[18:19], v[18:19], 0, v[84:85]
	v_lshl_add_u64 v[22:23], v[20:21], 0, v[84:85]
	v_lshl_add_u64 v[26:27], v[26:27], 0, v[84:85]
	v_lshl_add_u64 v[30:31], v[28:29], 0, v[84:85]
	v_lshl_add_u64 v[36:37], v[36:37], 0, v[86:87]
	v_lshl_add_u64 v[38:39], v[78:79], 0, v[34:35]
	global_load_dwordx4 v[0:3], v[0:1], off offset:2048 nt
	s_nop 0
	global_load_dwordx4 v[4:7], v[4:5], off offset:2048 nt
	s_nop 0
	global_load_dwordx4 v[10:13], v[10:11], off offset:2048 nt
	s_nop 0
	global_load_dwordx4 v[14:17], v[14:15], off offset:2048 nt
	s_nop 0
	global_load_dwordx4 v[18:21], v[18:19], off offset:2048 nt
	s_nop 0
	global_load_dwordx4 v[22:25], v[22:23], off offset:2048 nt
	s_nop 0
	global_load_dwordx4 v[26:29], v[26:27], off offset:2048 nt
	s_nop 0
	global_load_dwordx4 v[30:33], v[30:31], off offset:2048 nt
	s_nop 0
	global_load_dwordx4 v[34:37], v[36:37], off offset:1024 nt
	s_nop 0
	global_load_dword v85, v[38:39], off
	v_lshl_add_u64 v[38:39], s[12:13], 0, v[72:73]
	v_mad_u64_u32 v[40:41], s[0:1], v38, s95, v[46:47]
	v_mad_i32_i24 v41, v39, s95, v41
	v_lshl_add_u64 v[40:41], v[40:41], 0, s[66:67]
	v_lshlrev_b64 v[38:39], 6, v[38:39]
	v_lshl_add_u64 v[40:41], v[40:41], 0, v[86:87]
	v_lshl_add_u64 v[42:43], v[78:79], 0, v[38:39]
	global_load_dwordx4 v[38:41], v[40:41], off offset:1024 nt
	s_nop 0
	global_load_dword v97, v[42:43], off
	v_lshl_add_u64 v[42:43], s[12:13], 0, v[74:75]
	v_mad_u64_u32 v[44:45], s[0:1], v42, s95, v[46:47]
	v_mad_i32_i24 v45, v43, s95, v45
	v_lshl_add_u64 v[44:45], v[44:45], 0, s[66:67]
	v_lshlrev_b64 v[42:43], 6, v[42:43]
	v_lshl_add_u64 v[44:45], v[44:45], 0, v[86:87]
	v_lshl_add_u64 v[48:49], v[78:79], 0, v[42:43]
	global_load_dwordx4 v[42:45], v[44:45], off offset:1024 nt
	s_nop 0
	global_load_dword v98, v[48:49], off
	v_lshl_add_u64 v[48:49], s[12:13], 0, v[76:77]
	v_mad_u64_u32 v[46:47], s[0:1], v48, s95, v[46:47]
	v_mad_i32_i24 v47, v49, s95, v47
	v_lshl_add_u64 v[46:47], v[46:47], 0, s[66:67]
	v_lshl_add_u64 v[46:47], v[46:47], 0, v[86:87]
	v_lshlrev_b64 v[48:49], 6, v[48:49]
	v_lshl_add_u64 v[50:51], v[78:79], 0, v[48:49]
	global_load_dwordx4 v[46:49], v[46:47], off offset:1024 nt
	s_nop 0
	global_load_dword v87, v[50:51], off

; DEVI int obid() { int t = blockIdx.x; asm volatile("" : "+s"(t)); return t; }
; template <int KIND>
; DEVI void mix_state_phase(unsigned char* smem, const MixArgs a) {
;     ...
;     if (obid() < 16 * NCH) ST_PREF(obid());
.LBB0_520:
	s_and_b64 vcc, exec, s[2:3]
	s_cbranch_vccz .LBB0_576
	v_mov_b32_e32 v88, v154
	s_mov_b32 s0, s33
	s_cmpk_gt_i32 s0, 0x3ff
	v_lshlrev_b32_e32 v107, 3, v88
	v_ashrrev_i32_e32 v90, 5, v88
	v_add_u32_e32 v62, 0x400, v88
	v_add_u32_e32 v61, 0x600, v88
	v_add_u32_e32 v60, 0x800, v88
	s_waitcnt vmcnt(15)
	v_add_u32_e32 v0, 0xa00, v88
	v_add_u32_e32 v1, 0xc00, v88
	v_add_u32_e32 v2, 0xe00, v88
	s_movk_i32 s0, 0x830
	v_lshlrev_b32_e32 v63, 4, v88
	v_ashrrev_i32_e32 v92, 4, v88
	v_cmp_gt_i32_e32 vcc, s0, v88
	v_ashrrev_i32_e32 v91, 31, v90
	v_add_u32_e32 v122, 0x200, v88
	v_ashrrev_i32_e32 v94, 5, v62
	v_ashrrev_i32_e32 v96, 5, v61
	s_waitcnt vmcnt(2)
	v_ashrrev_i32_e32 v98, 5, v60
	v_ashrrev_i32_e32 v100, 5, v0
	v_ashrrev_i32_e32 v102, 5, v1
	v_ashrrev_i32_e32 v104, 5, v2
	v_and_b32_e32 v106, 0x78, v107
	s_cbranch_scc1 .LBB0_535
	s_mov_b32 s0, s33
	s_ashr_i32 s1, s0, 31
	s_lshr_b32 s1, s1, 26
	s_add_i32 s1, s0, s1
	s_andn2_b32 s1, s1, 63
	s_sub_i32 s1, s0, s1
	s_mov_b32 s0, s33
	s_ashr_i32 s2, s0, 31
	s_lshr_b32 s2, s2, 26
	s_add_i32 s2, s0, s2
	s_bfe_u32 s0, s2, 0x20006
	s_ashr_i32 s2, s2, 8
	s_ashr_i32 s3, s2, 31
	s_lshl_b32 s4, s1, 7
	s_lshl_b64 s[2:3], s[2:3], 13
	s_ashr_i32 s5, s4, 31
	s_add_u32 s4, s2, s4
	s_addc_u32 s5, s3, s5
	v_lshl_add_u64 v[0:1], s[4:5], 0, v[90:91]
	v_mov_b64_e32 v[28:29], s[28:29]
	v_mad_u64_u32 v[2:3], s[2:3], v0, s95, v[28:29]
	v_ashrrev_i32_e32 v95, 31, v94
	v_ashrrev_i32_e32 v99, 31, v98
	v_ashrrev_i32_e32 v103, 31, v102
	v_mad_i32_i24 v3, v1, s95, v3
	s_lshl_b32 s66, s0, 9
	v_add_u32_e32 v10, 0x200, v88
	v_lshl_add_u64 v[12:13], s[4:5], 0, v[94:95]
	v_lshl_add_u64 v[20:21], s[4:5], 0, v[98:99]
	v_lshl_add_u64 v[30:31], s[4:5], 0, v[102:103]
	v_lshl_add_u64 v[0:1], v[2:3], 0, s[66:67]
	v_ashrrev_i32_e32 v2, 5, v10
	v_mad_u64_u32 v[14:15], s[2:3], v12, s95, v[28:29]
	v_mad_u64_u32 v[22:23], s[2:3], v20, s95, v[28:29]
	v_mad_u64_u32 v[32:33], s[2:3], v30, s95, v[28:29]
	v_ashrrev_i32_e32 v3, 31, v2
	v_mad_i32_i24 v15, v13, s95, v15
	v_ashrrev_i32_e32 v97, 31, v96
	v_mad_i32_i24 v23, v21, s95, v23
	v_ashrrev_i32_e32 v101, 31, v100
	v_mad_i32_i24 v33, v31, s95, v33
	v_ashrrev_i32_e32 v105, 31, v104
	v_lshl_add_u64 v[2:3], s[4:5], 0, v[2:3]
	v_lshl_add_u64 v[12:13], v[14:15], 0, s[66:67]
	v_lshl_add_u64 v[14:15], s[4:5], 0, v[96:97]
	v_lshl_add_u64 v[20:21], v[22:23], 0, s[66:67]
	v_lshl_add_u64 v[22:23], s[4:5], 0, v[100:101]
	v_lshl_add_u64 v[30:31], v[32:33], 0, s[66:67]
	v_lshl_add_u64 v[32:33], s[4:5], 0, v[104:105]
	v_mad_u64_u32 v[4:5], s[2:3], v2, s95, v[28:29]
	v_mad_u64_u32 v[16:17], s[2:3], v14, s95, v[28:29]
	v_mad_u64_u32 v[24:25], s[2:3], v22, s95, v[28:29]
	v_mad_u64_u32 v[28:29], s[2:3], v32, s95, v[28:29]
	v_mad_i32_i24 v5, v3, s95, v5
	v_mad_i32_i24 v17, v15, s95, v17
	v_mad_i32_i24 v25, v23, s95, v25
	v_mad_i32_i24 v29, v33, s95, v29
	v_and_b32_e32 v8, 0x1f0, v63
	v_lshl_add_u64 v[2:3], v[4:5], 0, s[66:67]
	v_lshl_add_u64 v[14:15], v[16:17], 0, s[66:67]
	v_lshl_add_u64 v[22:23], v[24:25], 0, s[66:67]
	v_lshl_add_u64 v[28:29], v[28:29], 0, s[66:67]
	v_lshl_add_u64 v[0:1], v[0:1], 0, v[8:9]
	v_lshl_add_u64 v[4:5], v[2:3], 0, v[8:9]
	v_lshl_add_u64 v[12:13], v[12:13], 0, v[8:9]
	v_lshl_add_u64 v[16:17], v[14:15], 0, v[8:9]
	v_lshl_add_u64 v[20:21], v[20:21], 0, v[8:9]
	v_lshl_add_u64 v[24:25], v[22:23], 0, v[8:9]
	v_lshl_add_u64 v[30:31], v[30:31], 0, v[8:9]
	v_lshl_add_u64 v[32:33], v[28:29], 0, v[8:9]
	global_load_dwordx4 v[0:3], v[0:1], off offset:2048 nt
	s_nop 0
	global_load_dwordx4 v[4:7], v[4:5], off offset:2048 nt
	s_nop 0
	global_load_dwordx4 v[12:15], v[12:13], off offset:2048 nt
	s_nop 0
	global_load_dwordx4 v[16:19], v[16:17], off offset:2048 nt
	s_nop 0
	global_load_dwordx4 v[20:23], v[20:21], off offset:2048 nt
	s_nop 0
	global_load_dwordx4 v[24:27], v[24:25], off offset:2048 nt
	s_nop 0
	global_load_dwordx4 v[28:31], v[30:31], off offset:2048 nt
	s_nop 0
	global_load_dwordx4 v[32:35], v[32:33], off offset:2048 nt
	s_cmp_eq_u32 s1, 0
	s_cselect_b64 s[6:7], -1, 0
	s_cmp_lg_u32 s1, 0
	s_cselect_b64 s[8:9], -1, 0
	v_cmp_lt_i32_e64 s[2:3], 2, v92
	v_mov_b32_e32 v38, v9
	v_mov_b32_e32 v39, v9
	s_or_b64 s[2:3], s[2:3], s[8:9]
	v_mov_b32_e32 v36, v9
	v_mov_b32_e32 v37, v9
	v_mov_b64_e32 v[42:43], v[38:39]
	s_lshl_b32 s1, s0, 7
	s_and_b64 s[8:9], vcc, s[2:3]
	v_lshlrev_b32_e32 v56, 1, v106
	v_mov_b64_e32 v[40:41], v[36:37]
	s_and_saveexec_b64 s[2:3], s[8:9]
	s_cbranch_execz .LBB0_524
	v_ashrrev_i32_e32 v93, 31, v92
	v_lshl_add_u64 v[40:41], s[4:5], 0, v[92:93]
	v_mov_b64_e32 v[42:43], s[28:29]
	v_mad_u64_u32 v[42:43], s[8:9], v40, s95, v[42:43]
	v_mad_i32_i24 v43, v41, s95, v43
	s_lshl_b32 s66, s1, 1
	v_lshl_add_u64 v[40:41], v[42:43], 0, s[66:67]
	v_mov_b32_e32 v57, v9
	v_lshl_add_u64 v[40:41], v[40:41], 0, v[56:57]
	v_add_co_u32_e32 v40, vcc, 0xffffc000, v40
	s_nop 1
	v_addc_co_u32_e32 v41, vcc, -1, v41, vcc
	global_load_dwordx4 v[40:43], v[40:41], off offset:-1024 nt
.LBB0_524:
	s_or_b64 exec, exec, s[2:3]
	v_ashrrev_i32_e32 v10, 4, v10
	s_movk_i32 s2, 0x630
	v_cmp_gt_i32_e32 vcc, s2, v88
	v_cmp_lt_i32_e64 s[2:3], 2, v10
	s_xor_b64 s[6:7], s[6:7], -1
	s_or_b64 s[2:3], s[2:3], s[6:7]
	s_and_b64 s[8:9], vcc, s[2:3]
	s_and_saveexec_b64 s[2:3], s[8:9]
	s_cbranch_execz .LBB0_526
	v_ashrrev_i32_e32 v11, 31, v10
	v_lshl_add_u64 v[10:11], s[4:5], 0, v[10:11]
	v_mov_b64_e32 v[36:37], s[28:29]
	v_mad_u64_u32 v[36:37], s[8:9], v10, s95, v[36:37]
	v_mad_i32_i24 v37, v11, s95, v37
	s_lshl_b32 s66, s1, 1
	v_lshl_add_u64 v[10:11], v[36:37], 0, s[66:67]
	v_mov_b32_e32 v57, v9
	v_lshl_add_u64 v[10:11], v[10:11], 0, v[56:57]
	v_add_co_u32_e32 v10, vcc, 0xffffc000, v10
	s_nop 1
	v_addc_co_u32_e32 v11, vcc, -1, v11, vcc
	global_load_dwordx4 v[36:39], v[10:11], off offset:-1024 nt
.LBB0_526:
	s_or_b64 exec, exec, s[2:3]
	s_waitcnt vmcnt(9)
	v_ashrrev_i32_e32 v48, 4, v62
	s_movk_i32 s2, 0x430
	v_cmp_gt_i32_e32 vcc, s2, v88
	v_cmp_lt_i32_e64 s[2:3], 2, v48
	v_mov_b32_e32 v10, v9
	v_mov_b32_e32 v11, v9
	s_or_b64 s[2:3], s[2:3], s[6:7]
	v_mov_b32_e32 v8, v9
	v_mov_b64_e32 v[46:47], v[10:11]
	s_and_b64 s[8:9], vcc, s[2:3]
	v_mov_b64_e32 v[44:45], v[8:9]
	s_and_saveexec_b64 s[2:3], s[8:9]
	s_cbranch_execz .LBB0_528
	v_ashrrev_i32_e32 v49, 31, v48
	v_lshl_add_u64 v[44:45], s[4:5], 0, v[48:49]
	v_mov_b64_e32 v[46:47], s[28:29]
	v_mad_u64_u32 v[46:47], s[8:9], v44, s95, v[46:47]
	v_mad_i32_i24 v47, v45, s95, v47
	s_lshl_b32 s66, s1, 1
	v_lshl_add_u64 v[44:45], v[46:47], 0, s[66:67]
	v_mov_b32_e32 v57, v9
	v_lshl_add_u64 v[44:45], v[44:45], 0, v[56:57]
	v_add_co_u32_e32 v44, vcc, 0xffffc000, v44
	s_nop 1
	v_addc_co_u32_e32 v45, vcc, -1, v45, vcc
	global_load_dwordx4 v[44:47], v[44:45], off offset:-1024 nt
.LBB0_528:
	s_or_b64 exec, exec, s[2:3]
	v_ashrrev_i32_e32 v52, 4, v61
	s_movk_i32 s2, 0x230
	v_cmp_gt_i32_e32 vcc, s2, v88
	v_cmp_lt_i32_e64 s[2:3], 2, v52
	s_or_b64 s[2:3], s[2:3], s[6:7]
	v_mov_b64_e32 v[50:51], v[10:11]
	s_and_b64 s[8:9], vcc, s[2:3]
	v_mov_b64_e32 v[48:49], v[8:9]
	s_and_saveexec_b64 s[2:3], s[8:9]
	s_cbranch_execz .LBB0_530
	v_ashrrev_i32_e32 v53, 31, v52
	v_lshl_add_u64 v[10:11], s[4:5], 0, v[52:53]
	v_mov_b64_e32 v[48:49], s[28:29]
	v_mad_u64_u32 v[48:49], s[8:9], v10, s95, v[48:49]
	v_mad_i32_i24 v49, v11, s95, v49
	s_lshl_b32 s66, s1, 1
	v_lshl_add_u64 v[10:11], v[48:49], 0, s[66:67]
	v_mov_b32_e32 v57, v9
	v_lshl_add_u64 v[10:11], v[10:11], 0, v[56:57]
	v_add_co_u32_e32 v10, vcc, 0xffffc000, v10
	s_nop 1
	v_addc_co_u32_e32 v11, vcc, -1, v11, vcc
	global_load_dwordx4 v[48:51], v[10:11], off offset:-1024 nt
.LBB0_530:
	s_or_b64 exec, exec, s[2:3]
	v_ashrrev_i32_e32 v58, 4, v60
	v_cmp_lt_i32_e64 s[2:3], 2, v58
	v_mov_b32_e32 v10, v9
	v_mov_b32_e32 v11, v9
	v_cmp_gt_i32_e32 vcc, 48, v88
	s_or_b64 s[2:3], s[2:3], s[6:7]
	v_mov_b32_e32 v8, v9
	v_mov_b64_e32 v[54:55], v[10:11]
	s_and_b64 s[6:7], vcc, s[2:3]
	v_mov_b64_e32 v[52:53], v[8:9]
	s_and_saveexec_b64 s[2:3], s[6:7]
	s_cbranch_execz .LBB0_532
	v_ashrrev_i32_e32 v59, 31, v58
	v_lshl_add_u64 v[10:11], s[4:5], 0, v[58:59]
	v_mov_b64_e32 v[52:53], s[28:29]
	v_mad_u64_u32 v[52:53], s[6:7], v10, s95, v[52:53]
	v_mad_i32_i24 v53, v11, s95, v53
	s_lshl_b32 s66, s1, 1
	v_lshl_add_u64 v[10:11], v[52:53], 0, s[66:67]
	v_mov_b32_e32 v57, v9
	v_lshl_add_u64 v[10:11], v[10:11], 0, v[56:57]
	v_add_co_u32_e32 v10, vcc, 0xffffc000, v10
	s_nop 1
	v_addc_co_u32_e32 v11, vcc, -1, v11, vcc
	global_load_dwordx4 v[52:55], v[10:11], off offset:-1024 nt

; template <int KIND>
; DEVI void mix_state_phase(unsigned char* smem, const MixArgs a) {
;     ...
;         if (item + (int)gridDim.x < 16 * NCH) ST_PREF(item + (int)gridDim.x);
.LBB0_546:
	s_or_b64 exec, exec, s[88:89]
	s_add_i32 s46, s86, s22
	s_waitcnt lgkmcnt(0)
	s_barrier
	s_cmpk_gt_i32 s46, 0x3ff
	s_cselect_b64 s[68:69], -1, 0
	s_and_b64 vcc, exec, s[68:69]
	s_cbranch_vccnz .LBB0_560
	s_ashr_i32 s1, s46, 31
	s_lshr_b32 s1, s1, 26
	s_add_i32 s18, s46, s1
	s_and_b32 s1, s18, 0xffffffc0
	s_sub_i32 s26, s46, s1
	s_bfe_u32 s1, s18, 0x20006
	s_ashr_i32 s18, s18, 8
	s_ashr_i32 s19, s18, 31
	s_lshl_b32 s27, s26, 7
	s_lshl_b64 s[18:19], s[18:19], 13
	s_ashr_i32 s38, s27, 31
	s_add_u32 s88, s18, s27
	s_addc_u32 s89, s19, s38
	v_lshl_add_u64 v[0:1], s[88:89], 0, v[90:91]
	v_mov_b64_e32 v[10:11], s[28:29]
	v_lshl_add_u64 v[12:13], s[88:89], 0, v[94:95]
	v_lshl_add_u64 v[20:21], s[88:89], 0, v[98:99]
	v_mad_u64_u32 v[2:3], s[18:19], v0, s95, v[10:11]
	v_mad_u64_u32 v[14:15], s[18:19], v12, s95, v[10:11]
	v_mad_u64_u32 v[22:23], s[18:19], v20, s95, v[10:11]
	v_lshl_add_u64 v[28:29], s[88:89], 0, v[102:103]
	v_mad_i32_i24 v3, v1, s95, v3
	s_lshl_b32 s66, s1, 9
	v_mad_i32_i24 v15, v13, s95, v15
	v_mad_i32_i24 v23, v21, s95, v23
	v_mad_u64_u32 v[30:31], s[18:19], v28, s95, v[10:11]
	v_lshl_add_u64 v[0:1], v[2:3], 0, s[66:67]
	v_lshl_add_u64 v[2:3], s[88:89], 0, v[108:109]
	v_lshl_add_u64 v[12:13], v[14:15], 0, s[66:67]
	v_lshl_add_u64 v[14:15], s[88:89], 0, v[96:97]
	v_lshl_add_u64 v[20:21], v[22:23], 0, s[66:67]
	v_lshl_add_u64 v[22:23], s[88:89], 0, v[100:101]
	v_mad_i32_i24 v31, v29, s95, v31
	v_mad_u64_u32 v[4:5], s[18:19], v2, s95, v[10:11]
	v_mad_u64_u32 v[16:17], s[18:19], v14, s95, v[10:11]
	v_mad_u64_u32 v[24:25], s[18:19], v22, s95, v[10:11]
	v_lshl_add_u64 v[28:29], v[30:31], 0, s[66:67]
	v_lshl_add_u64 v[30:31], s[88:89], 0, v[104:105]
	v_mad_i32_i24 v5, v3, s95, v5
	v_mad_i32_i24 v17, v15, s95, v17
	v_mad_i32_i24 v25, v23, s95, v25
	v_mad_u64_u32 v[10:11], s[18:19], v30, s95, v[10:11]
	v_mov_b32_e32 v121, v9
	v_lshl_add_u64 v[2:3], v[4:5], 0, s[66:67]
	v_lshl_add_u64 v[14:15], v[16:17], 0, s[66:67]
	v_lshl_add_u64 v[22:23], v[24:25], 0, s[66:67]
	v_mad_i32_i24 v11, v31, s95, v11
	v_lshl_add_u64 v[0:1], v[0:1], 0, v[120:121]
	v_lshl_add_u64 v[4:5], v[2:3], 0, v[120:121]
	v_lshl_add_u64 v[12:13], v[12:13], 0, v[120:121]
	v_lshl_add_u64 v[16:17], v[14:15], 0, v[120:121]
	v_lshl_add_u64 v[20:21], v[20:21], 0, v[120:121]
	v_lshl_add_u64 v[24:25], v[22:23], 0, v[120:121]
	v_lshl_add_u64 v[28:29], v[28:29], 0, v[120:121]
	v_lshl_add_u64 v[10:11], v[10:11], 0, s[66:67]
	global_load_dwordx4 v[0:3], v[0:1], off offset:2048 nt
	s_nop 0
	global_load_dwordx4 v[4:7], v[4:5], off offset:2048 nt
	s_nop 0
	global_load_dwordx4 v[12:15], v[12:13], off offset:2048 nt
	s_nop 0
	global_load_dwordx4 v[16:19], v[16:17], off offset:2048 nt
	s_nop 0
	global_load_dwordx4 v[20:23], v[20:21], off offset:2048 nt
	s_nop 0
	global_load_dwordx4 v[24:27], v[24:25], off offset:2048 nt
	v_lshl_add_u64 v[10:11], v[10:11], 0, v[120:121]
	global_load_dwordx4 v[28:31], v[28:29], off offset:2048 nt
	s_nop 0
	global_load_dwordx4 v[32:35], v[10:11], off offset:2048 nt
	s_cmp_eq_u32 s26, 0
	v_readlane_b32 s26, v254, 11
	s_cselect_b64 s[90:91], -1, 0
	v_readlane_b32 s27, v254, 12
	v_mov_b32_e32 v38, v9
	v_mov_b32_e32 v39, v9
	s_and_b64 s[26:27], s[26:27], s[90:91]
	v_mov_b32_e32 v36, v9
	v_mov_b32_e32 v37, v9
	v_mov_b64_e32 v[42:43], v[38:39]
	s_lshl_b32 s18, s1, 7
	s_nor_b64 s[26:27], s[44:45], s[26:27]
	v_lshlrev_b32_e32 v56, 1, v106
	v_mov_b64_e32 v[40:41], v[36:37]
	s_and_saveexec_b64 s[92:93], s[26:27]
	s_cbranch_execz .LBB0_549
	v_lshl_add_u64 v[10:11], s[88:89], 0, v[92:93]
	v_mov_b64_e32 v[40:41], s[28:29]
	v_mad_u64_u32 v[40:41], s[26:27], v10, s95, v[40:41]
	v_mad_i32_i24 v41, v11, s95, v41
	s_lshl_b32 s66, s18, 1
	v_lshl_add_u64 v[10:11], v[40:41], 0, s[66:67]
	v_mov_b32_e32 v57, v9
	v_lshl_add_u64 v[10:11], v[10:11], 0, v[56:57]
	v_add_co_u32_e32 v10, vcc, 0xffffc000, v10
	s_nop 1
	v_addc_co_u32_e32 v11, vcc, -1, v11, vcc
	global_load_dwordx4 v[40:43], v[10:11], off offset:-1024 nt
.LBB0_549:
	s_or_b64 exec, exec, s[92:93]
	v_readlane_b32 s26, v254, 15
	v_readlane_b32 s27, v254, 16
	v_readlane_b32 s38, v254, 13
	s_and_b64 s[26:27], s[26:27], s[90:91]
	v_readlane_b32 s39, v254, 14
	s_nor_b64 s[26:27], s[38:39], s[26:27]
	s_and_saveexec_b64 s[92:93], s[26:27]
	s_cbranch_execz .LBB0_551
	v_lshl_add_u64 v[10:11], s[88:89], 0, v[110:111]
	v_mov_b64_e32 v[36:37], s[28:29]
	v_mad_u64_u32 v[36:37], s[26:27], v10, s95, v[36:37]
	v_mad_i32_i24 v37, v11, s95, v37
	s_lshl_b32 s66, s18, 1
	v_lshl_add_u64 v[10:11], v[36:37], 0, s[66:67]
	v_mov_b32_e32 v57, v9
	v_lshl_add_u64 v[10:11], v[10:11], 0, v[56:57]
	v_add_co_u32_e32 v10, vcc, 0xffffc000, v10
	s_nop 1
	v_addc_co_u32_e32 v11, vcc, -1, v11, vcc
	global_load_dwordx4 v[36:39], v[10:11], off offset:-1024 nt
.LBB0_551:
	s_or_b64 exec, exec, s[92:93]
	v_readlane_b32 s26, v254, 19
	v_readlane_b32 s27, v254, 20
	v_readlane_b32 s38, v254, 17
	v_mov_b32_e32 v10, v9
	v_mov_b32_e32 v11, v9
	s_and_b64 s[26:27], s[26:27], s[90:91]
	v_readlane_b32 s39, v254, 18
	v_mov_b32_e32 v8, v9
	v_mov_b64_e32 v[46:47], v[10:11]
	s_nor_b64 s[26:27], s[38:39], s[26:27]
	v_mov_b64_e32 v[44:45], v[8:9]
	s_and_saveexec_b64 s[92:93], s[26:27]
	s_cbranch_execz .LBB0_553
	v_lshl_add_u64 v[44:45], s[88:89], 0, v[112:113]
	v_mov_b64_e32 v[46:47], s[28:29]
	v_mad_u64_u32 v[46:47], s[26:27], v44, s95, v[46:47]
	v_mad_i32_i24 v47, v45, s95, v47
	s_lshl_b32 s66, s18, 1
	v_lshl_add_u64 v[44:45], v[46:47], 0, s[66:67]
	v_mov_b32_e32 v57, v9
	v_lshl_add_u64 v[44:45], v[44:45], 0, v[56:57]
	v_add_co_u32_e32 v44, vcc, 0xffffc000, v44
	s_nop 1
	v_addc_co_u32_e32 v45, vcc, -1, v45, vcc
	global_load_dwordx4 v[44:47], v[44:45], off offset:-1024 nt
.LBB0_553:
	s_or_b64 exec, exec, s[92:93]
	v_readlane_b32 s26, v254, 23
	v_readlane_b32 s27, v254, 24
	v_readlane_b32 s38, v254, 21
	s_and_b64 s[26:27], s[26:27], s[90:91]
	v_readlane_b32 s39, v254, 22
	v_mov_b64_e32 v[50:51], v[10:11]
	s_nor_b64 s[26:27], s[38:39], s[26:27]
	v_mov_b64_e32 v[48:49], v[8:9]
	s_and_saveexec_b64 s[92:93], s[26:27]
	s_cbranch_execz .LBB0_555
	v_lshl_add_u64 v[10:11], s[88:89], 0, v[114:115]
	v_mov_b64_e32 v[48:49], s[28:29]
	v_mad_u64_u32 v[48:49], s[26:27], v10, s95, v[48:49]
	v_mad_i32_i24 v49, v11, s95, v49
	s_lshl_b32 s66, s18, 1
	v_lshl_add_u64 v[10:11], v[48:49], 0, s[66:67]
	v_mov_b32_e32 v57, v9
	v_lshl_add_u64 v[10:11], v[10:11], 0, v[56:57]
	v_add_co_u32_e32 v10, vcc, 0xffffc000, v10
	s_nop 1
	v_addc_co_u32_e32 v11, vcc, -1, v11, vcc
	global_load_dwordx4 v[48:51], v[10:11], off offset:-1024 nt
.LBB0_555:
	s_or_b64 exec, exec, s[92:93]
	v_readlane_b32 s26, v254, 27
	v_readlane_b32 s27, v254, 28
	v_readlane_b32 s38, v254, 25
	v_mov_b32_e32 v10, v9
	v_mov_b32_e32 v11, v9
	s_and_b64 s[26:27], s[26:27], s[90:91]
	v_readlane_b32 s39, v254, 26
	v_mov_b32_e32 v8, v9
	v_mov_b64_e32 v[54:55], v[10:11]
	s_nor_b64 s[26:27], s[38:39], s[26:27]
	v_mov_b64_e32 v[52:53], v[8:9]
	s_and_saveexec_b64 s[90:91], s[26:27]
	s_cbranch_execz .LBB0_557
	v_lshl_add_u64 v[10:11], s[88:89], 0, v[116:117]
	v_mov_b64_e32 v[52:53], s[28:29]
	v_mad_u64_u32 v[52:53], s[26:27], v10, s95, v[52:53]
	v_mad_i32_i24 v53, v11, s95, v53
	s_lshl_b32 s66, s18, 1
	v_lshl_add_u64 v[10:11], v[52:53], 0, s[66:67]
	v_mov_b32_e32 v57, v9
	v_lshl_add_u64 v[10:11], v[10:11], 0, v[56:57]
	v_add_co_u32_e32 v10, vcc, 0xffffc000, v10
	s_nop 1
	v_addc_co_u32_e32 v11, vcc, -1, v11, vcc
	global_load_dwordx4 v[52:55], v[10:11], off offset:-1024 nt

; DEVI float bf2f(u16 b) { return __uint_as_float(((unsigned)b) << 16); }
; DEVI unsigned cvt_pk(float lo, float hi) { f32v2_t f = {lo, hi}; bf16v2_t v = __builtin_convertvector(f, bf16v2_t); return __builtin_bit_cast(unsigned, v); }
; DEVI float siluf_(float x) { return x * __builtin_amdgcn_rcpf(1.f + __expf(-x)); }
; DEVI void mlstm_conv8_lds(const u16* raw, const float* convw, int t, int c8, int ch0, float* out) {
;     float accv[8];
; #pragma unroll
;     for (int i = 0; i < 8; ++i) accv[i] = 0.f;
; #pragma unroll
;     for (int j = 0; j < 4; ++j) { const bf16x8 x = *(const bf16x8*)(raw + (t + j) * 128 + c8);
;         const f32x4 w0 = *(const f32x4*)(convw + j * 1024 + ch0), w1 = *(const f32x4*)(convw + j * 1024 + ch0 + 4);
; #pragma unroll
;         for (int i = 0; i < 4; ++i) { accv[i] += w0[i] * bf2f((u16)x[i]); accv[4 + i] += w1[i] * bf2f((u16)x[4 + i]); } }
; #pragma unroll
;     for (int i = 0; i < 8; ++i) out[i] = siluf_(accv[i]);
; }
; template <int KIND>
; DEVI void mix_state_phase(unsigned char* smem, const MixArgs a) {
;     ...
;             const float bl = fB[127];
; #pragma unroll 2
;             for (int i = tid; i < 128 * 16; i += 512) { const int t = i >> 4, c8 = (i & 15) * 8; float v[8]; mlstm_conv8_lds(RAWK, a.convw, t, c8, 512 + h * 128 + c8, v); const float w = __expf(bl - fB[t] + fI[t]);
;                 u32x4 pw; pw.x = cvt_pk(v[0] * w, v[1] * w); pw.y = cvt_pk(v[2] * w, v[3] * w); pw.z = cvt_pk(v[4] * w, v[5] * w); pw.w = cvt_pk(v[6] * w, v[7] * w);
;                 *(u32x4*)(KT + t * LP + c8) = pw; }
.LBB0_562:
	s_or_b64 exec, exec, s[88:89]
	s_waitcnt lgkmcnt(0)
	s_barrier
	s_and_saveexec_b64 s[88:89], s[6:7]
	s_cbranch_execz .LBB0_568
	ds_read_b32 v121, v9 offset:508
	s_mov_b64 s[38:39], 0x3800
	s_mov_b64 s[26:27], 0x2800
	s_mov_b64 s[18:19], 0x1800
	s_lshl_b32 s47, s0, 7
	v_mov_b32_e32 v80, v88
	s_mov_b64 s[90:91], exec
	v_readlane_b32 s0, v254, 41
	v_readlane_b32 s1, v254, 42
	s_and_b64 s[0:1], s[90:91], s[0:1]
	s_mov_b64 exec, s[0:1]
	s_cbranch_execz .LBB0_565
	v_or_b32_e32 v8, s47, v106
	v_lshlrev_b32_e32 v8, 2, v8
	v_lshl_add_u64 v[10:11], s[36:37], 0, v[8:9]
	v_add_co_u32_e32 v70, vcc, 0x1000, v10
	ds_read_b128 v[56:59], v142
	s_nop 0
	v_addc_co_u32_e32 v71, vcc, 0, v11, vcc
	global_load_dwordx4 v[60:63], v8, s[36:37] offset:2064
	global_load_dwordx4 v[146:149], v8, s[36:37] offset:2048
	v_add_co_u32_e32 v78, vcc, s49, v10
	ds_read_b128 v[64:67], v142 offset:256
	s_nop 0
	v_addc_co_u32_e32 v79, vcc, 0, v11, vcc
	v_lshl_add_u64 v[68:69], v[10:11], 0, s[18:19]
	global_load_dwordx4 v[150:153], v[70:71], off offset:2048 nt
	global_load_dwordx4 v[72:75], v[68:69], off offset:16 nt
	v_lshl_add_u64 v[76:77], v[10:11], 0, s[26:27]
	v_lshl_add_u64 v[84:85], v[10:11], 0, s[38:39]
	v_add_co_u32_e32 v10, vcc, s53, v10
	ds_read_b128 v[68:71], v142 offset:512
	global_load_dwordx4 v[176:179], v[78:79], off offset:2048 nt
	global_load_dwordx4 v[80:83], v[76:77], off offset:16 nt
	v_addc_co_u32_e32 v11, vcc, 0, v11, vcc
	ds_read_b128 v[76:79], v142 offset:768
	global_load_dwordx4 v[180:183], v[10:11], off offset:2048 nt
	s_nop 0
	global_load_dwordx4 v[84:87], v[84:85], off offset:16 nt
	ds_read2st64_b32 v[10:11], v131 offset1:2
	s_waitcnt lgkmcnt(0)
	v_sub_f32_e32 v8, v121, v10
	v_add_f32_e32 v8, v8, v11
	v_and_b32_e32 v11, 0xffff0000, v56
	v_lshlrev_b32_e32 v10, 16, v56
	v_mul_f32_e32 v8, 0x3fb8aa3b, v8
	v_exp_f32_e32 v8, v8
	s_waitcnt vmcnt(6)
	v_pk_fma_f32 v[10:11], v[146:147], v[10:11], 0 op_sel_hi:[1,1,0]
	v_and_b32_e32 v147, 0xffff0000, v64
	v_lshlrev_b32_e32 v146, 16, v64
	v_lshlrev_b32_e32 v64, 16, v69
	s_waitcnt vmcnt(5)
	v_pk_fma_f32 v[10:11], v[150:151], v[146:147], v[10:11]
	v_and_b32_e32 v147, 0xffff0000, v68
	v_lshlrev_b32_e32 v146, 16, v68
	s_waitcnt vmcnt(3)
	v_pk_fma_f32 v[10:11], v[176:177], v[146:147], v[10:11]
	v_and_b32_e32 v147, 0xffff0000, v76
	v_lshlrev_b32_e32 v146, 16, v76
	s_waitcnt vmcnt(1)
	v_pk_fma_f32 v[10:11], v[180:181], v[146:147], v[10:11]
	s_nop 0
	v_mul_f32_e32 v56, 0xbfb8aa3b, v10
	v_exp_f32_e32 v56, v56
	s_nop 0
	v_add_f32_e32 v56, 1.0, v56
	v_rcp_f32_e32 v146, v56
	v_mul_f32_e32 v56, 0xbfb8aa3b, v11
	v_exp_f32_e32 v56, v56
	s_nop 0
	v_add_f32_e32 v56, 1.0, v56
	v_rcp_f32_e32 v147, v56
	s_nop 0
	v_pk_mul_f32 v[10:11], v[10:11], v[146:147]
	s_nop 0
	v_pk_mul_f32 v[10:11], v[8:9], v[10:11] op_sel_hi:[0,1]
	v_cvt_pk_bf16_f32 v56, v10, v11
	v_and_b32_e32 v11, 0xffff0000, v57
	v_lshlrev_b32_e32 v10, 16, v57
	v_pk_fma_f32 v[10:11], v[148:149], v[10:11], 0 op_sel_hi:[1,1,0]
	v_and_b32_e32 v147, 0xffff0000, v65
	v_lshlrev_b32_e32 v146, 16, v65
	v_pk_fma_f32 v[10:11], v[152:153], v[146:147], v[10:11]
	v_and_b32_e32 v65, 0xffff0000, v69
	v_pk_fma_f32 v[10:11], v[178:179], v[64:65], v[10:11]
	v_and_b32_e32 v65, 0xffff0000, v77
	v_lshlrev_b32_e32 v64, 16, v77
	v_pk_fma_f32 v[10:11], v[182:183], v[64:65], v[10:11]
	s_nop 0
	v_mul_f32_e32 v57, 0xbfb8aa3b, v10
	v_exp_f32_e32 v57, v57
	s_nop 0
	v_add_f32_e32 v57, 1.0, v57
	v_rcp_f32_e32 v64, v57
	v_mul_f32_e32 v57, 0xbfb8aa3b, v11
	v_exp_f32_e32 v57, v57
	s_nop 0
	v_add_f32_e32 v57, 1.0, v57
	v_rcp_f32_e32 v65, v57
	s_nop 0
	v_pk_mul_f32 v[10:11], v[10:11], v[64:65]
	s_nop 0
	v_pk_mul_f32 v[10:11], v[8:9], v[10:11] op_sel_hi:[0,1]
	v_cvt_pk_bf16_f32 v57, v10, v11
	v_and_b32_e32 v11, 0xffff0000, v58
	v_lshlrev_b32_e32 v10, 16, v58
	v_pk_fma_f32 v[10:11], v[60:61], v[10:11], 0 op_sel_hi:[1,1,0]
	v_and_b32_e32 v61, 0xffff0000, v66
	v_lshlrev_b32_e32 v60, 16, v66
	v_pk_fma_f32 v[10:11], v[72:73], v[60:61], v[10:11]
	v_and_b32_e32 v61, 0xffff0000, v70
	v_lshlrev_b32_e32 v60, 16, v70
	v_pk_fma_f32 v[10:11], v[80:81], v[60:61], v[10:11]
	v_and_b32_e32 v61, 0xffff0000, v78
	v_lshlrev_b32_e32 v60, 16, v78
	s_waitcnt vmcnt(0)
	v_pk_fma_f32 v[10:11], v[84:85], v[60:61], v[10:11]
	v_mov_b32_e32 v80, v122
	v_mul_f32_e32 v58, 0xbfb8aa3b, v10
	v_exp_f32_e32 v58, v58
	s_nop 0
	v_add_f32_e32 v58, 1.0, v58
	v_rcp_f32_e32 v60, v58
	v_mul_f32_e32 v58, 0xbfb8aa3b, v11
	v_exp_f32_e32 v58, v58
	s_nop 0
	v_add_f32_e32 v58, 1.0, v58
	v_rcp_f32_e32 v61, v58
	s_nop 0
	v_pk_mul_f32 v[10:11], v[10:11], v[60:61]
	s_nop 0
	v_pk_mul_f32 v[10:11], v[8:9], v[10:11] op_sel_hi:[0,1]
	v_cvt_pk_bf16_f32 v58, v10, v11
	v_and_b32_e32 v11, 0xffff0000, v59
	v_lshlrev_b32_e32 v10, 16, v59
	v_pk_fma_f32 v[10:11], v[62:63], v[10:11], 0 op_sel_hi:[1,1,0]
	v_and_b32_e32 v61, 0xffff0000, v67
	v_lshlrev_b32_e32 v60, 16, v67
	v_pk_fma_f32 v[10:11], v[74:75], v[60:61], v[10:11]
	v_and_b32_e32 v61, 0xffff0000, v71
	v_lshlrev_b32_e32 v60, 16, v71
	v_pk_fma_f32 v[10:11], v[82:83], v[60:61], v[10:11]
	v_and_b32_e32 v61, 0xffff0000, v79
	v_lshlrev_b32_e32 v60, 16, v79
	v_pk_fma_f32 v[10:11], v[86:87], v[60:61], v[10:11]
	s_nop 0
	v_mul_f32_e32 v59, 0xbfb8aa3b, v10
	v_exp_f32_e32 v59, v59
	s_nop 0
	v_add_f32_e32 v59, 1.0, v59
	v_rcp_f32_e32 v60, v59
	v_mul_f32_e32 v59, 0xbfb8aa3b, v11
	v_exp_f32_e32 v59, v59
	s_nop 0
	v_add_f32_e32 v59, 1.0, v59
	v_rcp_f32_e32 v61, v59
	s_nop 0
	v_pk_mul_f32 v[10:11], v[10:11], v[60:61]
	s_nop 0
	v_pk_mul_f32 v[10:11], v[8:9], v[10:11] op_sel_hi:[0,1]
	v_cvt_pk_bf16_f32 v59, v10, v11
	ds_write_b128 v132, v[56:59]

; DEVI float bf2f(u16 b) { return __uint_as_float(((unsigned)b) << 16); }
; DEVI unsigned cvt_pk(float lo, float hi) { f32v2_t f = {lo, hi}; bf16v2_t v = __builtin_convertvector(f, bf16v2_t); return __builtin_bit_cast(unsigned, v); }
; DEVI float siluf_(float x) { return x * __builtin_amdgcn_rcpf(1.f + __expf(-x)); }
; DEVI void mlstm_conv8_lds(const u16* raw, const float* convw, int t, int c8, int ch0, float* out) {
;     float accv[8];
; #pragma unroll
;     for (int i = 0; i < 8; ++i) accv[i] = 0.f;
; #pragma unroll
;     for (int j = 0; j < 4; ++j) { const bf16x8 x = *(const bf16x8*)(raw + (t + j) * 128 + c8);
;         const f32x4 w0 = *(const f32x4*)(convw + j * 1024 + ch0), w1 = *(const f32x4*)(convw + j * 1024 + ch0 + 4);
; #pragma unroll
;         for (int i = 0; i < 4; ++i) { accv[i] += w0[i] * bf2f((u16)x[i]); accv[4 + i] += w1[i] * bf2f((u16)x[4 + i]); } }
; #pragma unroll
;     for (int i = 0; i < 8; ++i) out[i] = siluf_(accv[i]);
; }
; template <int KIND>
; DEVI void mix_state_phase(unsigned char* smem, const MixArgs a) {
;     ...
;             const float bl = fB[127];
; #pragma unroll 2
;             for (int i = tid; i < 128 * 16; i += 512) { const int t = i >> 4, c8 = (i & 15) * 8; float v[8]; mlstm_conv8_lds(RAWK, a.convw, t, c8, 512 + h * 128 + c8, v); const float w = __expf(bl - fB[t] + fI[t]);
;                 u32x4 pw; pw.x = cvt_pk(v[0] * w, v[1] * w); pw.y = cvt_pk(v[2] * w, v[3] * w); pw.z = cvt_pk(v[4] * w, v[5] * w); pw.w = cvt_pk(v[6] * w, v[7] * w);
;                 *(u32x4*)(KT + t * LP + c8) = pw; }
.LBB0_567:
	v_and_b32_e32 v8, 0x78, v81
	v_or_b32_e32 v10, s47, v8
	v_lshlrev_b32_e32 v82, 1, v8
	v_lshlrev_b32_e32 v8, 2, v10
	v_lshl_add_u64 v[72:73], s[36:37], 0, v[8:9]
	v_add_co_u32_e32 v10, vcc, s50, v72
	v_ashrrev_i32_e32 v192, 4, v80
	v_add_u32_e32 v83, s18, v82
	v_addc_co_u32_e32 v11, vcc, 0, v73, vcc
	v_lshl_add_u32 v78, v192, 8, v83
	v_add_co_u32_e32 v76, vcc, s49, v72
	ds_read_b128 v[84:87], v78
	global_load_dwordx4 v[60:63], v8, s[36:37] offset:2048
	global_load_dwordx4 v[56:59], v8, s[36:37] offset:2064
	v_lshl_add_u64 v[68:69], v[72:73], 0, s[26:27]
	v_addc_co_u32_e32 v77, vcc, 0, v73, vcc
	ds_read_b128 v[146:149], v78 offset:256
	global_load_dwordx4 v[64:67], v[10:11], off offset:2048 nt
	global_load_dwordx4 v[150:153], v[68:69], off offset:16 nt
	ds_read_b128 v[176:179], v78 offset:512
	v_lshl_add_u64 v[74:75], v[72:73], 0, s[38:39]
	global_load_dwordx4 v[68:71], v[76:77], off offset:2048 nt
	global_load_dwordx4 v[180:183], v[74:75], off offset:16 nt
	ds_read_b128 v[184:187], v78 offset:768
	v_add_co_u32_e32 v78, vcc, s53, v72
	v_lshl_add_u64 v[162:163], v[72:73], 0, s[42:43]
	s_nop 0
	v_addc_co_u32_e32 v79, vcc, 0, v73, vcc
	global_load_dwordx4 v[72:75], v[78:79], off offset:2048 nt
	global_load_dwordx4 v[188:191], v[162:163], off offset:16 nt
	v_lshl_add_u32 v8, v192, 2, 0
	ds_read2st64_b32 v[162:163], v8 offset1:2
	s_waitcnt lgkmcnt(3)
	v_and_b32_e32 v165, 0xffff0000, v146
	v_lshlrev_b32_e32 v164, 16, v146
	s_movk_i32 s0, 0x3ff
	v_cmp_lt_i32_e32 vcc, s0, v80
	s_waitcnt lgkmcnt(0)
	v_sub_f32_e32 v8, v121, v162
	v_add_f32_e32 v8, v8, v163
	v_and_b32_e32 v163, 0xffff0000, v84
	v_lshlrev_b32_e32 v162, 16, v84
	v_mul_f32_e32 v8, 0x3fb8aa3b, v8
	v_exp_f32_e32 v8, v8
	v_add_u32_e32 v81, 0x2000, v81
	s_or_b64 s[90:91], vcc, s[90:91]
	s_waitcnt vmcnt(7)
	v_pk_fma_f32 v[162:163], v[60:61], v[162:163], 0 op_sel_hi:[1,1,0]
	s_waitcnt vmcnt(5)
	v_pk_fma_f32 v[162:163], v[64:65], v[164:165], v[162:163]
	v_and_b32_e32 v165, 0xffff0000, v176
	v_lshlrev_b32_e32 v164, 16, v176
	s_waitcnt vmcnt(3)
	v_pk_fma_f32 v[162:163], v[68:69], v[164:165], v[162:163]
	v_and_b32_e32 v165, 0xffff0000, v184
	v_lshlrev_b32_e32 v164, 16, v184
	s_waitcnt vmcnt(1)
	v_pk_fma_f32 v[162:163], v[72:73], v[164:165], v[162:163]
	s_nop 0
	v_mul_f32_e32 v84, 0xbfb8aa3b, v162
	v_exp_f32_e32 v84, v84
	s_nop 0
	v_add_f32_e32 v84, 1.0, v84
	v_rcp_f32_e32 v164, v84
	v_mul_f32_e32 v84, 0xbfb8aa3b, v163
	v_exp_f32_e32 v84, v84
	s_nop 0
	v_add_f32_e32 v84, 1.0, v84
	v_rcp_f32_e32 v165, v84
	s_nop 0
	v_pk_mul_f32 v[162:163], v[162:163], v[164:165]
	s_nop 0
	v_pk_mul_f32 v[162:163], v[8:9], v[162:163] op_sel_hi:[0,1]
	v_cvt_pk_bf16_f32 v84, v162, v163
	v_and_b32_e32 v163, 0xffff0000, v85
	v_lshlrev_b32_e32 v162, 16, v85
	v_pk_fma_f32 v[162:163], v[62:63], v[162:163], 0 op_sel_hi:[1,1,0]
	v_and_b32_e32 v165, 0xffff0000, v147
	v_lshlrev_b32_e32 v164, 16, v147
	v_pk_fma_f32 v[146:147], v[66:67], v[164:165], v[162:163]
	v_and_b32_e32 v163, 0xffff0000, v177
	v_lshlrev_b32_e32 v162, 16, v177
	v_pk_fma_f32 v[146:147], v[70:71], v[162:163], v[146:147]
	v_and_b32_e32 v163, 0xffff0000, v185
	v_lshlrev_b32_e32 v162, 16, v185
	v_pk_fma_f32 v[146:147], v[74:75], v[162:163], v[146:147]
	s_nop 0
	v_mul_f32_e32 v85, 0xbfb8aa3b, v146
	v_exp_f32_e32 v85, v85
	s_nop 0
	v_add_f32_e32 v85, 1.0, v85
	v_rcp_f32_e32 v162, v85
	v_mul_f32_e32 v85, 0xbfb8aa3b, v147
	v_exp_f32_e32 v85, v85
	s_nop 0
	v_add_f32_e32 v85, 1.0, v85
	v_rcp_f32_e32 v163, v85
	s_nop 0
	v_pk_mul_f32 v[146:147], v[146:147], v[162:163]
	s_nop 0
	v_pk_mul_f32 v[146:147], v[8:9], v[146:147] op_sel_hi:[0,1]
	v_cvt_pk_bf16_f32 v85, v146, v147
	v_and_b32_e32 v147, 0xffff0000, v86
	v_lshlrev_b32_e32 v146, 16, v86
	v_pk_fma_f32 v[146:147], v[56:57], v[146:147], 0 op_sel_hi:[1,1,0]
	v_and_b32_e32 v163, 0xffff0000, v148
	v_lshlrev_b32_e32 v162, 16, v148
	v_pk_fma_f32 v[146:147], v[150:151], v[162:163], v[146:147]
	v_and_b32_e32 v151, 0xffff0000, v178
	v_lshlrev_b32_e32 v150, 16, v178
	v_pk_fma_f32 v[146:147], v[180:181], v[150:151], v[146:147]
	v_and_b32_e32 v151, 0xffff0000, v186
	v_lshlrev_b32_e32 v150, 16, v186
	s_waitcnt vmcnt(0)
; DEVI float bf2f(u16 b) { return __uint_as_float(((unsigned)b) << 16); }
; DEVI unsigned cvt_pk(float lo, float hi) { f32v2_t f = {lo, hi}; bf16v2_t v = __builtin_convertvector(f, bf16v2_t); return __builtin_bit_cast(unsigned, v); }
; DEVI float siluf_(float x) { return x * __builtin_amdgcn_rcpf(1.f + __expf(-x)); }
; DEVI void mlstm_conv8_lds(const u16* raw, const float* convw, int t, int c8, int ch0, float* out) {
;     float accv[8];
; #pragma unroll
;     for (int i = 0; i < 8; ++i) accv[i] = 0.f;
; #pragma unroll
;     for (int j = 0; j < 4; ++j) { const bf16x8 x = *(const bf16x8*)(raw + (t + j) * 128 + c8);
;         const f32x4 w0 = *(const f32x4*)(convw + j * 1024 + ch0), w1 = *(const f32x4*)(convw + j * 1024 + ch0 + 4);
; #pragma unroll
;         for (int i = 0; i < 4; ++i) { accv[i] += w0[i] * bf2f((u16)x[i]); accv[4 + i] += w1[i] * bf2f((u16)x[4 + i]); } }
; #pragma unroll
;     for (int i = 0; i < 8; ++i) out[i] = siluf_(accv[i]);
; }
; template <int KIND>
; DEVI void mix_state_phase(unsigned char* smem, const MixArgs a) {
;     ...
;             const float bl = fB[127];
; #pragma unroll 2
;             for (int i = tid; i < 128 * 16; i += 512) { const int t = i >> 4, c8 = (i & 15) * 8; float v[8]; mlstm_conv8_lds(RAWK, a.convw, t, c8, 512 + h * 128 + c8, v); const float w = __expf(bl - fB[t] + fI[t]);
;                 u32x4 pw; pw.x = cvt_pk(v[0] * w, v[1] * w); pw.y = cvt_pk(v[2] * w, v[3] * w); pw.z = cvt_pk(v[4] * w, v[5] * w); pw.w = cvt_pk(v[6] * w, v[7] * w);
;                 *(u32x4*)(KT + t * LP + c8) = pw; }
	v_pk_fma_f32 v[146:147], v[188:189], v[150:151], v[146:147]
	v_lshlrev_b32_e32 v148, 16, v179
	v_mul_f32_e32 v86, 0xbfb8aa3b, v146
	v_exp_f32_e32 v86, v86
	s_nop 0
	v_add_f32_e32 v86, 1.0, v86
	v_rcp_f32_e32 v150, v86
	v_mul_f32_e32 v86, 0xbfb8aa3b, v147
	v_exp_f32_e32 v86, v86
	s_nop 0
	v_add_f32_e32 v86, 1.0, v86
	v_rcp_f32_e32 v151, v86
	s_nop 0
	v_pk_mul_f32 v[146:147], v[146:147], v[150:151]
	s_nop 0
	v_pk_mul_f32 v[146:147], v[8:9], v[146:147] op_sel_hi:[0,1]
	v_cvt_pk_bf16_f32 v86, v146, v147
	v_and_b32_e32 v147, 0xffff0000, v87
	v_lshlrev_b32_e32 v146, 16, v87
	v_pk_fma_f32 v[146:147], v[58:59], v[146:147], 0 op_sel_hi:[1,1,0]
	v_and_b32_e32 v151, 0xffff0000, v149
	v_lshlrev_b32_e32 v150, 16, v149
	v_pk_fma_f32 v[146:147], v[152:153], v[150:151], v[146:147]
	v_and_b32_e32 v149, 0xffff0000, v179
	v_pk_fma_f32 v[146:147], v[182:183], v[148:149], v[146:147]
	v_and_b32_e32 v149, 0xffff0000, v187
	v_lshlrev_b32_e32 v148, 16, v187
	v_pk_fma_f32 v[146:147], v[190:191], v[148:149], v[146:147]
	s_nop 0
	v_mul_f32_e32 v87, 0xbfb8aa3b, v146
	v_exp_f32_e32 v87, v87
	s_nop 0
	v_add_f32_e32 v87, 1.0, v87
	v_rcp_f32_e32 v148, v87
	v_mul_f32_e32 v87, 0xbfb8aa3b, v147
	v_exp_f32_e32 v87, v87
	s_nop 0
	v_add_f32_e32 v87, 1.0, v87
	v_rcp_f32_e32 v149, v87
	s_nop 0
	v_pk_mul_f32 v[146:147], v[146:147], v[148:149]
	s_nop 0
	v_pk_mul_f32 v[146:147], v[8:9], v[146:147] op_sel_hi:[0,1]
	v_mul_lo_u32 v8, v192, s52
	v_cvt_pk_bf16_f32 v87, v146, v147
	v_add3_u32 v8, s96, v8, v82
	ds_write_b128 v8, v[84:87]
	v_add_u32_e32 v8, 0x200, v80
	v_ashrrev_i32_e32 v162, 4, v8
	v_lshl_add_u32 v8, v162, 8, v83
	ds_read_b128 v[84:87], v8
	ds_read_b128 v[146:149], v8 offset:256
	global_load_dwordx4 v[150:153], v[10:11], off offset:2064 nt
	global_load_dwordx4 v[180:183], v[76:77], off offset:2064 nt
	ds_read_b128 v[176:179], v8 offset:512
	ds_read_b128 v[184:187], v8 offset:768
	global_load_dwordx4 v[76:79], v[78:79], off offset:2064 nt
	v_lshl_add_u32 v8, v162, 2, 0
	ds_read2st64_b32 v[10:11], v8 offset1:2
	v_add_u32_e32 v80, 0x400, v80
	s_waitcnt lgkmcnt(0)
	v_sub_f32_e32 v8, v121, v10
	v_add_f32_e32 v8, v8, v11
	v_and_b32_e32 v11, 0xffff0000, v84
	v_lshlrev_b32_e32 v10, 16, v84
	v_pk_fma_f32 v[10:11], v[60:61], v[10:11], 0 op_sel_hi:[1,1,0]
	v_and_b32_e32 v61, 0xffff0000, v146
	v_lshlrev_b32_e32 v60, 16, v146
	v_pk_fma_f32 v[10:11], v[64:65], v[60:61], v[10:11]
	v_and_b32_e32 v61, 0xffff0000, v176
	v_lshlrev_b32_e32 v60, 16, v176
	v_pk_fma_f32 v[10:11], v[68:69], v[60:61], v[10:11]
	v_and_b32_e32 v61, 0xffff0000, v184
	v_lshlrev_b32_e32 v60, 16, v184
	v_pk_fma_f32 v[10:11], v[72:73], v[60:61], v[10:11]
	v_mul_f32_e32 v8, 0x3fb8aa3b, v8
	v_mul_f32_e32 v60, 0xbfb8aa3b, v10
	v_mul_f32_e32 v61, 0xbfb8aa3b, v11
	v_exp_f32_e32 v60, v60
	v_exp_f32_e32 v61, v61
	v_exp_f32_e32 v8, v8
	v_add_f32_e32 v60, 1.0, v60
	v_add_f32_e32 v61, 1.0, v61
	v_rcp_f32_e32 v60, v60
	v_rcp_f32_e32 v61, v61
	s_nop 0
	v_pk_mul_f32 v[10:11], v[10:11], v[60:61]
	s_nop 0
	v_pk_mul_f32 v[10:11], v[8:9], v[10:11] op_sel_hi:[0,1]
	v_cvt_pk_bf16_f32 v60, v10, v11
	v_and_b32_e32 v11, 0xffff0000, v85
	v_lshlrev_b32_e32 v10, 16, v85
	v_pk_fma_f32 v[10:11], v[62:63], v[10:11], 0 op_sel_hi:[1,1,0]
	v_and_b32_e32 v63, 0xffff0000, v147
	v_lshlrev_b32_e32 v62, 16, v147
	v_pk_fma_f32 v[10:11], v[66:67], v[62:63], v[10:11]
	v_and_b32_e32 v63, 0xffff0000, v177
	v_lshlrev_b32_e32 v62, 16, v177
	v_pk_fma_f32 v[10:11], v[70:71], v[62:63], v[10:11]
	v_and_b32_e32 v63, 0xffff0000, v185
	v_lshlrev_b32_e32 v62, 16, v185
	v_pk_fma_f32 v[10:11], v[74:75], v[62:63], v[10:11]
	s_nop 0
	v_mul_f32_e32 v61, 0xbfb8aa3b, v10
	v_exp_f32_e32 v61, v61
	s_nop 0
	v_add_f32_e32 v61, 1.0, v61
	v_rcp_f32_e32 v62, v61
	v_mul_f32_e32 v61, 0xbfb8aa3b, v11
	v_exp_f32_e32 v61, v61
	s_nop 0
	v_add_f32_e32 v61, 1.0, v61
	v_rcp_f32_e32 v63, v61
	s_nop 0
	v_pk_mul_f32 v[10:11], v[10:11], v[62:63]
	s_nop 0
	v_pk_mul_f32 v[10:11], v[8:9], v[10:11] op_sel_hi:[0,1]
	v_cvt_pk_bf16_f32 v61, v10, v11
	v_and_b32_e32 v11, 0xffff0000, v86
	v_lshlrev_b32_e32 v10, 16, v86
	v_pk_fma_f32 v[10:11], v[56:57], v[10:11], 0 op_sel_hi:[1,1,0]
	v_and_b32_e32 v57, 0xffff0000, v148
	v_lshlrev_b32_e32 v56, 16, v148
	s_waitcnt vmcnt(2)
	v_pk_fma_f32 v[10:11], v[150:151], v[56:57], v[10:11]
	v_and_b32_e32 v57, 0xffff0000, v178
	v_lshlrev_b32_e32 v56, 16, v178
	s_waitcnt vmcnt(1)
	v_pk_fma_f32 v[10:11], v[180:181], v[56:57], v[10:11]
	v_and_b32_e32 v57, 0xffff0000, v186
	v_lshlrev_b32_e32 v56, 16, v186
	s_waitcnt vmcnt(0)
	v_pk_fma_f32 v[10:11], v[76:77], v[56:57], v[10:11]
	s_nop 0
	v_mul_f32_e32 v56, 0xbfb8aa3b, v10
	v_mul_f32_e32 v57, 0xbfb8aa3b, v11
	v_exp_f32_e32 v56, v56
	v_exp_f32_e32 v57, v57
	v_add_f32_e32 v56, 1.0, v56
	v_add_f32_e32 v57, 1.0, v57
	v_rcp_f32_e32 v56, v56
	v_rcp_f32_e32 v57, v57
	s_nop 0
	v_pk_mul_f32 v[10:11], v[10:11], v[56:57]
	s_nop 0
	v_pk_mul_f32 v[10:11], v[8:9], v[10:11] op_sel_hi:[0,1]
	v_cvt_pk_bf16_f32 v62, v10, v11
	v_and_b32_e32 v11, 0xffff0000, v87
	v_lshlrev_b32_e32 v10, 16, v87
	v_pk_fma_f32 v[10:11], v[58:59], v[10:11], 0 op_sel_hi:[1,1,0]
	v_and_b32_e32 v57, 0xffff0000, v149
	v_lshlrev_b32_e32 v56, 16, v149
	v_pk_fma_f32 v[10:11], v[152:153], v[56:57], v[10:11]
	v_and_b32_e32 v57, 0xffff0000, v179
	v_lshlrev_b32_e32 v56, 16, v179
	v_pk_fma_f32 v[10:11], v[182:183], v[56:57], v[10:11]
	v_and_b32_e32 v57, 0xffff0000, v187
	v_lshlrev_b32_e32 v56, 16, v187
	v_pk_fma_f32 v[10:11], v[78:79], v[56:57], v[10:11]
	s_nop 0
	v_mul_f32_e32 v56, 0xbfb8aa3b, v10
	v_mul_f32_e32 v57, 0xbfb8aa3b, v11
	v_exp_f32_e32 v56, v56
	v_exp_f32_e32 v57, v57
	v_add_f32_e32 v56, 1.0, v56
	v_add_f32_e32 v57, 1.0, v57
	v_rcp_f32_e32 v56, v56
	v_rcp_f32_e32 v57, v57
	s_nop 0
	v_pk_mul_f32 v[10:11], v[10:11], v[56:57]
	s_nop 0
	v_pk_mul_f32 v[10:11], v[8:9], v[10:11] op_sel_hi:[0,1]
	v_mul_lo_u32 v8, v162, s52
	v_cvt_pk_bf16_f32 v63, v10, v11
	v_add3_u32 v8, s96, v8, v82
	ds_write_b128 v8, v[60:63]
	s_andn2_b64 exec, exec, s[90:91]
	s_cbranch_execnz .LBB0_567

; DEVI int obid() { int t = blockIdx.x; asm volatile("" : "+s"(t)); return t; }
; template <int KIND>
; DEVI void mix_out_phase(unsigned char* smem, const MixArgs a) {
;     ...
;     if (KIND == 1 && obid() < 16 * NCH) OUT_PREF(obid());
.LBB0_682:
	s_or_b64 exec, exec, s[2:3]
	v_readlane_b32 s0, v254, 5
	v_readlane_b32 s1, v254, 6
	s_mov_b64 s[2:3], -1
	s_and_b64 vcc, exec, s[0:1]
	s_waitcnt lgkmcnt(0)
	s_barrier
	s_cbranch_vccz .LBB0_772
	s_waitcnt vmcnt(0)
	v_mov_b32_e32 v37, v154
	s_mov_b32 s0, s33
	v_and_b32_e32 v36, 15, v37
	v_ashrrev_i32_e32 v146, 4, v37
	v_add_u32_e32 v38, 0x200, v37
	v_add_u32_e32 v0, 0x400, v37
	v_add_u32_e32 v1, 0x600, v37
	s_cmpk_gt_i32 s0, 0x3ff
	v_lshlrev_b32_e32 v8, 4, v36
	v_lshlrev_b32_e32 v34, 2, v36
	v_ashrrev_i32_e32 v147, 31, v146
	v_ashrrev_i32_e32 v148, 4, v38
	v_ashrrev_i32_e32 v150, 4, v0
	v_ashrrev_i32_e32 v152, 4, v1
	s_cbranch_scc1 .LBB0_685
	s_mov_b32 s0, s33
	s_ashr_i32 s1, s0, 31
	s_lshr_b32 s1, s1, 26
	s_add_i32 s1, s0, s1
	s_and_b32 s1, s1, 0x1ffffc0
	s_sub_i32 s2, s0, s1
	s_mov_b32 s0, s33
	s_ashr_i32 s1, s0, 31
	s_lshr_b32 s1, s1, 26
	s_add_i32 s3, s0, s1
	s_ashr_i32 s0, s3, 8
	s_ashr_i32 s1, s0, 31
	s_lshl_b32 s2, s2, 7
	s_lshl_b64 s[0:1], s[0:1], 13
	s_ashr_i32 s4, s2, 31
	s_add_u32 s0, s0, s2
	s_addc_u32 s1, s1, s4
	s_lshl_b32 s2, s3, 2
	s_and_b32 s2, s2, 0x300
	s_add_u32 s2, s28, s2
	s_addc_u32 s3, s29, 0
	v_ashrrev_i32_e32 v149, 31, v148
	v_ashrrev_i32_e32 v151, 31, v150
	v_ashrrev_i32_e32 v153, 31, v152
	v_lshl_add_u64 v[26:27], s[2:3], 0, v[8:9]
	v_lshl_add_u64 v[10:11], s[0:1], 0, v[146:147]
	v_lshl_add_u64 v[18:19], s[0:1], 0, v[148:149]
	v_lshl_add_u64 v[28:29], s[0:1], 0, v[150:151]
	v_lshl_add_u64 v[42:43], s[0:1], 0, v[152:153]
	v_mov_b32_e32 v35, v9
	v_mad_u64_u32 v[4:5], s[2:3], v10, s95, v[26:27]
	v_mad_u64_u32 v[14:15], s[2:3], v18, s95, v[26:27]
	v_mad_u64_u32 v[22:23], s[2:3], v28, s95, v[26:27]
	v_mad_u64_u32 v[30:31], s[0:1], v42, s95, v[26:27]
	v_lshl_add_u64 v[40:41], s[58:59], 0, v[34:35]
	v_mad_i32_i24 v5, v11, s95, v5
	v_lshlrev_b64 v[10:11], 6, v[10:11]
	v_mad_i32_i24 v15, v19, s95, v15
	v_lshlrev_b64 v[18:19], 6, v[18:19]
	v_mad_i32_i24 v23, v29, s95, v23
	v_lshlrev_b64 v[28:29], 6, v[28:29]
	v_mad_i32_i24 v31, v43, s95, v31
	v_lshlrev_b64 v[42:43], 6, v[42:43]
	v_lshl_add_u64 v[10:11], v[40:41], 0, v[10:11]
	v_lshl_add_u64 v[18:19], v[40:41], 0, v[18:19]
	v_lshl_add_u64 v[28:29], v[40:41], 0, v[28:29]
	v_lshl_add_u64 v[40:41], v[40:41], 0, v[42:43]
	global_load_dwordx4 v[0:3], v[4:5], off nt
	s_nop 0
	global_load_dwordx4 v[4:7], v[4:5], off offset:1024 nt
	s_nop 0
	global_load_dword v185, v[10:11], off
	s_nop 0
	global_load_dwordx4 v[10:13], v[14:15], off nt
	s_nop 0
	global_load_dwordx4 v[14:17], v[14:15], off offset:1024 nt
	s_nop 0
	global_load_dword v200, v[18:19], off
	s_nop 0
	global_load_dwordx4 v[18:21], v[22:23], off nt
	s_nop 0
	global_load_dwordx4 v[22:25], v[22:23], off offset:1024 nt
	s_nop 0
	global_load_dword v201, v[28:29], off
	s_nop 0
	global_load_dwordx4 v[26:29], v[30:31], off nt
	s_nop 0
	global_load_dwordx4 v[30:33], v[30:31], off offset:1024 nt
	s_nop 0
	global_load_dword v207, v[40:41], off

; DEVI float logsigf_(float x) { return fminf(x, 0.f) - __logf(1.f + __expf(-fabsf(x))); }
; DEVI void lds_barrier() { asm volatile("s_waitcnt lgkmcnt(0)\n\ts_barrier" ::: "memory"); }
; #define MIX_PREF(qq, bb) do { _Pragma("unroll") for (int k = 0; k < 2; ++k) { const int i = tid + k * 512; \
;             pv[bb][k] = *(const u32x4*)(a.proj + (tok0 + (i >> 3)) * 3072 + 1024 + h * 256 + (qq) * 64 + (i & 7) * 8); \
;             pc[bb][k] = *(const u32x4*)(a.states + ((size_t)item * 256 + (qq) * 64 + (i >> 4)) * 128 + (i & 15) * 8); } } while (0)
; template <int KIND>
; DEVI void mix_out_phase(unsigned char* smem, const MixArgs a) {
;     ...
;         MIX_PREF(0, 0);
;         lds_barrier();
;         if (KIND == 0) {
; #pragma unroll
;             for (int k = 0; k < 9; ++k) { const int q = tid + k * 512; if (q < 131 * 32) *(u32x4*)(RAW + ((q >> 4) & 1) * (131 * 128) + (q >> 5) * 128 + (q & 15) * 8) = prq[k]; }
;             if (tid < 128) { fI[tid] = pg[0] + a.gateb[h]; fB[tid] = logsigf_(pg[1] + a.gateb[4 + h]); fN[tid] = pg[2]; }
;         } else {
; #pragma unroll
;             for (int k = 0; k < 4; ++k) { const int i = tid + k * 512; *(u32x4*)(QS + (i >> 4) * LP + (i & 15) * 8) = prq[k]; *(u32x4*)(KS + (i >> 4) * LP + (i & 15) * 8) = prq[4 + k]; gl[i] = pg[k]; }
;         }
;         lds_barrier();
.LBB0_688:
	s_ashr_i32 s47, s88, 31
	s_lshr_b32 s0, s47, 26
	s_add_i32 s1, s88, s0
	s_and_b32 s0, s1, 0x1ffffc0
	s_sub_i32 s16, s88, s0
	s_ashr_i32 s14, s1, 8
	s_bfe_u32 s0, s1, 0x20006
	s_ashr_i32 s15, s14, 31
	s_lshl_b32 s1, s16, 7
	s_lshl_b64 s[14:15], s[14:15], 13
	s_ashr_i32 s16, s1, 31
	s_add_u32 s68, s14, s1
	s_addc_u32 s69, s15, s16
	s_mov_b32 s46, s88
	s_lshl_b64 s[14:15], s[46:47], 16
	v_lshl_add_u64 v[36:37], s[68:69], 0, v[186:187]
	v_mov_b64_e32 v[38:39], s[28:29]
	v_lshl_add_u64 v[34:35], v[178:179], 0, s[14:15]
	v_mad_u64_u32 v[40:41], s[14:15], v36, s95, v[38:39]
	v_mad_i32_i24 v41, v37, s95, v41
	s_lshl_b32 s66, s0, 9
	v_lshl_add_u64 v[36:37], v[40:41], 0, s[66:67]
	v_lshl_add_u64 v[40:41], s[68:69], 0, v[190:191]
	v_mad_u64_u32 v[38:39], s[14:15], v40, s95, v[38:39]
	v_mad_i32_i24 v39, v41, s95, v39
	v_lshl_add_u64 v[130:131], v[36:37], 0, v[8:9]
	v_lshl_add_u64 v[36:37], v[34:35], 0, v[188:189]
	v_lshl_add_u64 v[38:39], v[38:39], 0, s[66:67]
	v_lshl_add_u64 v[134:135], v[38:39], 0, v[8:9]
	global_load_dwordx4 v[50:53], v[130:131], off offset:2048 nt
	global_load_dwordx4 v[42:45], v[134:135], off offset:2048 nt
	v_lshl_add_u64 v[34:35], v[34:35], 0, v[192:193]
	global_load_dwordx4 v[54:57], v[36:37], off nt
	global_load_dwordx4 v[46:49], v[34:35], off nt
	s_waitcnt lgkmcnt(0)
	s_barrier
	s_waitcnt vmcnt(15)
	ds_write_b128 v213, v[0:3] offset:16384
	s_waitcnt vmcnt(14)
	ds_write_b128 v213, v[4:7] offset:51200
	s_waitcnt vmcnt(13)
	ds_write_b32 v204, v185 offset:4096
	s_waitcnt vmcnt(12)
	ds_write_b128 v215, v[10:13] offset:16384
	s_waitcnt vmcnt(11)
	ds_write_b128 v215, v[14:17] offset:51200
	s_waitcnt vmcnt(10)
	ds_write_b32 v204, v200 offset:6144
	s_waitcnt vmcnt(9)
	ds_write_b128 v194, v[18:21] offset:16384
	s_waitcnt vmcnt(8)
	ds_write_b128 v194, v[22:25] offset:51200
	s_waitcnt vmcnt(7)
	ds_write_b32 v204, v201 offset:8192
	s_waitcnt vmcnt(6)
	ds_write_b128 v196, v[26:29] offset:16384
	s_waitcnt vmcnt(5)
	ds_write_b128 v196, v[30:33] offset:51200
	s_waitcnt vmcnt(4)
	ds_write_b32 v204, v207 offset:10240
	s_add_i32 s88, s88, s22
	s_waitcnt lgkmcnt(0)
	s_barrier

; DEVI float logsigf_(float x) { return fminf(x, 0.f) - __logf(1.f + __expf(-fabsf(x))); }
; DEVI float gla_la(const float* gl, int t, const float* w2r, float gb) { float x = gb;
; #pragma unroll
;     for (int r = 0; r < 16; ++r) x += gl[t * 16 + r] * w2r[r];
;     return logsigf_(x) * (1.f / 16.f); }
; template <int KIND>
; DEVI void mix_out_phase(unsigned char* smem, const MixArgs a) {
;     ...
;             for (int t = sg * 32; t < sg * 32 + 32; ++t) ssum += gla_la(gl, t, w2r, gb);
.LBB0_691:
	v_add_u32_e32 v84, s0, v195
	ds_read_b128 v[68:71], v84
	ds_read_b128 v[72:75], v84 offset:16
	ds_read_b128 v[76:79], v84 offset:32
	ds_read_b128 v[80:83], v84 offset:48
	ds_read_b128 v[100:103], v84 offset:64
	ds_read_b128 v[104:107], v84 offset:80
	ds_read_b128 v[108:111], v84 offset:96
	ds_read_b128 v[112:115], v84 offset:112
	s_addk_i32 s0, 0x80
	s_waitcnt vmcnt(1) lgkmcnt(7)
	v_fma_f32 v85, v63, v68, v66
	v_fmac_f32_e32 v85, v64, v69
	v_fmac_f32_e32 v85, v60, v70
	v_fmac_f32_e32 v85, v65, v71
	s_waitcnt lgkmcnt(6)
	v_fmac_f32_e32 v85, v61, v72
	v_fmac_f32_e32 v85, v62, v73
	v_pk_mul_f32 v[68:69], v[34:35], v[74:75]
	v_add_f32_e32 v68, v85, v68
	v_add_f32_e32 v70, v68, v69
	s_waitcnt lgkmcnt(5)
	v_pk_mul_f32 v[68:69], v[36:37], v[76:77]
	s_nop 0
	v_add_f32_e32 v68, v70, v68
	v_add_f32_e32 v70, v68, v69
	v_pk_mul_f32 v[68:69], v[38:39], v[78:79]
	s_nop 0
	v_add_f32_e32 v68, v70, v68
	v_add_f32_e32 v70, v68, v69
	s_waitcnt lgkmcnt(4)
	v_pk_mul_f32 v[68:69], v[40:41], v[80:81]
	s_nop 0
	v_add_f32_e32 v68, v70, v68
	v_add_f32_e32 v70, v68, v69
	s_waitcnt vmcnt(0)
	v_pk_mul_f32 v[68:69], v[58:59], v[82:83]
	s_nop 0
	v_add_f32_e32 v68, v70, v68
	v_add_f32_e32 v68, v68, v69
	v_min_f32_e32 v69, 0, v68
	v_mul_f32_e64 v68, |v68|, s73
	v_exp_f32_e32 v68, v68
	s_nop 0
	v_add_f32_e32 v68, 1.0, v68
	v_cmp_gt_f32_e32 vcc, s94, v68
	s_nop 1
	v_cndmask_b32_e64 v70, 0, 32, vcc
	v_ldexp_f32 v68, v68, v70
	v_log_f32_e32 v68, v68
	s_nop 0
	v_mul_f32_e32 v70, 0x3f317217, v68
	v_fma_f32 v70, v68, s97, -v70
	v_fmac_f32_e32 v70, 0x3377d1cf, v68
	v_fmac_f32_e32 v70, 0x3f317217, v68
	v_cmp_lt_f32_e64 s[14:15], |v68|, s23
	s_nop 1
	v_cndmask_b32_e64 v68, v68, v70, s[14:15]
	v_cndmask_b32_e32 v70, 0, v211, vcc
	v_sub_f32_e32 v68, v68, v70
	v_sub_f32_e32 v68, v69, v68
	v_fmac_f32_e32 v67, 0x3d800000, v68
	v_mov_b32_e32 v86, v68
	s_waitcnt lgkmcnt(0)
	v_fma_f32 v72, v63, v100, v66
	v_fmac_f32_e32 v72, v64, v101
	v_fmac_f32_e32 v72, v60, v102
	v_fmac_f32_e32 v72, v65, v103
	v_fmac_f32_e32 v72, v61, v104
	v_fmac_f32_e32 v72, v62, v105
	v_pk_mul_f32 v[68:69], v[34:35], v[106:107]
	s_nop 0
	v_add_f32_e32 v68, v72, v68
	v_add_f32_e32 v72, v68, v69
	v_pk_mul_f32 v[68:69], v[36:37], v[108:109]
	s_nop 0
	v_add_f32_e32 v68, v72, v68
	v_add_f32_e32 v72, v68, v69
	v_pk_mul_f32 v[68:69], v[38:39], v[110:111]
	s_nop 0
	v_add_f32_e32 v68, v72, v68
	v_add_f32_e32 v72, v68, v69
	v_pk_mul_f32 v[68:69], v[40:41], v[112:113]
	s_nop 0
	v_add_f32_e32 v68, v72, v68
	v_add_f32_e32 v72, v68, v69
	v_pk_mul_f32 v[68:69], v[58:59], v[114:115]
	s_nop 0
	v_add_f32_e32 v68, v72, v68
	v_add_f32_e32 v68, v68, v69
	v_min_f32_e32 v69, 0, v68
	v_mul_f32_e64 v68, |v68|, s73
	v_exp_f32_e32 v68, v68
	s_nop 0
	v_add_f32_e32 v68, 1.0, v68
	v_cmp_gt_f32_e32 vcc, s94, v68
	s_nop 1
	v_cndmask_b32_e64 v70, 0, 32, vcc
	v_ldexp_f32 v68, v68, v70
	v_log_f32_e32 v68, v68
	s_nop 0
	v_mul_f32_e32 v70, 0x3f317217, v68
	v_fma_f32 v70, v68, s97, -v70
	v_fmac_f32_e32 v70, 0x3377d1cf, v68
	v_fmac_f32_e32 v70, 0x3f317217, v68
	v_cmp_lt_f32_e64 s[14:15], |v68|, s23
	s_nop 1
	v_cndmask_b32_e64 v68, v68, v70, s[14:15]
	v_cndmask_b32_e32 v70, 0, v211, vcc
	v_sub_f32_e32 v68, v68, v70
	v_sub_f32_e32 v68, v69, v68
	v_fmac_f32_e32 v67, 0x3d800000, v68
	v_mov_b32_e32 v87, v68
	v_add_u32_e32 v84, s0, v195
	ds_read_b128 v[68:71], v84
	ds_read_b128 v[72:75], v84 offset:16
	ds_read_b128 v[76:79], v84 offset:32
	ds_read_b128 v[80:83], v84 offset:48
	ds_read_b128 v[100:103], v84 offset:64
	ds_read_b128 v[104:107], v84 offset:80
	ds_read_b128 v[108:111], v84 offset:96
	ds_read_b128 v[112:115], v84 offset:112
	s_addk_i32 s0, 0x80
	s_waitcnt vmcnt(1) lgkmcnt(7)
	v_fma_f32 v85, v63, v68, v66
	v_fmac_f32_e32 v85, v64, v69
	v_fmac_f32_e32 v85, v60, v70
	v_fmac_f32_e32 v85, v65, v71
	s_waitcnt lgkmcnt(6)
	v_fmac_f32_e32 v85, v61, v72
	v_fmac_f32_e32 v85, v62, v73
	v_pk_mul_f32 v[68:69], v[34:35], v[74:75]
	v_add_f32_e32 v68, v85, v68
	v_add_f32_e32 v70, v68, v69
	s_waitcnt lgkmcnt(5)
	v_pk_mul_f32 v[68:69], v[36:37], v[76:77]
	s_nop 0
	v_add_f32_e32 v68, v70, v68
	v_add_f32_e32 v70, v68, v69
	v_pk_mul_f32 v[68:69], v[38:39], v[78:79]
	s_nop 0
	v_add_f32_e32 v68, v70, v68
	v_add_f32_e32 v70, v68, v69
	s_waitcnt lgkmcnt(4)
	v_pk_mul_f32 v[68:69], v[40:41], v[80:81]
	s_nop 0
	v_add_f32_e32 v68, v70, v68
	v_add_f32_e32 v70, v68, v69
	s_waitcnt vmcnt(0)
	v_pk_mul_f32 v[68:69], v[58:59], v[82:83]
	s_nop 0
	v_add_f32_e32 v68, v70, v68
	v_add_f32_e32 v68, v68, v69
	v_min_f32_e32 v69, 0, v68
	v_mul_f32_e64 v68, |v68|, s73
	v_exp_f32_e32 v68, v68
	s_nop 0
	v_add_f32_e32 v68, 1.0, v68
	v_cmp_gt_f32_e32 vcc, s94, v68
	s_nop 1
	v_cndmask_b32_e64 v70, 0, 32, vcc
	v_ldexp_f32 v68, v68, v70
	v_log_f32_e32 v68, v68
	s_nop 0
	v_mul_f32_e32 v70, 0x3f317217, v68
	v_fma_f32 v70, v68, s97, -v70
	v_fmac_f32_e32 v70, 0x3377d1cf, v68
	v_fmac_f32_e32 v70, 0x3f317217, v68
	v_cmp_lt_f32_e64 s[14:15], |v68|, s23
	s_nop 1
	v_cndmask_b32_e64 v68, v68, v70, s[14:15]
	v_cndmask_b32_e32 v70, 0, v211, vcc
	v_sub_f32_e32 v68, v68, v70
	v_sub_f32_e32 v68, v69, v68
	v_fmac_f32_e32 v67, 0x3d800000, v68
	v_mov_b32_e32 v88, v68
	s_waitcnt lgkmcnt(0)
; DEVI float logsigf_(float x) { return fminf(x, 0.f) - __logf(1.f + __expf(-fabsf(x))); }
; DEVI float gla_la(const float* gl, int t, const float* w2r, float gb) { float x = gb;
; #pragma unroll
;     for (int r = 0; r < 16; ++r) x += gl[t * 16 + r] * w2r[r];
;     return logsigf_(x) * (1.f / 16.f); }
; template <int KIND>
; DEVI void mix_out_phase(unsigned char* smem, const MixArgs a) {
;     ...
;             for (int t = sg * 32; t < sg * 32 + 32; ++t) ssum += gla_la(gl, t, w2r, gb);
	v_fma_f32 v72, v63, v100, v66
	v_fmac_f32_e32 v72, v64, v101
	v_fmac_f32_e32 v72, v60, v102
	v_fmac_f32_e32 v72, v65, v103
	v_fmac_f32_e32 v72, v61, v104
	v_fmac_f32_e32 v72, v62, v105
	v_pk_mul_f32 v[68:69], v[34:35], v[106:107]
	s_nop 0
	v_add_f32_e32 v68, v72, v68
	v_add_f32_e32 v72, v68, v69
	v_pk_mul_f32 v[68:69], v[36:37], v[108:109]
	s_nop 0
	v_add_f32_e32 v68, v72, v68
	v_add_f32_e32 v72, v68, v69
	v_pk_mul_f32 v[68:69], v[38:39], v[110:111]
	s_nop 0
	v_add_f32_e32 v68, v72, v68
	v_add_f32_e32 v72, v68, v69
	v_pk_mul_f32 v[68:69], v[40:41], v[112:113]
	s_nop 0
	v_add_f32_e32 v68, v72, v68
	v_add_f32_e32 v72, v68, v69
	v_pk_mul_f32 v[68:69], v[58:59], v[114:115]
	s_nop 0
	v_add_f32_e32 v68, v72, v68
	v_add_f32_e32 v68, v68, v69
	v_min_f32_e32 v69, 0, v68
	v_mul_f32_e64 v68, |v68|, s73
	v_exp_f32_e32 v68, v68
	s_nop 0
	v_add_f32_e32 v68, 1.0, v68
	v_cmp_gt_f32_e32 vcc, s94, v68
	s_nop 1
	v_cndmask_b32_e64 v70, 0, 32, vcc
	v_ldexp_f32 v68, v68, v70
	v_log_f32_e32 v68, v68
	s_nop 0
	v_mul_f32_e32 v70, 0x3f317217, v68
	v_fma_f32 v70, v68, s97, -v70
	v_fmac_f32_e32 v70, 0x3377d1cf, v68
	v_fmac_f32_e32 v70, 0x3f317217, v68
	v_cmp_lt_f32_e64 s[14:15], |v68|, s23
	s_nop 1
	v_cndmask_b32_e64 v68, v68, v70, s[14:15]
	v_cndmask_b32_e32 v70, 0, v211, vcc
	v_sub_f32_e32 v68, v68, v70
	v_sub_f32_e32 v68, v69, v68
	v_fmac_f32_e32 v67, 0x3d800000, v68
	v_mov_b32_e32 v89, v68
	v_add_u32_e32 v84, s0, v195
	ds_read_b128 v[68:71], v84
	ds_read_b128 v[72:75], v84 offset:16
	ds_read_b128 v[76:79], v84 offset:32
	ds_read_b128 v[80:83], v84 offset:48
	ds_read_b128 v[100:103], v84 offset:64
	ds_read_b128 v[104:107], v84 offset:80
	ds_read_b128 v[108:111], v84 offset:96
	ds_read_b128 v[112:115], v84 offset:112
	s_addk_i32 s0, 0x80
	s_waitcnt vmcnt(1) lgkmcnt(7)
	v_fma_f32 v85, v63, v68, v66
	v_fmac_f32_e32 v85, v64, v69
	v_fmac_f32_e32 v85, v60, v70
	v_fmac_f32_e32 v85, v65, v71
	s_waitcnt lgkmcnt(6)
	v_fmac_f32_e32 v85, v61, v72
	v_fmac_f32_e32 v85, v62, v73
	v_pk_mul_f32 v[68:69], v[34:35], v[74:75]
	v_add_f32_e32 v68, v85, v68
	v_add_f32_e32 v70, v68, v69
	s_waitcnt lgkmcnt(5)
	v_pk_mul_f32 v[68:69], v[36:37], v[76:77]
	s_nop 0
	v_add_f32_e32 v68, v70, v68
	v_add_f32_e32 v70, v68, v69
	v_pk_mul_f32 v[68:69], v[38:39], v[78:79]
	s_nop 0
	v_add_f32_e32 v68, v70, v68
	v_add_f32_e32 v70, v68, v69
	s_waitcnt lgkmcnt(4)
	v_pk_mul_f32 v[68:69], v[40:41], v[80:81]
	s_nop 0
	v_add_f32_e32 v68, v70, v68
	v_add_f32_e32 v70, v68, v69
	s_waitcnt vmcnt(0)
	v_pk_mul_f32 v[68:69], v[58:59], v[82:83]
	s_nop 0
	v_add_f32_e32 v68, v70, v68
	v_add_f32_e32 v68, v68, v69
	v_min_f32_e32 v69, 0, v68
	v_mul_f32_e64 v68, |v68|, s73
	v_exp_f32_e32 v68, v68
	s_nop 0
	v_add_f32_e32 v68, 1.0, v68
	v_cmp_gt_f32_e32 vcc, s94, v68
	s_nop 1
	v_cndmask_b32_e64 v70, 0, 32, vcc
	v_ldexp_f32 v68, v68, v70
	v_log_f32_e32 v68, v68
	s_nop 0
	v_mul_f32_e32 v70, 0x3f317217, v68
	v_fma_f32 v70, v68, s97, -v70
	v_fmac_f32_e32 v70, 0x3377d1cf, v68
	v_fmac_f32_e32 v70, 0x3f317217, v68
	v_cmp_lt_f32_e64 s[14:15], |v68|, s23
	s_nop 1
	v_cndmask_b32_e64 v68, v68, v70, s[14:15]
	v_cndmask_b32_e32 v70, 0, v211, vcc
	v_sub_f32_e32 v68, v68, v70
	v_sub_f32_e32 v68, v69, v68
	v_fmac_f32_e32 v67, 0x3d800000, v68
	v_mov_b32_e32 v90, v68
	s_waitcnt lgkmcnt(0)
	v_fma_f32 v72, v63, v100, v66
	v_fmac_f32_e32 v72, v64, v101
	v_fmac_f32_e32 v72, v60, v102
	v_fmac_f32_e32 v72, v65, v103
	v_fmac_f32_e32 v72, v61, v104
	v_fmac_f32_e32 v72, v62, v105
	v_pk_mul_f32 v[68:69], v[34:35], v[106:107]
	s_nop 0
	v_add_f32_e32 v68, v72, v68
	v_add_f32_e32 v72, v68, v69
	v_pk_mul_f32 v[68:69], v[36:37], v[108:109]
	s_nop 0
	v_add_f32_e32 v68, v72, v68
	v_add_f32_e32 v72, v68, v69
	v_pk_mul_f32 v[68:69], v[38:39], v[110:111]
	s_nop 0
	v_add_f32_e32 v68, v72, v68
	v_add_f32_e32 v72, v68, v69
	v_pk_mul_f32 v[68:69], v[40:41], v[112:113]
	s_nop 0
	v_add_f32_e32 v68, v72, v68
	v_add_f32_e32 v72, v68, v69
	v_pk_mul_f32 v[68:69], v[58:59], v[114:115]
	s_nop 0
	v_add_f32_e32 v68, v72, v68
	v_add_f32_e32 v68, v68, v69
	v_min_f32_e32 v69, 0, v68
	v_mul_f32_e64 v68, |v68|, s73
	v_exp_f32_e32 v68, v68
	s_nop 0
	v_add_f32_e32 v68, 1.0, v68
	v_cmp_gt_f32_e32 vcc, s94, v68
	s_nop 1
	v_cndmask_b32_e64 v70, 0, 32, vcc
	v_ldexp_f32 v68, v68, v70
	v_log_f32_e32 v68, v68
	s_nop 0
	v_mul_f32_e32 v70, 0x3f317217, v68
	v_fma_f32 v70, v68, s97, -v70
	v_fmac_f32_e32 v70, 0x3377d1cf, v68
	v_fmac_f32_e32 v70, 0x3f317217, v68
	v_cmp_lt_f32_e64 s[14:15], |v68|, s23
	s_nop 1
	v_cndmask_b32_e64 v68, v68, v70, s[14:15]
	v_cndmask_b32_e32 v70, 0, v211, vcc
	v_sub_f32_e32 v68, v68, v70
	v_sub_f32_e32 v68, v69, v68
	v_fmac_f32_e32 v67, 0x3d800000, v68
	v_mov_b32_e32 v91, v68
	v_add_u32_e32 v84, s0, v195
	ds_read_b128 v[68:71], v84
	ds_read_b128 v[72:75], v84 offset:16
	ds_read_b128 v[76:79], v84 offset:32
	ds_read_b128 v[80:83], v84 offset:48
	ds_read_b128 v[100:103], v84 offset:64
	ds_read_b128 v[104:107], v84 offset:80
	ds_read_b128 v[108:111], v84 offset:96
	ds_read_b128 v[112:115], v84 offset:112
	s_addk_i32 s0, 0x80
	s_waitcnt vmcnt(1) lgkmcnt(7)
	v_fma_f32 v85, v63, v68, v66
	v_fmac_f32_e32 v85, v64, v69
	v_fmac_f32_e32 v85, v60, v70
	v_fmac_f32_e32 v85, v65, v71
	s_waitcnt lgkmcnt(6)
	v_fmac_f32_e32 v85, v61, v72
	v_fmac_f32_e32 v85, v62, v73
	v_pk_mul_f32 v[68:69], v[34:35], v[74:75]
	v_add_f32_e32 v68, v85, v68
	v_add_f32_e32 v70, v68, v69
	s_waitcnt lgkmcnt(5)
	v_pk_mul_f32 v[68:69], v[36:37], v[76:77]
	s_nop 0
	v_add_f32_e32 v68, v70, v68
	v_add_f32_e32 v70, v68, v69
	v_pk_mul_f32 v[68:69], v[38:39], v[78:79]
	s_nop 0
	v_add_f32_e32 v68, v70, v68
	v_add_f32_e32 v70, v68, v69
	s_waitcnt lgkmcnt(4)
; DEVI float logsigf_(float x) { return fminf(x, 0.f) - __logf(1.f + __expf(-fabsf(x))); }
; DEVI float gla_la(const float* gl, int t, const float* w2r, float gb) { float x = gb;
; #pragma unroll
;     for (int r = 0; r < 16; ++r) x += gl[t * 16 + r] * w2r[r];
;     return logsigf_(x) * (1.f / 16.f); }
; template <int KIND>
; DEVI void mix_out_phase(unsigned char* smem, const MixArgs a) {
;     ...
;             for (int t = sg * 32; t < sg * 32 + 32; ++t) ssum += gla_la(gl, t, w2r, gb);
	v_pk_mul_f32 v[68:69], v[40:41], v[80:81]
	s_nop 0
	v_add_f32_e32 v68, v70, v68
	v_add_f32_e32 v70, v68, v69
	s_waitcnt vmcnt(0)
	v_pk_mul_f32 v[68:69], v[58:59], v[82:83]
	s_nop 0
	v_add_f32_e32 v68, v70, v68
	v_add_f32_e32 v68, v68, v69
	v_min_f32_e32 v69, 0, v68
	v_mul_f32_e64 v68, |v68|, s73
	v_exp_f32_e32 v68, v68
	s_nop 0
	v_add_f32_e32 v68, 1.0, v68
	v_cmp_gt_f32_e32 vcc, s94, v68
	s_nop 1
	v_cndmask_b32_e64 v70, 0, 32, vcc
	v_ldexp_f32 v68, v68, v70
	v_log_f32_e32 v68, v68
	s_nop 0
	v_mul_f32_e32 v70, 0x3f317217, v68
	v_fma_f32 v70, v68, s97, -v70
	v_fmac_f32_e32 v70, 0x3377d1cf, v68
	v_fmac_f32_e32 v70, 0x3f317217, v68
	v_cmp_lt_f32_e64 s[14:15], |v68|, s23
	s_nop 1
	v_cndmask_b32_e64 v68, v68, v70, s[14:15]
	v_cndmask_b32_e32 v70, 0, v211, vcc
	v_sub_f32_e32 v68, v68, v70
	v_sub_f32_e32 v68, v69, v68
	v_fmac_f32_e32 v67, 0x3d800000, v68
	v_mov_b32_e32 v92, v68
	s_waitcnt lgkmcnt(0)
	v_fma_f32 v72, v63, v100, v66
	v_fmac_f32_e32 v72, v64, v101
	v_fmac_f32_e32 v72, v60, v102
	v_fmac_f32_e32 v72, v65, v103
	v_fmac_f32_e32 v72, v61, v104
	v_fmac_f32_e32 v72, v62, v105
	v_pk_mul_f32 v[68:69], v[34:35], v[106:107]
	s_nop 0
	v_add_f32_e32 v68, v72, v68
	v_add_f32_e32 v72, v68, v69
	v_pk_mul_f32 v[68:69], v[36:37], v[108:109]
	s_nop 0
	v_add_f32_e32 v68, v72, v68
	v_add_f32_e32 v72, v68, v69
	v_pk_mul_f32 v[68:69], v[38:39], v[110:111]
	s_nop 0
	v_add_f32_e32 v68, v72, v68
	v_add_f32_e32 v72, v68, v69
	v_pk_mul_f32 v[68:69], v[40:41], v[112:113]
	s_nop 0
	v_add_f32_e32 v68, v72, v68
	v_add_f32_e32 v72, v68, v69
	v_pk_mul_f32 v[68:69], v[58:59], v[114:115]
	s_nop 0
	v_add_f32_e32 v68, v72, v68
	v_add_f32_e32 v68, v68, v69
	v_min_f32_e32 v69, 0, v68
	v_mul_f32_e64 v68, |v68|, s73
	v_exp_f32_e32 v68, v68
	s_nop 0
	v_add_f32_e32 v68, 1.0, v68
	v_cmp_gt_f32_e32 vcc, s94, v68
	s_nop 1
	v_cndmask_b32_e64 v70, 0, 32, vcc
	v_ldexp_f32 v68, v68, v70
	v_log_f32_e32 v68, v68
	s_nop 0
	v_mul_f32_e32 v70, 0x3f317217, v68
	v_fma_f32 v70, v68, s97, -v70
	v_fmac_f32_e32 v70, 0x3377d1cf, v68
	v_fmac_f32_e32 v70, 0x3f317217, v68
	v_cmp_lt_f32_e64 s[14:15], |v68|, s23
	s_nop 1
	v_cndmask_b32_e64 v68, v68, v70, s[14:15]
	v_cndmask_b32_e32 v70, 0, v211, vcc
	v_sub_f32_e32 v68, v68, v70
	v_sub_f32_e32 v68, v69, v68
	v_fmac_f32_e32 v67, 0x3d800000, v68
	v_mov_b32_e32 v93, v68
	v_add_u32_e32 v84, s0, v195
	ds_read_b128 v[68:71], v84
	ds_read_b128 v[72:75], v84 offset:16
	ds_read_b128 v[76:79], v84 offset:32
	ds_read_b128 v[80:83], v84 offset:48
	ds_read_b128 v[100:103], v84 offset:64
	ds_read_b128 v[104:107], v84 offset:80
	ds_read_b128 v[108:111], v84 offset:96
	ds_read_b128 v[112:115], v84 offset:112
	s_addk_i32 s0, 0x80
	s_waitcnt vmcnt(1) lgkmcnt(7)
	v_fma_f32 v85, v63, v68, v66
	v_fmac_f32_e32 v85, v64, v69
	v_fmac_f32_e32 v85, v60, v70
	v_fmac_f32_e32 v85, v65, v71
	s_waitcnt lgkmcnt(6)
	v_fmac_f32_e32 v85, v61, v72
	v_fmac_f32_e32 v85, v62, v73
	v_pk_mul_f32 v[68:69], v[34:35], v[74:75]
	v_add_f32_e32 v68, v85, v68
	v_add_f32_e32 v70, v68, v69
	s_waitcnt lgkmcnt(5)
	v_pk_mul_f32 v[68:69], v[36:37], v[76:77]
	s_nop 0
	v_add_f32_e32 v68, v70, v68
	v_add_f32_e32 v70, v68, v69
	v_pk_mul_f32 v[68:69], v[38:39], v[78:79]
	s_nop 0
	v_add_f32_e32 v68, v70, v68
	v_add_f32_e32 v70, v68, v69
	s_waitcnt lgkmcnt(4)
	v_pk_mul_f32 v[68:69], v[40:41], v[80:81]
	s_nop 0
	v_add_f32_e32 v68, v70, v68
	v_add_f32_e32 v70, v68, v69
	s_waitcnt vmcnt(0)
	v_pk_mul_f32 v[68:69], v[58:59], v[82:83]
	s_nop 0
	v_add_f32_e32 v68, v70, v68
	v_add_f32_e32 v68, v68, v69
	v_min_f32_e32 v69, 0, v68
	v_mul_f32_e64 v68, |v68|, s73
	v_exp_f32_e32 v68, v68
	s_nop 0
	v_add_f32_e32 v68, 1.0, v68
	v_cmp_gt_f32_e32 vcc, s94, v68
	s_nop 1
	v_cndmask_b32_e64 v70, 0, 32, vcc
	v_ldexp_f32 v68, v68, v70
	v_log_f32_e32 v68, v68
	s_nop 0
	v_mul_f32_e32 v70, 0x3f317217, v68
	v_fma_f32 v70, v68, s97, -v70
	v_fmac_f32_e32 v70, 0x3377d1cf, v68
	v_fmac_f32_e32 v70, 0x3f317217, v68
	v_cmp_lt_f32_e64 s[14:15], |v68|, s23
	s_nop 1
	v_cndmask_b32_e64 v68, v68, v70, s[14:15]
	v_cndmask_b32_e32 v70, 0, v211, vcc
	v_sub_f32_e32 v68, v68, v70
	v_sub_f32_e32 v68, v69, v68
	v_fmac_f32_e32 v67, 0x3d800000, v68
	v_mov_b32_e32 v94, v68
	s_waitcnt lgkmcnt(0)
	v_fma_f32 v72, v63, v100, v66
	v_fmac_f32_e32 v72, v64, v101
	v_fmac_f32_e32 v72, v60, v102
	v_fmac_f32_e32 v72, v65, v103
	v_fmac_f32_e32 v72, v61, v104
	v_fmac_f32_e32 v72, v62, v105
	v_pk_mul_f32 v[68:69], v[34:35], v[106:107]
	s_nop 0
	v_add_f32_e32 v68, v72, v68
	v_add_f32_e32 v72, v68, v69
	v_pk_mul_f32 v[68:69], v[36:37], v[108:109]
	s_nop 0
	v_add_f32_e32 v68, v72, v68
	v_add_f32_e32 v72, v68, v69
	v_pk_mul_f32 v[68:69], v[38:39], v[110:111]
	s_nop 0
	v_add_f32_e32 v68, v72, v68
	v_add_f32_e32 v72, v68, v69
	v_pk_mul_f32 v[68:69], v[40:41], v[112:113]
	s_nop 0
	v_add_f32_e32 v68, v72, v68
	v_add_f32_e32 v72, v68, v69
	v_pk_mul_f32 v[68:69], v[58:59], v[114:115]
	s_nop 0
	v_add_f32_e32 v68, v72, v68
	v_add_f32_e32 v68, v68, v69
	v_min_f32_e32 v69, 0, v68
	v_mul_f32_e64 v68, |v68|, s73
	v_exp_f32_e32 v68, v68
	s_nop 0
	v_add_f32_e32 v68, 1.0, v68
	v_cmp_gt_f32_e32 vcc, s94, v68
	s_nop 1
	v_cndmask_b32_e64 v70, 0, 32, vcc
	v_ldexp_f32 v68, v68, v70
	v_log_f32_e32 v68, v68
	s_nop 0
	v_mul_f32_e32 v70, 0x3f317217, v68
	v_fma_f32 v70, v68, s97, -v70
	v_fmac_f32_e32 v70, 0x3377d1cf, v68
	v_fmac_f32_e32 v70, 0x3f317217, v68
	v_cmp_lt_f32_e64 s[14:15], |v68|, s23
	s_nop 1
	v_cndmask_b32_e64 v68, v68, v70, s[14:15]
	v_cndmask_b32_e32 v70, 0, v211, vcc
	v_sub_f32_e32 v68, v68, v70
	v_sub_f32_e32 v68, v69, v68
	v_fmac_f32_e32 v67, 0x3d800000, v68
	v_mov_b32_e32 v95, v68
	v_add_u32_e32 v84, s0, v195
	ds_read_b128 v[68:71], v84
	ds_read_b128 v[72:75], v84 offset:16
	ds_read_b128 v[76:79], v84 offset:32
	ds_read_b128 v[80:83], v84 offset:48
	ds_read_b128 v[100:103], v84 offset:64
	ds_read_b128 v[104:107], v84 offset:80
	ds_read_b128 v[108:111], v84 offset:96
	ds_read_b128 v[112:115], v84 offset:112
	s_addk_i32 s0, 0x80
	s_waitcnt vmcnt(1) lgkmcnt(7)
; DEVI float logsigf_(float x) { return fminf(x, 0.f) - __logf(1.f + __expf(-fabsf(x))); }
; DEVI float gla_la(const float* gl, int t, const float* w2r, float gb) { float x = gb;
; #pragma unroll
;     for (int r = 0; r < 16; ++r) x += gl[t * 16 + r] * w2r[r];
;     return logsigf_(x) * (1.f / 16.f); }
; template <int KIND>
; DEVI void mix_out_phase(unsigned char* smem, const MixArgs a) {
;     ...
;             for (int t = sg * 32; t < sg * 32 + 32; ++t) ssum += gla_la(gl, t, w2r, gb);
	v_fma_f32 v85, v63, v68, v66
	v_fmac_f32_e32 v85, v64, v69
	v_fmac_f32_e32 v85, v60, v70
	v_fmac_f32_e32 v85, v65, v71
	s_waitcnt lgkmcnt(6)
	v_fmac_f32_e32 v85, v61, v72
	v_fmac_f32_e32 v85, v62, v73
	v_pk_mul_f32 v[68:69], v[34:35], v[74:75]
	v_add_f32_e32 v68, v85, v68
	v_add_f32_e32 v70, v68, v69
	s_waitcnt lgkmcnt(5)
	v_pk_mul_f32 v[68:69], v[36:37], v[76:77]
	s_nop 0
	v_add_f32_e32 v68, v70, v68
	v_add_f32_e32 v70, v68, v69
	v_pk_mul_f32 v[68:69], v[38:39], v[78:79]
	s_nop 0
	v_add_f32_e32 v68, v70, v68
	v_add_f32_e32 v70, v68, v69
	s_waitcnt lgkmcnt(4)
	v_pk_mul_f32 v[68:69], v[40:41], v[80:81]
	s_nop 0
	v_add_f32_e32 v68, v70, v68
	v_add_f32_e32 v70, v68, v69
	s_waitcnt vmcnt(0)
	v_pk_mul_f32 v[68:69], v[58:59], v[82:83]
	s_nop 0
	v_add_f32_e32 v68, v70, v68
	v_add_f32_e32 v68, v68, v69
	v_min_f32_e32 v69, 0, v68
	v_mul_f32_e64 v68, |v68|, s73
	v_exp_f32_e32 v68, v68
	s_nop 0
	v_add_f32_e32 v68, 1.0, v68
	v_cmp_gt_f32_e32 vcc, s94, v68
	s_nop 1
	v_cndmask_b32_e64 v70, 0, 32, vcc
	v_ldexp_f32 v68, v68, v70
	v_log_f32_e32 v68, v68
	s_nop 0
	v_mul_f32_e32 v70, 0x3f317217, v68
	v_fma_f32 v70, v68, s97, -v70
	v_fmac_f32_e32 v70, 0x3377d1cf, v68
	v_fmac_f32_e32 v70, 0x3f317217, v68
	v_cmp_lt_f32_e64 s[14:15], |v68|, s23
	s_nop 1
	v_cndmask_b32_e64 v68, v68, v70, s[14:15]
	v_cndmask_b32_e32 v70, 0, v211, vcc
	v_sub_f32_e32 v68, v68, v70
	v_sub_f32_e32 v68, v69, v68
	v_fmac_f32_e32 v67, 0x3d800000, v68
	v_mov_b32_e32 v96, v68
	s_waitcnt lgkmcnt(0)
	v_fma_f32 v72, v63, v100, v66
	v_fmac_f32_e32 v72, v64, v101
	v_fmac_f32_e32 v72, v60, v102
	v_fmac_f32_e32 v72, v65, v103
	v_fmac_f32_e32 v72, v61, v104
	v_fmac_f32_e32 v72, v62, v105
	v_pk_mul_f32 v[68:69], v[34:35], v[106:107]
	s_nop 0
	v_add_f32_e32 v68, v72, v68
	v_add_f32_e32 v72, v68, v69
	v_pk_mul_f32 v[68:69], v[36:37], v[108:109]
	s_nop 0
	v_add_f32_e32 v68, v72, v68
	v_add_f32_e32 v72, v68, v69
	v_pk_mul_f32 v[68:69], v[38:39], v[110:111]
	s_nop 0
	v_add_f32_e32 v68, v72, v68
	v_add_f32_e32 v72, v68, v69
	v_pk_mul_f32 v[68:69], v[40:41], v[112:113]
	s_nop 0
	v_add_f32_e32 v68, v72, v68
	v_add_f32_e32 v72, v68, v69
	v_pk_mul_f32 v[68:69], v[58:59], v[114:115]
	s_nop 0
	v_add_f32_e32 v68, v72, v68
	v_add_f32_e32 v68, v68, v69
	v_min_f32_e32 v69, 0, v68
	v_mul_f32_e64 v68, |v68|, s73
	v_exp_f32_e32 v68, v68
	s_nop 0
	v_add_f32_e32 v68, 1.0, v68
	v_cmp_gt_f32_e32 vcc, s94, v68
	s_nop 1
	v_cndmask_b32_e64 v70, 0, 32, vcc
	v_ldexp_f32 v68, v68, v70
	v_log_f32_e32 v68, v68
	s_nop 0
	v_mul_f32_e32 v70, 0x3f317217, v68
	v_fma_f32 v70, v68, s97, -v70
	v_fmac_f32_e32 v70, 0x3377d1cf, v68
	v_fmac_f32_e32 v70, 0x3f317217, v68
	v_cmp_lt_f32_e64 s[14:15], |v68|, s23
	s_nop 1
	v_cndmask_b32_e64 v68, v68, v70, s[14:15]
	v_cndmask_b32_e32 v70, 0, v211, vcc
	v_sub_f32_e32 v68, v68, v70
	v_sub_f32_e32 v68, v69, v68
	v_fmac_f32_e32 v67, 0x3d800000, v68
	v_mov_b32_e32 v97, v68
	v_add_u32_e32 v84, s0, v195
	ds_read_b128 v[68:71], v84
	ds_read_b128 v[72:75], v84 offset:16
	ds_read_b128 v[76:79], v84 offset:32
	ds_read_b128 v[80:83], v84 offset:48
	ds_read_b128 v[100:103], v84 offset:64
	ds_read_b128 v[104:107], v84 offset:80
	ds_read_b128 v[108:111], v84 offset:96
	ds_read_b128 v[112:115], v84 offset:112
	s_addk_i32 s0, 0x80
	s_waitcnt vmcnt(1) lgkmcnt(7)
	v_fma_f32 v85, v63, v68, v66
	v_fmac_f32_e32 v85, v64, v69
	v_fmac_f32_e32 v85, v60, v70
	v_fmac_f32_e32 v85, v65, v71
	s_waitcnt lgkmcnt(6)
	v_fmac_f32_e32 v85, v61, v72
	v_fmac_f32_e32 v85, v62, v73
	v_pk_mul_f32 v[68:69], v[34:35], v[74:75]
	v_add_f32_e32 v68, v85, v68
	v_add_f32_e32 v70, v68, v69
	s_waitcnt lgkmcnt(5)
	v_pk_mul_f32 v[68:69], v[36:37], v[76:77]
	s_nop 0
	v_add_f32_e32 v68, v70, v68
	v_add_f32_e32 v70, v68, v69
	v_pk_mul_f32 v[68:69], v[38:39], v[78:79]
	s_nop 0
	v_add_f32_e32 v68, v70, v68
	v_add_f32_e32 v70, v68, v69
	s_waitcnt lgkmcnt(4)
	v_pk_mul_f32 v[68:69], v[40:41], v[80:81]
	s_nop 0
	v_add_f32_e32 v68, v70, v68
	v_add_f32_e32 v70, v68, v69
	s_waitcnt vmcnt(0)
	v_pk_mul_f32 v[68:69], v[58:59], v[82:83]
	s_nop 0
	v_add_f32_e32 v68, v70, v68
	v_add_f32_e32 v68, v68, v69
	v_min_f32_e32 v69, 0, v68
	v_mul_f32_e64 v68, |v68|, s73
	v_exp_f32_e32 v68, v68
	s_nop 0
	v_add_f32_e32 v68, 1.0, v68
	v_cmp_gt_f32_e32 vcc, s94, v68
	s_nop 1
	v_cndmask_b32_e64 v70, 0, 32, vcc
	v_ldexp_f32 v68, v68, v70
	v_log_f32_e32 v68, v68
	s_nop 0
	v_mul_f32_e32 v70, 0x3f317217, v68
	v_fma_f32 v70, v68, s97, -v70
	v_fmac_f32_e32 v70, 0x3377d1cf, v68
	v_fmac_f32_e32 v70, 0x3f317217, v68
	v_cmp_lt_f32_e64 s[14:15], |v68|, s23
	s_nop 1
	v_cndmask_b32_e64 v68, v68, v70, s[14:15]
	v_cndmask_b32_e32 v70, 0, v211, vcc
	v_sub_f32_e32 v68, v68, v70
	v_sub_f32_e32 v68, v69, v68
	v_fmac_f32_e32 v67, 0x3d800000, v68
	v_mov_b32_e32 v98, v68
	s_waitcnt lgkmcnt(0)
	v_fma_f32 v72, v63, v100, v66
	v_fmac_f32_e32 v72, v64, v101
	v_fmac_f32_e32 v72, v60, v102
	v_fmac_f32_e32 v72, v65, v103
	v_fmac_f32_e32 v72, v61, v104
	v_fmac_f32_e32 v72, v62, v105
	v_pk_mul_f32 v[68:69], v[34:35], v[106:107]
	s_nop 0
	v_add_f32_e32 v68, v72, v68
	v_add_f32_e32 v72, v68, v69
	v_pk_mul_f32 v[68:69], v[36:37], v[108:109]
	s_nop 0
	v_add_f32_e32 v68, v72, v68
	v_add_f32_e32 v72, v68, v69
	v_pk_mul_f32 v[68:69], v[38:39], v[110:111]
	s_nop 0
	v_add_f32_e32 v68, v72, v68
	v_add_f32_e32 v72, v68, v69
	v_pk_mul_f32 v[68:69], v[40:41], v[112:113]
	s_nop 0
	v_add_f32_e32 v68, v72, v68
	v_add_f32_e32 v72, v68, v69
	v_pk_mul_f32 v[68:69], v[58:59], v[114:115]
	s_nop 0
	v_add_f32_e32 v68, v72, v68
	v_add_f32_e32 v68, v68, v69
	v_min_f32_e32 v69, 0, v68
	v_mul_f32_e64 v68, |v68|, s73
	v_exp_f32_e32 v68, v68
	s_nop 0
	v_add_f32_e32 v68, 1.0, v68
	v_cmp_gt_f32_e32 vcc, s94, v68
	s_nop 1
	v_cndmask_b32_e64 v70, 0, 32, vcc
	v_ldexp_f32 v68, v68, v70
	v_log_f32_e32 v68, v68
	s_nop 0
	v_mul_f32_e32 v70, 0x3f317217, v68
	v_fma_f32 v70, v68, s97, -v70
	v_fmac_f32_e32 v70, 0x3377d1cf, v68
	v_fmac_f32_e32 v70, 0x3f317217, v68
	v_cmp_lt_f32_e64 s[14:15], |v68|, s23
	s_nop 1
	v_cndmask_b32_e64 v68, v68, v70, s[14:15]
	v_cndmask_b32_e32 v70, 0, v211, vcc
	v_sub_f32_e32 v68, v68, v70
	v_sub_f32_e32 v68, v69, v68
	v_fmac_f32_e32 v67, 0x3d800000, v68
	v_mov_b32_e32 v99, v68
	v_add_u32_e32 v84, s0, v195
	ds_read_b128 v[68:71], v84
	ds_read_b128 v[72:75], v84 offset:16
	ds_read_b128 v[76:79], v84 offset:32
	ds_read_b128 v[80:83], v84 offset:48
	ds_read_b128 v[100:103], v84 offset:64
	ds_read_b128 v[104:107], v84 offset:80
	ds_read_b128 v[108:111], v84 offset:96
	ds_read_b128 v[112:115], v84 offset:112
	s_addk_i32 s0, 0x80
	s_waitcnt vmcnt(1) lgkmcnt(7)
; DEVI float logsigf_(float x) { return fminf(x, 0.f) - __logf(1.f + __expf(-fabsf(x))); }
; DEVI float gla_la(const float* gl, int t, const float* w2r, float gb) { float x = gb;
; #pragma unroll
;     for (int r = 0; r < 16; ++r) x += gl[t * 16 + r] * w2r[r];
;     return logsigf_(x) * (1.f / 16.f); }
; template <int KIND>
; DEVI void mix_out_phase(unsigned char* smem, const MixArgs a) {
;     ...
;             for (int t = sg * 32; t < sg * 32 + 32; ++t) ssum += gla_la(gl, t, w2r, gb);
	v_fma_f32 v85, v63, v68, v66
	v_fmac_f32_e32 v85, v64, v69
	v_fmac_f32_e32 v85, v60, v70
	v_fmac_f32_e32 v85, v65, v71
	s_waitcnt lgkmcnt(6)
	v_fmac_f32_e32 v85, v61, v72
	v_fmac_f32_e32 v85, v62, v73
	v_pk_mul_f32 v[68:69], v[34:35], v[74:75]
	v_add_f32_e32 v68, v85, v68
	v_add_f32_e32 v70, v68, v69
	s_waitcnt lgkmcnt(5)
	v_pk_mul_f32 v[68:69], v[36:37], v[76:77]
	s_nop 0
	v_add_f32_e32 v68, v70, v68
	v_add_f32_e32 v70, v68, v69
	v_pk_mul_f32 v[68:69], v[38:39], v[78:79]
	s_nop 0
	v_add_f32_e32 v68, v70, v68
	v_add_f32_e32 v70, v68, v69
	s_waitcnt lgkmcnt(4)
	v_pk_mul_f32 v[68:69], v[40:41], v[80:81]
	s_nop 0
	v_add_f32_e32 v68, v70, v68
	v_add_f32_e32 v70, v68, v69
	s_waitcnt vmcnt(0)
	v_pk_mul_f32 v[68:69], v[58:59], v[82:83]
	s_nop 0
	v_add_f32_e32 v68, v70, v68
	v_add_f32_e32 v68, v68, v69
	v_min_f32_e32 v69, 0, v68
	v_mul_f32_e64 v68, |v68|, s73
	v_exp_f32_e32 v68, v68
	s_nop 0
	v_add_f32_e32 v68, 1.0, v68
	v_cmp_gt_f32_e32 vcc, s94, v68
	s_nop 1
	v_cndmask_b32_e64 v70, 0, 32, vcc
	v_ldexp_f32 v68, v68, v70
	v_log_f32_e32 v68, v68
	s_nop 0
	v_mul_f32_e32 v70, 0x3f317217, v68
	v_fma_f32 v70, v68, s97, -v70
	v_fmac_f32_e32 v70, 0x3377d1cf, v68
	v_fmac_f32_e32 v70, 0x3f317217, v68
	v_cmp_lt_f32_e64 s[14:15], |v68|, s23
	s_nop 1
	v_cndmask_b32_e64 v68, v68, v70, s[14:15]
	v_cndmask_b32_e32 v70, 0, v211, vcc
	v_sub_f32_e32 v68, v68, v70
	v_sub_f32_e32 v68, v69, v68
	v_fmac_f32_e32 v67, 0x3d800000, v68
	v_mov_b32_e32 v116, v68
	s_waitcnt lgkmcnt(0)
	v_fma_f32 v72, v63, v100, v66
	v_fmac_f32_e32 v72, v64, v101
	v_fmac_f32_e32 v72, v60, v102
	v_fmac_f32_e32 v72, v65, v103
	v_fmac_f32_e32 v72, v61, v104
	v_fmac_f32_e32 v72, v62, v105
	v_pk_mul_f32 v[68:69], v[34:35], v[106:107]
	s_nop 0
	v_add_f32_e32 v68, v72, v68
	v_add_f32_e32 v72, v68, v69
	v_pk_mul_f32 v[68:69], v[36:37], v[108:109]
	s_nop 0
	v_add_f32_e32 v68, v72, v68
	v_add_f32_e32 v72, v68, v69
	v_pk_mul_f32 v[68:69], v[38:39], v[110:111]
	s_nop 0
	v_add_f32_e32 v68, v72, v68
	v_add_f32_e32 v72, v68, v69
	v_pk_mul_f32 v[68:69], v[40:41], v[112:113]
	s_nop 0
	v_add_f32_e32 v68, v72, v68
	v_add_f32_e32 v72, v68, v69
	v_pk_mul_f32 v[68:69], v[58:59], v[114:115]
	s_nop 0
	v_add_f32_e32 v68, v72, v68
	v_add_f32_e32 v68, v68, v69
	v_min_f32_e32 v69, 0, v68
	v_mul_f32_e64 v68, |v68|, s73
	v_exp_f32_e32 v68, v68
	s_nop 0
	v_add_f32_e32 v68, 1.0, v68
	v_cmp_gt_f32_e32 vcc, s94, v68
	s_nop 1
	v_cndmask_b32_e64 v70, 0, 32, vcc
	v_ldexp_f32 v68, v68, v70
	v_log_f32_e32 v68, v68
	s_nop 0
	v_mul_f32_e32 v70, 0x3f317217, v68
	v_fma_f32 v70, v68, s97, -v70
	v_fmac_f32_e32 v70, 0x3377d1cf, v68
	v_fmac_f32_e32 v70, 0x3f317217, v68
	v_cmp_lt_f32_e64 s[14:15], |v68|, s23
	s_nop 1
	v_cndmask_b32_e64 v68, v68, v70, s[14:15]
	v_cndmask_b32_e32 v70, 0, v211, vcc
	v_sub_f32_e32 v68, v68, v70
	v_sub_f32_e32 v68, v69, v68
	v_fmac_f32_e32 v67, 0x3d800000, v68
	v_mov_b32_e32 v117, v68
	v_add_u32_e32 v84, s0, v195
	ds_read_b128 v[68:71], v84
	ds_read_b128 v[72:75], v84 offset:16
	ds_read_b128 v[76:79], v84 offset:32
	ds_read_b128 v[80:83], v84 offset:48
	ds_read_b128 v[100:103], v84 offset:64
	ds_read_b128 v[104:107], v84 offset:80
	ds_read_b128 v[108:111], v84 offset:96
	ds_read_b128 v[112:115], v84 offset:112
	s_addk_i32 s0, 0x80
	s_waitcnt vmcnt(1) lgkmcnt(7)
	v_fma_f32 v85, v63, v68, v66
	v_fmac_f32_e32 v85, v64, v69
	v_fmac_f32_e32 v85, v60, v70
	v_fmac_f32_e32 v85, v65, v71
	s_waitcnt lgkmcnt(6)
	v_fmac_f32_e32 v85, v61, v72
	v_fmac_f32_e32 v85, v62, v73
	v_pk_mul_f32 v[68:69], v[34:35], v[74:75]
	v_add_f32_e32 v68, v85, v68
	v_add_f32_e32 v70, v68, v69
	s_waitcnt lgkmcnt(5)
	v_pk_mul_f32 v[68:69], v[36:37], v[76:77]
	s_nop 0
	v_add_f32_e32 v68, v70, v68
	v_add_f32_e32 v70, v68, v69
	v_pk_mul_f32 v[68:69], v[38:39], v[78:79]
	s_nop 0
	v_add_f32_e32 v68, v70, v68
	v_add_f32_e32 v70, v68, v69
	s_waitcnt lgkmcnt(4)
	v_pk_mul_f32 v[68:69], v[40:41], v[80:81]
	s_nop 0
	v_add_f32_e32 v68, v70, v68
	v_add_f32_e32 v70, v68, v69
	s_waitcnt vmcnt(0)
	v_pk_mul_f32 v[68:69], v[58:59], v[82:83]
	s_nop 0
	v_add_f32_e32 v68, v70, v68
	v_add_f32_e32 v68, v68, v69
	v_min_f32_e32 v69, 0, v68
	v_mul_f32_e64 v68, |v68|, s73
	v_exp_f32_e32 v68, v68
	s_nop 0
	v_add_f32_e32 v68, 1.0, v68
	v_cmp_gt_f32_e32 vcc, s94, v68
	s_nop 1
	v_cndmask_b32_e64 v70, 0, 32, vcc
	v_ldexp_f32 v68, v68, v70
	v_log_f32_e32 v68, v68
	s_nop 0
	v_mul_f32_e32 v70, 0x3f317217, v68
	v_fma_f32 v70, v68, s97, -v70
	v_fmac_f32_e32 v70, 0x3377d1cf, v68
	v_fmac_f32_e32 v70, 0x3f317217, v68
	v_cmp_lt_f32_e64 s[14:15], |v68|, s23
	s_nop 1
	v_cndmask_b32_e64 v68, v68, v70, s[14:15]
	v_cndmask_b32_e32 v70, 0, v211, vcc
	v_sub_f32_e32 v68, v68, v70
	v_sub_f32_e32 v68, v69, v68
	v_fmac_f32_e32 v67, 0x3d800000, v68
	v_mov_b32_e32 v118, v68
	s_waitcnt lgkmcnt(0)
	v_fma_f32 v72, v63, v100, v66
	v_fmac_f32_e32 v72, v64, v101
	v_fmac_f32_e32 v72, v60, v102
	v_fmac_f32_e32 v72, v65, v103
	v_fmac_f32_e32 v72, v61, v104
	v_fmac_f32_e32 v72, v62, v105
	v_pk_mul_f32 v[68:69], v[34:35], v[106:107]
	s_nop 0
	v_add_f32_e32 v68, v72, v68
	v_add_f32_e32 v72, v68, v69
	v_pk_mul_f32 v[68:69], v[36:37], v[108:109]
	s_nop 0
	v_add_f32_e32 v68, v72, v68
	v_add_f32_e32 v72, v68, v69
	v_pk_mul_f32 v[68:69], v[38:39], v[110:111]
	s_nop 0
	v_add_f32_e32 v68, v72, v68
	v_add_f32_e32 v72, v68, v69
	v_pk_mul_f32 v[68:69], v[40:41], v[112:113]
	s_nop 0
	v_add_f32_e32 v68, v72, v68
	v_add_f32_e32 v72, v68, v69
	v_pk_mul_f32 v[68:69], v[58:59], v[114:115]
	s_nop 0
	v_add_f32_e32 v68, v72, v68
	v_add_f32_e32 v68, v68, v69
	v_min_f32_e32 v69, 0, v68
	v_mul_f32_e64 v68, |v68|, s73
	v_exp_f32_e32 v68, v68
	s_nop 0
	v_add_f32_e32 v68, 1.0, v68
	v_cmp_gt_f32_e32 vcc, s94, v68
	s_nop 1
	v_cndmask_b32_e64 v70, 0, 32, vcc
	v_ldexp_f32 v68, v68, v70
	v_log_f32_e32 v68, v68
	s_nop 0
	v_mul_f32_e32 v70, 0x3f317217, v68
	v_fma_f32 v70, v68, s97, -v70
	v_fmac_f32_e32 v70, 0x3377d1cf, v68
	v_fmac_f32_e32 v70, 0x3f317217, v68
	v_cmp_lt_f32_e64 s[14:15], |v68|, s23
	s_nop 1
	v_cndmask_b32_e64 v68, v68, v70, s[14:15]
	v_cndmask_b32_e32 v70, 0, v211, vcc
	v_sub_f32_e32 v68, v68, v70
	v_sub_f32_e32 v68, v69, v68
	v_fmac_f32_e32 v67, 0x3d800000, v68
	v_mov_b32_e32 v119, v68
	v_add_u32_e32 v84, s0, v195
	ds_read_b128 v[68:71], v84
	ds_read_b128 v[72:75], v84 offset:16
	ds_read_b128 v[76:79], v84 offset:32
	ds_read_b128 v[80:83], v84 offset:48
	ds_read_b128 v[100:103], v84 offset:64
	ds_read_b128 v[104:107], v84 offset:80
	ds_read_b128 v[108:111], v84 offset:96
	ds_read_b128 v[112:115], v84 offset:112
	s_addk_i32 s0, 0x80
	s_waitcnt vmcnt(1) lgkmcnt(7)
; DEVI float logsigf_(float x) { return fminf(x, 0.f) - __logf(1.f + __expf(-fabsf(x))); }
; DEVI float gla_la(const float* gl, int t, const float* w2r, float gb) { float x = gb;
; #pragma unroll
;     for (int r = 0; r < 16; ++r) x += gl[t * 16 + r] * w2r[r];
;     return logsigf_(x) * (1.f / 16.f); }
; template <int KIND>
; DEVI void mix_out_phase(unsigned char* smem, const MixArgs a) {
;     ...
;             for (int t = sg * 32; t < sg * 32 + 32; ++t) ssum += gla_la(gl, t, w2r, gb);
	v_fma_f32 v85, v63, v68, v66
	v_fmac_f32_e32 v85, v64, v69
	v_fmac_f32_e32 v85, v60, v70
	v_fmac_f32_e32 v85, v65, v71
	s_waitcnt lgkmcnt(6)
	v_fmac_f32_e32 v85, v61, v72
	v_fmac_f32_e32 v85, v62, v73
	v_pk_mul_f32 v[68:69], v[34:35], v[74:75]
	v_add_f32_e32 v68, v85, v68
	v_add_f32_e32 v70, v68, v69
	s_waitcnt lgkmcnt(5)
	v_pk_mul_f32 v[68:69], v[36:37], v[76:77]
	s_nop 0
	v_add_f32_e32 v68, v70, v68
	v_add_f32_e32 v70, v68, v69
	v_pk_mul_f32 v[68:69], v[38:39], v[78:79]
	s_nop 0
	v_add_f32_e32 v68, v70, v68
	v_add_f32_e32 v70, v68, v69
	s_waitcnt lgkmcnt(4)
	v_pk_mul_f32 v[68:69], v[40:41], v[80:81]
	s_nop 0
	v_add_f32_e32 v68, v70, v68
	v_add_f32_e32 v70, v68, v69
	s_waitcnt vmcnt(0)
	v_pk_mul_f32 v[68:69], v[58:59], v[82:83]
	s_nop 0
	v_add_f32_e32 v68, v70, v68
	v_add_f32_e32 v68, v68, v69
	v_min_f32_e32 v69, 0, v68
	v_mul_f32_e64 v68, |v68|, s73
	v_exp_f32_e32 v68, v68
	s_nop 0
	v_add_f32_e32 v68, 1.0, v68
	v_cmp_gt_f32_e32 vcc, s94, v68
	s_nop 1
	v_cndmask_b32_e64 v70, 0, 32, vcc
	v_ldexp_f32 v68, v68, v70
	v_log_f32_e32 v68, v68
	s_nop 0
	v_mul_f32_e32 v70, 0x3f317217, v68
	v_fma_f32 v70, v68, s97, -v70
	v_fmac_f32_e32 v70, 0x3377d1cf, v68
	v_fmac_f32_e32 v70, 0x3f317217, v68
	v_cmp_lt_f32_e64 s[14:15], |v68|, s23
	s_nop 1
	v_cndmask_b32_e64 v68, v68, v70, s[14:15]
	v_cndmask_b32_e32 v70, 0, v211, vcc
	v_sub_f32_e32 v68, v68, v70
	v_sub_f32_e32 v68, v69, v68
	v_fmac_f32_e32 v67, 0x3d800000, v68
	v_mov_b32_e32 v120, v68
	s_waitcnt lgkmcnt(0)
	v_fma_f32 v72, v63, v100, v66
	v_fmac_f32_e32 v72, v64, v101
	v_fmac_f32_e32 v72, v60, v102
	v_fmac_f32_e32 v72, v65, v103
	v_fmac_f32_e32 v72, v61, v104
	v_fmac_f32_e32 v72, v62, v105
	v_pk_mul_f32 v[68:69], v[34:35], v[106:107]
	s_nop 0
	v_add_f32_e32 v68, v72, v68
	v_add_f32_e32 v72, v68, v69
	v_pk_mul_f32 v[68:69], v[36:37], v[108:109]
	s_nop 0
	v_add_f32_e32 v68, v72, v68
	v_add_f32_e32 v72, v68, v69
	v_pk_mul_f32 v[68:69], v[38:39], v[110:111]
	s_nop 0
	v_add_f32_e32 v68, v72, v68
	v_add_f32_e32 v72, v68, v69
	v_pk_mul_f32 v[68:69], v[40:41], v[112:113]
	s_nop 0
	v_add_f32_e32 v68, v72, v68
	v_add_f32_e32 v72, v68, v69
	v_pk_mul_f32 v[68:69], v[58:59], v[114:115]
	s_nop 0
	v_add_f32_e32 v68, v72, v68
	v_add_f32_e32 v68, v68, v69
	v_min_f32_e32 v69, 0, v68
	v_mul_f32_e64 v68, |v68|, s73
	v_exp_f32_e32 v68, v68
	s_nop 0
	v_add_f32_e32 v68, 1.0, v68
	v_cmp_gt_f32_e32 vcc, s94, v68
	s_nop 1
	v_cndmask_b32_e64 v70, 0, 32, vcc
	v_ldexp_f32 v68, v68, v70
	v_log_f32_e32 v68, v68
	s_nop 0
	v_mul_f32_e32 v70, 0x3f317217, v68
	v_fma_f32 v70, v68, s97, -v70
	v_fmac_f32_e32 v70, 0x3377d1cf, v68
	v_fmac_f32_e32 v70, 0x3f317217, v68
	v_cmp_lt_f32_e64 s[14:15], |v68|, s23
	s_nop 1
	v_cndmask_b32_e64 v68, v68, v70, s[14:15]
	v_cndmask_b32_e32 v70, 0, v211, vcc
	v_sub_f32_e32 v68, v68, v70
	v_sub_f32_e32 v68, v69, v68
	v_fmac_f32_e32 v67, 0x3d800000, v68
	v_mov_b32_e32 v121, v68
	v_add_u32_e32 v84, s0, v195
	ds_read_b128 v[68:71], v84
	ds_read_b128 v[72:75], v84 offset:16
	ds_read_b128 v[76:79], v84 offset:32
	ds_read_b128 v[80:83], v84 offset:48
	ds_read_b128 v[100:103], v84 offset:64
	ds_read_b128 v[104:107], v84 offset:80
	ds_read_b128 v[108:111], v84 offset:96
	ds_read_b128 v[112:115], v84 offset:112
	s_addk_i32 s0, 0x80
	s_waitcnt vmcnt(1) lgkmcnt(7)
	v_fma_f32 v85, v63, v68, v66
	v_fmac_f32_e32 v85, v64, v69
	v_fmac_f32_e32 v85, v60, v70
	v_fmac_f32_e32 v85, v65, v71
	s_waitcnt lgkmcnt(6)
	v_fmac_f32_e32 v85, v61, v72
	v_fmac_f32_e32 v85, v62, v73
	v_pk_mul_f32 v[68:69], v[34:35], v[74:75]
	v_add_f32_e32 v68, v85, v68
	v_add_f32_e32 v70, v68, v69
	s_waitcnt lgkmcnt(5)
	v_pk_mul_f32 v[68:69], v[36:37], v[76:77]
	s_nop 0
	v_add_f32_e32 v68, v70, v68
	v_add_f32_e32 v70, v68, v69
	v_pk_mul_f32 v[68:69], v[38:39], v[78:79]
	s_nop 0
	v_add_f32_e32 v68, v70, v68
	v_add_f32_e32 v70, v68, v69
	s_waitcnt lgkmcnt(4)
	v_pk_mul_f32 v[68:69], v[40:41], v[80:81]
	s_nop 0
	v_add_f32_e32 v68, v70, v68
	v_add_f32_e32 v70, v68, v69
	s_waitcnt vmcnt(0)
	v_pk_mul_f32 v[68:69], v[58:59], v[82:83]
	s_nop 0
	v_add_f32_e32 v68, v70, v68
	v_add_f32_e32 v68, v68, v69
	v_min_f32_e32 v69, 0, v68
	v_mul_f32_e64 v68, |v68|, s73
	v_exp_f32_e32 v68, v68
	s_nop 0
	v_add_f32_e32 v68, 1.0, v68
	v_cmp_gt_f32_e32 vcc, s94, v68
	s_nop 1
	v_cndmask_b32_e64 v70, 0, 32, vcc
	v_ldexp_f32 v68, v68, v70
	v_log_f32_e32 v68, v68
	s_nop 0
	v_mul_f32_e32 v70, 0x3f317217, v68
	v_fma_f32 v70, v68, s97, -v70
	v_fmac_f32_e32 v70, 0x3377d1cf, v68
	v_fmac_f32_e32 v70, 0x3f317217, v68
	v_cmp_lt_f32_e64 s[14:15], |v68|, s23
	s_nop 1
	v_cndmask_b32_e64 v68, v68, v70, s[14:15]
	v_cndmask_b32_e32 v70, 0, v211, vcc
	v_sub_f32_e32 v68, v68, v70
	v_sub_f32_e32 v68, v69, v68
	v_fmac_f32_e32 v67, 0x3d800000, v68
	v_mov_b32_e32 v122, v68
	s_waitcnt lgkmcnt(0)
	v_fma_f32 v72, v63, v100, v66
	v_fmac_f32_e32 v72, v64, v101
	v_fmac_f32_e32 v72, v60, v102
	v_fmac_f32_e32 v72, v65, v103
	v_fmac_f32_e32 v72, v61, v104
	v_fmac_f32_e32 v72, v62, v105
	v_pk_mul_f32 v[68:69], v[34:35], v[106:107]
	s_nop 0
	v_add_f32_e32 v68, v72, v68
	v_add_f32_e32 v72, v68, v69
	v_pk_mul_f32 v[68:69], v[36:37], v[108:109]
	s_nop 0
	v_add_f32_e32 v68, v72, v68
	v_add_f32_e32 v72, v68, v69
	v_pk_mul_f32 v[68:69], v[38:39], v[110:111]
	s_nop 0
	v_add_f32_e32 v68, v72, v68
	v_add_f32_e32 v72, v68, v69
	v_pk_mul_f32 v[68:69], v[40:41], v[112:113]
	s_nop 0
	v_add_f32_e32 v68, v72, v68
	v_add_f32_e32 v72, v68, v69
	v_pk_mul_f32 v[68:69], v[58:59], v[114:115]
	s_nop 0
	v_add_f32_e32 v68, v72, v68
	v_add_f32_e32 v68, v68, v69
	v_min_f32_e32 v69, 0, v68
	v_mul_f32_e64 v68, |v68|, s73
	v_exp_f32_e32 v68, v68
	s_nop 0
	v_add_f32_e32 v68, 1.0, v68
	v_cmp_gt_f32_e32 vcc, s94, v68
	s_nop 1
	v_cndmask_b32_e64 v70, 0, 32, vcc
	v_ldexp_f32 v68, v68, v70
	v_log_f32_e32 v68, v68
	s_nop 0
	v_mul_f32_e32 v70, 0x3f317217, v68
	v_fma_f32 v70, v68, s97, -v70
	v_fmac_f32_e32 v70, 0x3377d1cf, v68
	v_fmac_f32_e32 v70, 0x3f317217, v68
	v_cmp_lt_f32_e64 s[14:15], |v68|, s23
	s_nop 1
	v_cndmask_b32_e64 v68, v68, v70, s[14:15]
	v_cndmask_b32_e32 v70, 0, v211, vcc
	v_sub_f32_e32 v68, v68, v70
	v_sub_f32_e32 v68, v69, v68
	v_fmac_f32_e32 v67, 0x3d800000, v68
	v_mov_b32_e32 v123, v68
	v_add_u32_e32 v84, s0, v195
	ds_read_b128 v[68:71], v84
	ds_read_b128 v[72:75], v84 offset:16
	ds_read_b128 v[76:79], v84 offset:32
	ds_read_b128 v[80:83], v84 offset:48
	ds_read_b128 v[100:103], v84 offset:64
	ds_read_b128 v[104:107], v84 offset:80
	ds_read_b128 v[108:111], v84 offset:96
	ds_read_b128 v[112:115], v84 offset:112
	s_addk_i32 s0, 0x80
	s_waitcnt vmcnt(1) lgkmcnt(7)
; DEVI float logsigf_(float x) { return fminf(x, 0.f) - __logf(1.f + __expf(-fabsf(x))); }
; DEVI float gla_la(const float* gl, int t, const float* w2r, float gb) { float x = gb;
; #pragma unroll
;     for (int r = 0; r < 16; ++r) x += gl[t * 16 + r] * w2r[r];
;     return logsigf_(x) * (1.f / 16.f); }
; template <int KIND>
; DEVI void mix_out_phase(unsigned char* smem, const MixArgs a) {
;     ...
;             for (int t = sg * 32; t < sg * 32 + 32; ++t) ssum += gla_la(gl, t, w2r, gb);
	v_fma_f32 v85, v63, v68, v66
	v_fmac_f32_e32 v85, v64, v69
	v_fmac_f32_e32 v85, v60, v70
	v_fmac_f32_e32 v85, v65, v71
	s_waitcnt lgkmcnt(6)
	v_fmac_f32_e32 v85, v61, v72
	v_fmac_f32_e32 v85, v62, v73
	v_pk_mul_f32 v[68:69], v[34:35], v[74:75]
	v_add_f32_e32 v68, v85, v68
	v_add_f32_e32 v70, v68, v69
	s_waitcnt lgkmcnt(5)
	v_pk_mul_f32 v[68:69], v[36:37], v[76:77]
	s_nop 0
	v_add_f32_e32 v68, v70, v68
	v_add_f32_e32 v70, v68, v69
	v_pk_mul_f32 v[68:69], v[38:39], v[78:79]
	s_nop 0
	v_add_f32_e32 v68, v70, v68
	v_add_f32_e32 v70, v68, v69
	s_waitcnt lgkmcnt(4)
	v_pk_mul_f32 v[68:69], v[40:41], v[80:81]
	s_nop 0
	v_add_f32_e32 v68, v70, v68
	v_add_f32_e32 v70, v68, v69
	s_waitcnt vmcnt(0)
	v_pk_mul_f32 v[68:69], v[58:59], v[82:83]
	s_nop 0
	v_add_f32_e32 v68, v70, v68
	v_add_f32_e32 v68, v68, v69
	v_min_f32_e32 v69, 0, v68
	v_mul_f32_e64 v68, |v68|, s73
	v_exp_f32_e32 v68, v68
	s_nop 0
	v_add_f32_e32 v68, 1.0, v68
	v_cmp_gt_f32_e32 vcc, s94, v68
	s_nop 1
	v_cndmask_b32_e64 v70, 0, 32, vcc
	v_ldexp_f32 v68, v68, v70
	v_log_f32_e32 v68, v68
	s_nop 0
	v_mul_f32_e32 v70, 0x3f317217, v68
	v_fma_f32 v70, v68, s97, -v70
	v_fmac_f32_e32 v70, 0x3377d1cf, v68
	v_fmac_f32_e32 v70, 0x3f317217, v68
	v_cmp_lt_f32_e64 s[14:15], |v68|, s23
	s_nop 1
	v_cndmask_b32_e64 v68, v68, v70, s[14:15]
	v_cndmask_b32_e32 v70, 0, v211, vcc
	v_sub_f32_e32 v68, v68, v70
	v_sub_f32_e32 v68, v69, v68
	v_fmac_f32_e32 v67, 0x3d800000, v68
	v_mov_b32_e32 v124, v68
	s_waitcnt lgkmcnt(0)
	v_fma_f32 v72, v63, v100, v66
	v_fmac_f32_e32 v72, v64, v101
	v_fmac_f32_e32 v72, v60, v102
	v_fmac_f32_e32 v72, v65, v103
	v_fmac_f32_e32 v72, v61, v104
	v_fmac_f32_e32 v72, v62, v105
	v_pk_mul_f32 v[68:69], v[34:35], v[106:107]
	s_nop 0
	v_add_f32_e32 v68, v72, v68
	v_add_f32_e32 v72, v68, v69
	v_pk_mul_f32 v[68:69], v[36:37], v[108:109]
	s_nop 0
	v_add_f32_e32 v68, v72, v68
	v_add_f32_e32 v72, v68, v69
	v_pk_mul_f32 v[68:69], v[38:39], v[110:111]
	s_nop 0
	v_add_f32_e32 v68, v72, v68
	v_add_f32_e32 v72, v68, v69
	v_pk_mul_f32 v[68:69], v[40:41], v[112:113]
	s_nop 0
	v_add_f32_e32 v68, v72, v68
	v_add_f32_e32 v72, v68, v69
	v_pk_mul_f32 v[68:69], v[58:59], v[114:115]
	s_nop 0
	v_add_f32_e32 v68, v72, v68
	v_add_f32_e32 v68, v68, v69
	v_min_f32_e32 v69, 0, v68
	v_mul_f32_e64 v68, |v68|, s73
	v_exp_f32_e32 v68, v68
	s_nop 0
	v_add_f32_e32 v68, 1.0, v68
	v_cmp_gt_f32_e32 vcc, s94, v68
	s_nop 1
	v_cndmask_b32_e64 v70, 0, 32, vcc
	v_ldexp_f32 v68, v68, v70
	v_log_f32_e32 v68, v68
	s_nop 0
	v_mul_f32_e32 v70, 0x3f317217, v68
	v_fma_f32 v70, v68, s97, -v70
	v_fmac_f32_e32 v70, 0x3377d1cf, v68
	v_fmac_f32_e32 v70, 0x3f317217, v68
	v_cmp_lt_f32_e64 s[14:15], |v68|, s23
	s_nop 1
	v_cndmask_b32_e64 v68, v68, v70, s[14:15]
	v_cndmask_b32_e32 v70, 0, v211, vcc
	v_sub_f32_e32 v68, v68, v70
	v_sub_f32_e32 v68, v69, v68
	v_fmac_f32_e32 v67, 0x3d800000, v68
	v_mov_b32_e32 v125, v68
	v_add_u32_e32 v84, s0, v195
	ds_read_b128 v[68:71], v84
	ds_read_b128 v[72:75], v84 offset:16
	ds_read_b128 v[76:79], v84 offset:32
	ds_read_b128 v[80:83], v84 offset:48
	ds_read_b128 v[100:103], v84 offset:64
	ds_read_b128 v[104:107], v84 offset:80
	ds_read_b128 v[108:111], v84 offset:96
	ds_read_b128 v[112:115], v84 offset:112
	s_addk_i32 s0, 0x80
	s_waitcnt vmcnt(1) lgkmcnt(7)
	v_fma_f32 v85, v63, v68, v66
	v_fmac_f32_e32 v85, v64, v69
	v_fmac_f32_e32 v85, v60, v70
	v_fmac_f32_e32 v85, v65, v71
	s_waitcnt lgkmcnt(6)
	v_fmac_f32_e32 v85, v61, v72
	v_fmac_f32_e32 v85, v62, v73
	v_pk_mul_f32 v[68:69], v[34:35], v[74:75]
	v_add_f32_e32 v68, v85, v68
	v_add_f32_e32 v70, v68, v69
	s_waitcnt lgkmcnt(5)
	v_pk_mul_f32 v[68:69], v[36:37], v[76:77]
	s_nop 0
	v_add_f32_e32 v68, v70, v68
	v_add_f32_e32 v70, v68, v69
	v_pk_mul_f32 v[68:69], v[38:39], v[78:79]
	s_nop 0
	v_add_f32_e32 v68, v70, v68
	v_add_f32_e32 v70, v68, v69
	s_waitcnt lgkmcnt(4)
	v_pk_mul_f32 v[68:69], v[40:41], v[80:81]
	s_nop 0
	v_add_f32_e32 v68, v70, v68
	v_add_f32_e32 v70, v68, v69
	s_waitcnt vmcnt(0)
	v_pk_mul_f32 v[68:69], v[58:59], v[82:83]
	s_nop 0
	v_add_f32_e32 v68, v70, v68
	v_add_f32_e32 v68, v68, v69
	v_min_f32_e32 v69, 0, v68
	v_mul_f32_e64 v68, |v68|, s73
	v_exp_f32_e32 v68, v68
	s_nop 0
	v_add_f32_e32 v68, 1.0, v68
	v_cmp_gt_f32_e32 vcc, s94, v68
	s_nop 1
	v_cndmask_b32_e64 v70, 0, 32, vcc
	v_ldexp_f32 v68, v68, v70
	v_log_f32_e32 v68, v68
	s_nop 0
	v_mul_f32_e32 v70, 0x3f317217, v68
	v_fma_f32 v70, v68, s97, -v70
	v_fmac_f32_e32 v70, 0x3377d1cf, v68
	v_fmac_f32_e32 v70, 0x3f317217, v68
	v_cmp_lt_f32_e64 s[14:15], |v68|, s23
	s_nop 1
	v_cndmask_b32_e64 v68, v68, v70, s[14:15]
	v_cndmask_b32_e32 v70, 0, v211, vcc
	v_sub_f32_e32 v68, v68, v70
	v_sub_f32_e32 v68, v69, v68
	v_fmac_f32_e32 v67, 0x3d800000, v68
	v_mov_b32_e32 v126, v68
	s_waitcnt lgkmcnt(0)
	v_fma_f32 v72, v63, v100, v66
	v_fmac_f32_e32 v72, v64, v101
	v_fmac_f32_e32 v72, v60, v102
	v_fmac_f32_e32 v72, v65, v103
	v_fmac_f32_e32 v72, v61, v104
	v_fmac_f32_e32 v72, v62, v105
	v_pk_mul_f32 v[68:69], v[34:35], v[106:107]
	s_nop 0
	v_add_f32_e32 v68, v72, v68
	v_add_f32_e32 v72, v68, v69
	v_pk_mul_f32 v[68:69], v[36:37], v[108:109]
	s_nop 0
	v_add_f32_e32 v68, v72, v68
	v_add_f32_e32 v72, v68, v69
	v_pk_mul_f32 v[68:69], v[38:39], v[110:111]
	s_nop 0
	v_add_f32_e32 v68, v72, v68
	v_add_f32_e32 v72, v68, v69
	v_pk_mul_f32 v[68:69], v[40:41], v[112:113]
	s_nop 0
	v_add_f32_e32 v68, v72, v68
	v_add_f32_e32 v72, v68, v69
	v_pk_mul_f32 v[68:69], v[58:59], v[114:115]
	s_nop 0
	v_add_f32_e32 v68, v72, v68
	v_add_f32_e32 v68, v68, v69
	v_min_f32_e32 v69, 0, v68
	v_mul_f32_e64 v68, |v68|, s73
	v_exp_f32_e32 v68, v68
	s_nop 0
	v_add_f32_e32 v68, 1.0, v68
	v_cmp_gt_f32_e32 vcc, s94, v68
	s_nop 1
	v_cndmask_b32_e64 v70, 0, 32, vcc
	v_ldexp_f32 v68, v68, v70
	v_log_f32_e32 v68, v68
	s_nop 0
	v_mul_f32_e32 v70, 0x3f317217, v68
	v_fma_f32 v70, v68, s97, -v70
	v_fmac_f32_e32 v70, 0x3377d1cf, v68
	v_fmac_f32_e32 v70, 0x3f317217, v68
	v_cmp_lt_f32_e64 s[14:15], |v68|, s23
	s_nop 1
	v_cndmask_b32_e64 v68, v68, v70, s[14:15]
	v_cndmask_b32_e32 v70, 0, v211, vcc
	v_sub_f32_e32 v68, v68, v70
	v_sub_f32_e32 v68, v69, v68
	v_fmac_f32_e32 v67, 0x3d800000, v68
	v_mov_b32_e32 v127, v68
	v_add_u32_e32 v84, s0, v195
	ds_read_b128 v[68:71], v84
	ds_read_b128 v[72:75], v84 offset:16
	ds_read_b128 v[76:79], v84 offset:32
	ds_read_b128 v[80:83], v84 offset:48
	ds_read_b128 v[100:103], v84 offset:64
	ds_read_b128 v[104:107], v84 offset:80
	ds_read_b128 v[108:111], v84 offset:96
	ds_read_b128 v[112:115], v84 offset:112
	s_addk_i32 s0, 0x80
	s_waitcnt vmcnt(1) lgkmcnt(7)
; DEVI float logsigf_(float x) { return fminf(x, 0.f) - __logf(1.f + __expf(-fabsf(x))); }
; DEVI float gla_la(const float* gl, int t, const float* w2r, float gb) { float x = gb;
; #pragma unroll
;     for (int r = 0; r < 16; ++r) x += gl[t * 16 + r] * w2r[r];
;     return logsigf_(x) * (1.f / 16.f); }
; template <int KIND>
; DEVI void mix_out_phase(unsigned char* smem, const MixArgs a) {
;     ...
;             for (int t = sg * 32; t < sg * 32 + 32; ++t) ssum += gla_la(gl, t, w2r, gb);
	v_fma_f32 v85, v63, v68, v66
	v_fmac_f32_e32 v85, v64, v69
	v_fmac_f32_e32 v85, v60, v70
	v_fmac_f32_e32 v85, v65, v71
	s_waitcnt lgkmcnt(6)
	v_fmac_f32_e32 v85, v61, v72
	v_fmac_f32_e32 v85, v62, v73
	v_pk_mul_f32 v[68:69], v[34:35], v[74:75]
	v_add_f32_e32 v68, v85, v68
	v_add_f32_e32 v70, v68, v69
	s_waitcnt lgkmcnt(5)
	v_pk_mul_f32 v[68:69], v[36:37], v[76:77]
	s_nop 0
	v_add_f32_e32 v68, v70, v68
	v_add_f32_e32 v70, v68, v69
	v_pk_mul_f32 v[68:69], v[38:39], v[78:79]
	s_nop 0
	v_add_f32_e32 v68, v70, v68
	v_add_f32_e32 v70, v68, v69
	s_waitcnt lgkmcnt(4)
	v_pk_mul_f32 v[68:69], v[40:41], v[80:81]
	s_nop 0
	v_add_f32_e32 v68, v70, v68
	v_add_f32_e32 v70, v68, v69
	s_waitcnt vmcnt(0)
	v_pk_mul_f32 v[68:69], v[58:59], v[82:83]
	s_nop 0
	v_add_f32_e32 v68, v70, v68
	v_add_f32_e32 v68, v68, v69
	v_min_f32_e32 v69, 0, v68
	v_mul_f32_e64 v68, |v68|, s73
	v_exp_f32_e32 v68, v68
	s_nop 0
	v_add_f32_e32 v68, 1.0, v68
	v_cmp_gt_f32_e32 vcc, s94, v68
	s_nop 1
	v_cndmask_b32_e64 v70, 0, 32, vcc
	v_ldexp_f32 v68, v68, v70
	v_log_f32_e32 v68, v68
	s_nop 0
	v_mul_f32_e32 v70, 0x3f317217, v68
	v_fma_f32 v70, v68, s97, -v70
	v_fmac_f32_e32 v70, 0x3377d1cf, v68
	v_fmac_f32_e32 v70, 0x3f317217, v68
	v_cmp_lt_f32_e64 s[14:15], |v68|, s23
	s_nop 1
	v_cndmask_b32_e64 v68, v68, v70, s[14:15]
	v_cndmask_b32_e32 v70, 0, v211, vcc
	v_sub_f32_e32 v68, v68, v70
	v_sub_f32_e32 v68, v69, v68
	v_fmac_f32_e32 v67, 0x3d800000, v68
	v_mov_b32_e32 v128, v68
	s_waitcnt lgkmcnt(0)
	v_fma_f32 v72, v63, v100, v66
	v_fmac_f32_e32 v72, v64, v101
	v_fmac_f32_e32 v72, v60, v102
	v_fmac_f32_e32 v72, v65, v103
	v_fmac_f32_e32 v72, v61, v104
	v_fmac_f32_e32 v72, v62, v105
	v_pk_mul_f32 v[68:69], v[34:35], v[106:107]
	s_nop 0
	v_add_f32_e32 v68, v72, v68
	v_add_f32_e32 v72, v68, v69
	v_pk_mul_f32 v[68:69], v[36:37], v[108:109]
	s_nop 0
	v_add_f32_e32 v68, v72, v68
	v_add_f32_e32 v72, v68, v69
	v_pk_mul_f32 v[68:69], v[38:39], v[110:111]
	s_nop 0
	v_add_f32_e32 v68, v72, v68
	v_add_f32_e32 v72, v68, v69
	v_pk_mul_f32 v[68:69], v[40:41], v[112:113]
	s_nop 0
	v_add_f32_e32 v68, v72, v68
	v_add_f32_e32 v72, v68, v69
	v_pk_mul_f32 v[68:69], v[58:59], v[114:115]
	s_nop 0
	v_add_f32_e32 v68, v72, v68
	v_add_f32_e32 v68, v68, v69
	v_min_f32_e32 v69, 0, v68
	v_mul_f32_e64 v68, |v68|, s73
	v_exp_f32_e32 v68, v68
	s_nop 0
	v_add_f32_e32 v68, 1.0, v68
	v_cmp_gt_f32_e32 vcc, s94, v68
	s_nop 1
	v_cndmask_b32_e64 v70, 0, 32, vcc
	v_ldexp_f32 v68, v68, v70
	v_log_f32_e32 v68, v68
	s_nop 0
	v_mul_f32_e32 v70, 0x3f317217, v68
	v_fma_f32 v70, v68, s97, -v70
	v_fmac_f32_e32 v70, 0x3377d1cf, v68
	v_fmac_f32_e32 v70, 0x3f317217, v68
	v_cmp_lt_f32_e64 s[14:15], |v68|, s23
	s_nop 1
	v_cndmask_b32_e64 v68, v68, v70, s[14:15]
	v_cndmask_b32_e32 v70, 0, v211, vcc
	v_sub_f32_e32 v68, v68, v70
	v_sub_f32_e32 v68, v69, v68
	v_fmac_f32_e32 v67, 0x3d800000, v68
	v_mov_b32_e32 v129, v68
	v_add_u32_e32 v84, s0, v195
	ds_read_b128 v[68:71], v84
	ds_read_b128 v[72:75], v84 offset:16
	ds_read_b128 v[76:79], v84 offset:32
	ds_read_b128 v[80:83], v84 offset:48
	ds_read_b128 v[100:103], v84 offset:64
	ds_read_b128 v[104:107], v84 offset:80
	ds_read_b128 v[108:111], v84 offset:96
	ds_read_b128 v[112:115], v84 offset:112
	s_addk_i32 s0, 0x80
	s_waitcnt vmcnt(1) lgkmcnt(7)
	v_fma_f32 v85, v63, v68, v66
	v_fmac_f32_e32 v85, v64, v69
	v_fmac_f32_e32 v85, v60, v70
	v_fmac_f32_e32 v85, v65, v71
	s_waitcnt lgkmcnt(6)
	v_fmac_f32_e32 v85, v61, v72
	v_fmac_f32_e32 v85, v62, v73
	v_pk_mul_f32 v[68:69], v[34:35], v[74:75]
	v_add_f32_e32 v68, v85, v68
	v_add_f32_e32 v70, v68, v69
	s_waitcnt lgkmcnt(5)
	v_pk_mul_f32 v[68:69], v[36:37], v[76:77]
	s_nop 0
	v_add_f32_e32 v68, v70, v68
	v_add_f32_e32 v70, v68, v69
	v_pk_mul_f32 v[68:69], v[38:39], v[78:79]
	s_nop 0
	v_add_f32_e32 v68, v70, v68
	v_add_f32_e32 v70, v68, v69
	s_waitcnt lgkmcnt(4)
	v_pk_mul_f32 v[68:69], v[40:41], v[80:81]
	s_nop 0
	v_add_f32_e32 v68, v70, v68
	v_add_f32_e32 v70, v68, v69
	s_waitcnt vmcnt(0)
	v_pk_mul_f32 v[68:69], v[58:59], v[82:83]
	s_nop 0
	v_add_f32_e32 v68, v70, v68
	v_add_f32_e32 v68, v68, v69
	v_min_f32_e32 v69, 0, v68
	v_mul_f32_e64 v68, |v68|, s73
	v_exp_f32_e32 v68, v68
	s_nop 0
	v_add_f32_e32 v68, 1.0, v68
	v_cmp_gt_f32_e32 vcc, s94, v68
	s_nop 1
	v_cndmask_b32_e64 v70, 0, 32, vcc
	v_ldexp_f32 v68, v68, v70
	v_log_f32_e32 v68, v68
	s_nop 0
	v_mul_f32_e32 v70, 0x3f317217, v68
	v_fma_f32 v70, v68, s97, -v70
	v_fmac_f32_e32 v70, 0x3377d1cf, v68
	v_fmac_f32_e32 v70, 0x3f317217, v68
	v_cmp_lt_f32_e64 s[14:15], |v68|, s23
	s_nop 1
	v_cndmask_b32_e64 v68, v68, v70, s[14:15]
	v_cndmask_b32_e32 v70, 0, v211, vcc
	v_sub_f32_e32 v68, v68, v70
	v_sub_f32_e32 v68, v69, v68
	v_fmac_f32_e32 v67, 0x3d800000, v68
	v_mov_b32_e32 v136, v68
	s_waitcnt lgkmcnt(0)
	v_fma_f32 v72, v63, v100, v66
	v_fmac_f32_e32 v72, v64, v101
	v_fmac_f32_e32 v72, v60, v102
	v_fmac_f32_e32 v72, v65, v103
	v_fmac_f32_e32 v72, v61, v104
	v_fmac_f32_e32 v72, v62, v105
	v_pk_mul_f32 v[68:69], v[34:35], v[106:107]
	s_nop 0
	v_add_f32_e32 v68, v72, v68
	v_add_f32_e32 v72, v68, v69
	v_pk_mul_f32 v[68:69], v[36:37], v[108:109]
	s_nop 0
	v_add_f32_e32 v68, v72, v68
	v_add_f32_e32 v72, v68, v69
	v_pk_mul_f32 v[68:69], v[38:39], v[110:111]
	s_nop 0
	v_add_f32_e32 v68, v72, v68
	v_add_f32_e32 v72, v68, v69
	v_pk_mul_f32 v[68:69], v[40:41], v[112:113]
	s_nop 0
	v_add_f32_e32 v68, v72, v68
	v_add_f32_e32 v72, v68, v69
	v_pk_mul_f32 v[68:69], v[58:59], v[114:115]
	s_nop 0
	v_add_f32_e32 v68, v72, v68
	v_add_f32_e32 v68, v68, v69
	v_min_f32_e32 v69, 0, v68
	v_mul_f32_e64 v68, |v68|, s73
	v_exp_f32_e32 v68, v68
	s_nop 0
	v_add_f32_e32 v68, 1.0, v68
	v_cmp_gt_f32_e32 vcc, s94, v68
	s_nop 1
	v_cndmask_b32_e64 v70, 0, 32, vcc
	v_ldexp_f32 v68, v68, v70
	v_log_f32_e32 v68, v68
	s_nop 0
	v_mul_f32_e32 v70, 0x3f317217, v68
	v_fma_f32 v70, v68, s97, -v70
	v_fmac_f32_e32 v70, 0x3377d1cf, v68
	v_fmac_f32_e32 v70, 0x3f317217, v68
	v_cmp_lt_f32_e64 s[14:15], |v68|, s23
	s_nop 1
	v_cndmask_b32_e64 v68, v68, v70, s[14:15]
	v_cndmask_b32_e32 v70, 0, v211, vcc
	v_sub_f32_e32 v68, v68, v70
	v_sub_f32_e32 v68, v69, v68
	v_fmac_f32_e32 v67, 0x3d800000, v68
	v_mov_b32_e32 v137, v68
	v_add_u32_e32 v84, s0, v195
	ds_read_b128 v[68:71], v84
	ds_read_b128 v[72:75], v84 offset:16
	ds_read_b128 v[76:79], v84 offset:32
	ds_read_b128 v[80:83], v84 offset:48
	ds_read_b128 v[100:103], v84 offset:64
	ds_read_b128 v[104:107], v84 offset:80
	ds_read_b128 v[108:111], v84 offset:96
	ds_read_b128 v[112:115], v84 offset:112
	s_addk_i32 s0, 0x80
	s_waitcnt vmcnt(1) lgkmcnt(7)
; DEVI float logsigf_(float x) { return fminf(x, 0.f) - __logf(1.f + __expf(-fabsf(x))); }
; DEVI float gla_la(const float* gl, int t, const float* w2r, float gb) { float x = gb;
; #pragma unroll
;     for (int r = 0; r < 16; ++r) x += gl[t * 16 + r] * w2r[r];
;     return logsigf_(x) * (1.f / 16.f); }
	v_fma_f32 v85, v63, v68, v66
	v_fmac_f32_e32 v85, v64, v69
	v_fmac_f32_e32 v85, v60, v70
	v_fmac_f32_e32 v85, v65, v71
	s_waitcnt lgkmcnt(6)
	v_fmac_f32_e32 v85, v61, v72
	v_fmac_f32_e32 v85, v62, v73
	v_pk_mul_f32 v[68:69], v[34:35], v[74:75]
	v_add_f32_e32 v68, v85, v68
	v_add_f32_e32 v70, v68, v69
	s_waitcnt lgkmcnt(5)
	v_pk_mul_f32 v[68:69], v[36:37], v[76:77]
	s_nop 0
	v_add_f32_e32 v68, v70, v68
	v_add_f32_e32 v70, v68, v69
	v_pk_mul_f32 v[68:69], v[38:39], v[78:79]
	s_nop 0
	v_add_f32_e32 v68, v70, v68
	v_add_f32_e32 v70, v68, v69
	s_waitcnt lgkmcnt(4)
	v_pk_mul_f32 v[68:69], v[40:41], v[80:81]
	s_nop 0
	v_add_f32_e32 v68, v70, v68
	v_add_f32_e32 v70, v68, v69
	s_waitcnt vmcnt(0)
	v_pk_mul_f32 v[68:69], v[58:59], v[82:83]
	s_nop 0
	v_add_f32_e32 v68, v70, v68
	v_add_f32_e32 v68, v68, v69
	v_min_f32_e32 v69, 0, v68
	v_mul_f32_e64 v68, |v68|, s73
	v_exp_f32_e32 v68, v68
	s_nop 0
	v_add_f32_e32 v68, 1.0, v68
	v_cmp_gt_f32_e32 vcc, s94, v68
	s_nop 1
	v_cndmask_b32_e64 v70, 0, 32, vcc
	v_ldexp_f32 v68, v68, v70
	v_log_f32_e32 v68, v68
	s_nop 0
	v_mul_f32_e32 v70, 0x3f317217, v68
	v_fma_f32 v70, v68, s97, -v70
	v_fmac_f32_e32 v70, 0x3377d1cf, v68
	v_fmac_f32_e32 v70, 0x3f317217, v68
	v_cmp_lt_f32_e64 s[14:15], |v68|, s23
	s_nop 1
	v_cndmask_b32_e64 v68, v68, v70, s[14:15]
	v_cndmask_b32_e32 v70, 0, v211, vcc
	v_sub_f32_e32 v68, v68, v70
	v_sub_f32_e32 v68, v69, v68
	v_fmac_f32_e32 v67, 0x3d800000, v68
	v_mov_b32_e32 v138, v68
	s_waitcnt lgkmcnt(0)
	v_fma_f32 v72, v63, v100, v66
	v_fmac_f32_e32 v72, v64, v101
	v_fmac_f32_e32 v72, v60, v102
	v_fmac_f32_e32 v72, v65, v103
	v_fmac_f32_e32 v72, v61, v104
	v_fmac_f32_e32 v72, v62, v105
	v_pk_mul_f32 v[68:69], v[34:35], v[106:107]
	s_nop 0
	v_add_f32_e32 v68, v72, v68
	v_add_f32_e32 v72, v68, v69
	v_pk_mul_f32 v[68:69], v[36:37], v[108:109]
	s_nop 0
	v_add_f32_e32 v68, v72, v68
	v_add_f32_e32 v72, v68, v69
	v_pk_mul_f32 v[68:69], v[38:39], v[110:111]
	s_nop 0
	v_add_f32_e32 v68, v72, v68
	v_add_f32_e32 v72, v68, v69
	v_pk_mul_f32 v[68:69], v[40:41], v[112:113]
	s_nop 0
	v_add_f32_e32 v68, v72, v68
	v_add_f32_e32 v72, v68, v69
	v_pk_mul_f32 v[68:69], v[58:59], v[114:115]
	s_nop 0
	v_add_f32_e32 v68, v72, v68
	v_add_f32_e32 v68, v68, v69
	v_min_f32_e32 v69, 0, v68
	v_mul_f32_e64 v68, |v68|, s73
	v_exp_f32_e32 v68, v68
	s_nop 0
	v_add_f32_e32 v68, 1.0, v68
	v_cmp_gt_f32_e32 vcc, s94, v68
	s_nop 1
	v_cndmask_b32_e64 v70, 0, 32, vcc
	v_ldexp_f32 v68, v68, v70
	v_log_f32_e32 v68, v68
	s_nop 0
	v_mul_f32_e32 v70, 0x3f317217, v68
	v_fma_f32 v70, v68, s97, -v70
	v_fmac_f32_e32 v70, 0x3377d1cf, v68
	v_fmac_f32_e32 v70, 0x3f317217, v68
	v_cmp_lt_f32_e64 s[14:15], |v68|, s23
	s_nop 1
	v_cndmask_b32_e64 v68, v68, v70, s[14:15]
	v_cndmask_b32_e32 v70, 0, v211, vcc
	v_sub_f32_e32 v68, v68, v70
	v_sub_f32_e32 v68, v69, v68
	v_fmac_f32_e32 v67, 0x3d800000, v68
	v_mov_b32_e32 v139, v68
	s_cmpk_gt_i32 s88, 0x3ff
	s_cselect_b64 s[16:17], -1, 0
	s_and_b64 vcc, exec, s[16:17]
	s_cbranch_vccnz .Lpfm_out
	s_ashr_i32 s1, s88, 31
	s_lshr_b32 s1, s1, 26
	s_add_i32 s1, s88, s1
	s_and_b32 s14, s1, 0x1ffffc0
	s_sub_i32 s18, s88, s14
	s_ashr_i32 s14, s1, 8
	s_ashr_i32 s15, s14, 31
	s_lshl_b32 s18, s18, 7
	s_lshl_b64 s[14:15], s[14:15], 13
	s_ashr_i32 s19, s18, 31
	s_add_u32 s14, s14, s18
	s_addc_u32 s15, s15, s19
	s_lshl_b32 s1, s1, 2
	s_and_b32 s66, s1, 0x300
	v_lshl_add_u64 v[26:27], v[180:181], 0, s[66:67]
	v_lshl_add_u64 v[10:11], s[14:15], 0, v[146:147]
	v_lshl_add_u64 v[18:19], s[14:15], 0, v[148:149]
	v_lshl_add_u64 v[28:29], s[14:15], 0, v[150:151]
	v_lshl_add_u64 v[34:35], s[14:15], 0, v[152:153]
	v_mad_u64_u32 v[4:5], s[18:19], v10, s95, v[26:27]
	v_mad_u64_u32 v[14:15], s[18:19], v18, s95, v[26:27]
	v_mad_u64_u32 v[22:23], s[18:19], v28, s95, v[26:27]
	v_mad_u64_u32 v[30:31], s[14:15], v34, s95, v[26:27]
	v_mad_i32_i24 v5, v11, s95, v5
	v_lshlrev_b64 v[10:11], 6, v[10:11]
	v_mad_i32_i24 v15, v19, s95, v15
	v_lshlrev_b64 v[18:19], 6, v[18:19]
	v_mad_i32_i24 v23, v29, s95, v23
	v_lshlrev_b64 v[28:29], 6, v[28:29]
	v_mad_i32_i24 v31, v35, s95, v31
	v_lshlrev_b64 v[34:35], 6, v[34:35]
	v_lshl_add_u64 v[10:11], v[182:183], 0, v[10:11]
	v_lshl_add_u64 v[18:19], v[182:183], 0, v[18:19]
	v_lshl_add_u64 v[28:29], v[182:183], 0, v[28:29]
	v_lshl_add_u64 v[34:35], v[182:183], 0, v[34:35]
	global_load_dwordx4 v[0:3], v[4:5], off nt
	s_nop 0
	global_load_dwordx4 v[4:7], v[4:5], off offset:1024 nt
	s_nop 0
	global_load_dword v185, v[10:11], off
	s_nop 0
	global_load_dwordx4 v[10:13], v[14:15], off nt
	s_nop 0
	global_load_dwordx4 v[14:17], v[14:15], off offset:1024 nt
	s_nop 0
	global_load_dword v200, v[18:19], off
	s_nop 0
	global_load_dwordx4 v[18:21], v[22:23], off nt
	s_nop 0
	global_load_dwordx4 v[22:25], v[22:23], off offset:1024 nt
	s_nop 0
	global_load_dword v201, v[28:29], off
	s_nop 0
	global_load_dwordx4 v[26:29], v[30:31], off nt
	s_nop 0
	global_load_dwordx4 v[30:33], v[30:31], off offset:1024 nt
	s_nop 0
	global_load_dword v207, v[34:35], off

; DEVI void lds_barrier() { asm volatile("s_waitcnt lgkmcnt(0)\n\ts_barrier" ::: "memory"); }
; DEVI f32x4 mfma16(bf16x8 a, bf16x8 b, f32x4 c) { return __builtin_amdgcn_mfma_f32_16x16x32_bf16(a, b, c, 0, 0, 0); }
; #define MIX_PREF(qq, bb) do { _Pragma("unroll") for (int k = 0; k < 2; ++k) { const int i = tid + k * 512; \
;             pv[bb][k] = *(const u32x4*)(a.proj + (tok0 + (i >> 3)) * 3072 + 1024 + h * 256 + (qq) * 64 + (i & 7) * 8); \
;             pc[bb][k] = *(const u32x4*)(a.states + ((size_t)item * 256 + (qq) * 64 + (i >> 4)) * 128 + (i & 15) * 8); } } while (0)
; template <int KIND>
; DEVI void mix_out_phase(unsigned char* smem, const MixArgs a) {
;     ...
;         bf16x8 gtv[8];
; #pragma unroll
;         for (int i = 0; i < 8; ++i) gtv[i] = *(const bf16x8*)(a.proj + tok * 3072 + 2048 + h * 256 + i * 32 + fq * 8);
;         f32x4 o[16];
; #pragma unroll
;         for (int qv = 0; qv < 4; ++qv) {
;             lds_barrier();
; #pragma unroll
;             for (int k = 0; k < 2; ++k) { const int i = tid + k * 512; *(u32x4*)(VT + (i >> 3) * VQP + (i & 7) * 8) = pv[0][k]; *(u32x4*)(CT + (i >> 4) * LP + (i & 15) * 8) = pc[0][k]; }
;             lds_barrier();
;             if (qv < 3) MIX_PREF(qv + 1, 0);
; #pragma unroll
;             for (int n = 0; n < 4; ++n) { f32x4 ac = (f32x4){0.f, 0.f, 0.f, 0.f};
; #pragma unroll
;                 for (int ks = 0; ks < 4; ++ks) { const bf16x8 cb = *(const bf16x8*)(CT + (32 * (n >> 1) + 8 * (fr >> 2) + 4 * (n & 1) + (fr & 3)) * LP + ks * 32 + fq * 8); ac = mfma16(cb, qa[ks], ac); }
.LBB0_707:
	s_or_b64 exec, exec, s[14:15]
	v_lshl_add_u64 v[198:199], s[68:69], 0, v[176:177]
	v_mov_b64_e32 v[34:35], s[28:29]
	v_mad_u64_u32 v[34:35], s[0:1], v198, s95, v[34:35]
	v_mad_i32_i24 v35, v199, s95, v35
	s_lshl_b32 s66, s89, 1
	v_lshl_add_u64 v[34:35], v[34:35], 0, s[66:67]
	v_lshlrev_b32_e32 v36, 1, v184
	v_mov_b32_e32 v37, v9
	v_lshl_add_u64 v[34:35], v[34:35], 0, v[36:37]
	s_mov_b64 s[0:1], 0x1000
	v_lshl_add_u64 v[36:37], v[34:35], 0, s[0:1]
	v_add_co_u32_e32 v34, vcc, s50, v34
	v_add_u32_e32 v229, v208, v209
	s_nop 0
	v_addc_co_u32_e32 v35, vcc, 0, v35, vcc
	v_add_u32_e32 v230, v208, v214
	global_load_dwordx4 v[74:77], v[36:37], off offset:64 nt
	global_load_dwordx4 v[70:73], v[36:37], off offset:128 nt
	global_load_dwordx4 v[66:69], v[36:37], off offset:192 nt
	global_load_dwordx4 v[62:65], v[36:37], off offset:256 nt
	global_load_dwordx4 v[58:61], v[36:37], off offset:320 nt
	global_load_dwordx4 v[38:41], v[36:37], off offset:384 nt
	global_load_dwordx4 v[78:81], v[34:35], off nt
	s_nop 0
	global_load_dwordx4 v[34:37], v[36:37], off offset:448 nt
	s_waitcnt lgkmcnt(0)
	s_barrier
	ds_write_b128 v226, v[50:53]
	ds_write_b128 v229, v[54:57]
	ds_write_b128 v227, v[42:45]
	ds_write_b128 v230, v[46:49]
	s_waitcnt lgkmcnt(0)
	s_barrier
	ds_read_b128 v[42:45], v228
	ds_read_b128 v[46:49], v228 offset:64
	s_lshl_b64 s[14:15], s[46:47], 8
	s_waitcnt lgkmcnt(1)
	v_mfma_f32_16x16x32_bf16 v[42:45], v[42:45], v[94:97], 0
	s_or_b32 s0, s14, 64
	s_mov_b32 s1, s15
	v_lshl_add_u64 v[50:51], s[0:1], 0, v[146:147]
	v_lshlrev_b64 v[50:51], 8, v[50:51]
	v_lshl_add_u64 v[56:57], s[0:1], 0, v[148:149]
	v_lshl_add_u64 v[54:55], v[178:179], 0, v[50:51]
	s_waitcnt lgkmcnt(0)
	v_mfma_f32_16x16x32_bf16 v[42:45], v[46:49], v[90:93], v[42:45]
	v_lshlrev_b64 v[46:47], 8, v[56:57]
	ds_read_b128 v[50:53], v228 offset:128
	global_load_dwordx4 v[102:105], v[130:131], off offset:2176 nt
	global_load_dwordx4 v[98:101], v[134:135], off offset:2176 nt
	v_lshl_add_u64 v[56:57], v[178:179], 0, v[46:47]
	ds_read_b128 v[46:49], v228 offset:192
	global_load_dwordx4 v[110:113], v[54:55], off nt
	global_load_dwordx4 v[106:109], v[56:57], off nt
	s_waitcnt lgkmcnt(1)
	v_mfma_f32_16x16x32_bf16 v[42:45], v[50:53], v[86:89], v[42:45]
	s_waitcnt lgkmcnt(0)
	v_mfma_f32_16x16x32_bf16 v[42:45], v[46:49], v[82:85], v[42:45]
	s_and_saveexec_b64 s[46:47], s[4:5]
	s_cbranch_execz .LBB0_711
	s_mov_b64 s[68:69], 0
	v_mov_b32_e32 v46, v221
	v_mov_b32_e32 v47, v220
	v_mov_b32_e32 v48, v219

; DEVI void lds_barrier() { asm volatile("s_waitcnt lgkmcnt(0)\n\ts_barrier" ::: "memory"); }
; DEVI f32x4 mfma16(bf16x8 a, bf16x8 b, f32x4 c) { return __builtin_amdgcn_mfma_f32_16x16x32_bf16(a, b, c, 0, 0, 0); }
; #define MIX_PREF(qq, bb) do { _Pragma("unroll") for (int k = 0; k < 2; ++k) { const int i = tid + k * 512; \
;             pv[bb][k] = *(const u32x4*)(a.proj + (tok0 + (i >> 3)) * 3072 + 1024 + h * 256 + (qq) * 64 + (i & 7) * 8); \
;             pc[bb][k] = *(const u32x4*)(a.states + ((size_t)item * 256 + (qq) * 64 + (i >> 4)) * 128 + (i & 15) * 8); } } while (0)
; template <int KIND>
; DEVI void mix_out_phase(unsigned char* smem, const MixArgs a) {
;     ...
;             lds_barrier();
; #pragma unroll
;             for (int k = 0; k < 2; ++k) { const int i = tid + k * 512; *(u32x4*)(VT + (i >> 3) * VQP + (i & 7) * 8) = pv[0][k]; *(u32x4*)(CT + (i >> 4) * LP + (i & 15) * 8) = pc[0][k]; }
;             lds_barrier();
;             if (qv < 3) MIX_PREF(qv + 1, 0);
; #pragma unroll
;             for (int n = 0; n < 4; ++n) { f32x4 ac = (f32x4){0.f, 0.f, 0.f, 0.f};
; #pragma unroll
;                 for (int ks = 0; ks < 4; ++ks) { const bf16x8 cb = *(const bf16x8*)(CT + (32 * (n >> 1) + 8 * (fr >> 2) + 4 * (n & 1) + (fr & 3)) * LP + ks * 32 + fq * 8); ac = mfma16(cb, qa[ks], ac); }
.LBB0_723:
	s_or_b64 exec, exec, s[46:47]
	s_waitcnt lgkmcnt(0)
	s_barrier
	s_waitcnt vmcnt(3)
	ds_write_b128 v226, v[102:105]
	s_waitcnt vmcnt(1)
	ds_write_b128 v229, v[110:113]
	ds_write_b128 v227, v[98:101]
	s_waitcnt vmcnt(0)
	ds_write_b128 v230, v[106:109]
	s_waitcnt lgkmcnt(0)
	s_barrier
	ds_read_b128 v[98:101], v228
	ds_read_b128 v[102:105], v228 offset:64
	s_or_b32 s0, s14, 0x80
	s_mov_b32 s1, s15
	v_lshl_add_u64 v[106:107], s[0:1], 0, v[146:147]
	v_lshlrev_b64 v[106:107], 8, v[106:107]
	v_lshl_add_u64 v[112:113], s[0:1], 0, v[148:149]
	v_lshl_add_u64 v[110:111], v[178:179], 0, v[106:107]
	s_waitcnt lgkmcnt(1)
	v_mfma_f32_16x16x32_bf16 v[98:101], v[98:101], v[94:97], 0
	ds_read_b128 v[106:109], v228 offset:128
	global_load_dwordx4 v[118:121], v[130:131], off offset:2304 nt
	global_load_dwordx4 v[114:117], v[134:135], off offset:2304 nt
	s_waitcnt lgkmcnt(1)
	v_mfma_f32_16x16x32_bf16 v[98:101], v[102:105], v[90:93], v[98:101]
	v_lshlrev_b64 v[102:103], 8, v[112:113]
	v_lshl_add_u64 v[112:113], v[178:179], 0, v[102:103]
	ds_read_b128 v[102:105], v228 offset:192
	global_load_dwordx4 v[126:129], v[110:111], off nt
	global_load_dwordx4 v[122:125], v[112:113], off nt
	s_waitcnt lgkmcnt(1)
	v_mfma_f32_16x16x32_bf16 v[98:101], v[106:109], v[86:89], v[98:101]
	s_waitcnt lgkmcnt(0)
	v_mfma_f32_16x16x32_bf16 v[98:101], v[102:105], v[82:85], v[98:101]
	s_and_saveexec_b64 s[46:47], s[4:5]
	s_cbranch_execz .LBB0_727
	s_mov_b64 s[68:69], 0
	v_mov_b32_e32 v102, v221
	v_mov_b32_e32 v103, v220
	v_mov_b32_e32 v104, v219

; DEVI void lds_barrier() { asm volatile("s_waitcnt lgkmcnt(0)\n\ts_barrier" ::: "memory"); }
; DEVI f32x4 mfma16(bf16x8 a, bf16x8 b, f32x4 c) { return __builtin_amdgcn_mfma_f32_16x16x32_bf16(a, b, c, 0, 0, 0); }
; #define MIX_PREF(qq, bb) do { _Pragma("unroll") for (int k = 0; k < 2; ++k) { const int i = tid + k * 512; \
;             pv[bb][k] = *(const u32x4*)(a.proj + (tok0 + (i >> 3)) * 3072 + 1024 + h * 256 + (qq) * 64 + (i & 7) * 8); \
;             pc[bb][k] = *(const u32x4*)(a.states + ((size_t)item * 256 + (qq) * 64 + (i >> 4)) * 128 + (i & 15) * 8); } } while (0)
; template <int KIND>
; DEVI void mix_out_phase(unsigned char* smem, const MixArgs a) {
;     ...
;             lds_barrier();
; #pragma unroll
;             for (int k = 0; k < 2; ++k) { const int i = tid + k * 512; *(u32x4*)(VT + (i >> 3) * VQP + (i & 7) * 8) = pv[0][k]; *(u32x4*)(CT + (i >> 4) * LP + (i & 15) * 8) = pc[0][k]; }
;             lds_barrier();
;             if (qv < 3) MIX_PREF(qv + 1, 0);
; #pragma unroll
;             for (int n = 0; n < 4; ++n) { f32x4 ac = (f32x4){0.f, 0.f, 0.f, 0.f};
; #pragma unroll
;                 for (int ks = 0; ks < 4; ++ks) { const bf16x8 cb = *(const bf16x8*)(CT + (32 * (n >> 1) + 8 * (fr >> 2) + 4 * (n & 1) + (fr & 3)) * LP + ks * 32 + fq * 8); ac = mfma16(cb, qa[ks], ac); }
.LBB0_739:
	s_or_b64 exec, exec, s[46:47]
	s_waitcnt lgkmcnt(0)
	s_barrier
	s_waitcnt vmcnt(3)
	ds_write_b128 v226, v[118:121]
	s_waitcnt vmcnt(1)
	ds_write_b128 v229, v[126:129]
	ds_write_b128 v227, v[114:117]
	s_waitcnt vmcnt(0)
	ds_write_b128 v230, v[122:125]
	s_waitcnt lgkmcnt(0)
	s_barrier
	ds_read_b128 v[114:117], v228
	ds_read_b128 v[118:121], v228 offset:64
	s_or_b32 s14, s14, 0xc0
	v_lshl_add_u64 v[122:123], s[14:15], 0, v[146:147]
	v_lshlrev_b64 v[122:123], 8, v[122:123]
	v_lshl_add_u64 v[136:137], v[178:179], 0, v[122:123]
	ds_read_b128 v[126:129], v228 offset:128
	global_load_dwordx4 v[130:133], v[130:131], off offset:2432 nt
	s_nop 0
	global_load_dwordx4 v[122:125], v[134:135], off offset:2432 nt
	s_waitcnt lgkmcnt(2)
	v_mfma_f32_16x16x32_bf16 v[114:117], v[114:117], v[94:97], 0
	v_lshl_add_u64 v[134:135], s[14:15], 0, v[148:149]
	s_waitcnt lgkmcnt(1)
	v_mfma_f32_16x16x32_bf16 v[114:117], v[118:121], v[90:93], v[114:117]
	v_lshlrev_b64 v[118:119], 8, v[134:135]
	v_lshl_add_u64 v[134:135], v[178:179], 0, v[118:119]
	ds_read_b128 v[118:121], v228 offset:192
	global_load_dwordx4 v[142:145], v[136:137], off nt
	global_load_dwordx4 v[138:141], v[134:135], off nt
	s_waitcnt lgkmcnt(1)
	v_mfma_f32_16x16x32_bf16 v[114:117], v[126:129], v[86:89], v[114:117]
	s_waitcnt lgkmcnt(0)
	v_mfma_f32_16x16x32_bf16 v[114:117], v[118:121], v[82:85], v[114:117]
	s_and_saveexec_b64 s[14:15], s[4:5]
	s_cbranch_execz .LBB0_743
	s_mov_b64 s[46:47], 0
	v_mov_b32_e32 v118, v221
	v_mov_b32_e32 v119, v220
	v_mov_b32_e32 v120, v219

.LBB0_776:
	s_ashr_i32 s69, s68, 31
	s_lshr_b32 s0, s69, 26
	s_add_i32 s0, s68, s0
	s_and_b32 s1, s0, 0xffffffc0
	s_sub_i32 s6, s68, s1
	s_bfe_u32 s16, s0, 0x20006
	s_ashr_i32 s0, s0, 8
	s_ashr_i32 s1, s0, 31
	s_lshl_b32 s7, s6, 7
	s_lshl_b64 s[0:1], s[0:1], 13
	s_ashr_i32 s11, s7, 31
	s_add_u32 s10, s0, s7
	s_addc_u32 s11, s1, s11
	s_cmp_eq_u32 s6, 0
	v_readlane_b32 s0, v254, 19
	s_cselect_b64 s[12:13], -1, 0
	v_readlane_b32 s1, v254, 20
	v_readlane_b32 s6, v254, 17
	s_and_b64 s[0:1], s[0:1], s[12:13]
	v_readlane_b32 s7, v254, 18
	s_lshl_b32 s17, s16, 7
	s_nor_b64 s[0:1], s[6:7], s[0:1]
	v_mov_b32_e32 v18, 0
	v_lshlrev_b32_e32 v2, 1, v118
	v_lshlrev_b32_e32 v0, 1, v120
	v_mov_b32_e32 v22, 0
	v_mov_b32_e32 v23, 0
	v_mov_b32_e32 v24, 0
	v_mov_b32_e32 v25, 0
	s_and_saveexec_b64 s[14:15], s[0:1]
	s_cbranch_execz .LBB0_778
	v_lshl_add_u64 v[4:5], s[10:11], 0, v[128:129]
	v_mov_b64_e32 v[6:7], s[28:29]
	v_mad_u64_u32 v[6:7], s[0:1], v4, s95, v[6:7]
	v_mad_i32_i24 v7, v5, s95, v7
	v_mov_b32_e32 v3, v9
	v_lshl_add_u64 v[4:5], v[6:7], 0, v[2:3]
	s_lshl_b32 s66, s17, 1
	v_lshl_add_u64 v[4:5], v[4:5], 0, s[66:67]
	v_mov_b32_e32 v1, v9
	v_lshl_add_u64 v[4:5], v[4:5], 0, v[0:1]
	v_add_co_u32_e32 v4, vcc, 0xffffc000, v4
	s_nop 1
	v_addc_co_u32_e32 v5, vcc, -1, v5, vcc
	global_load_dwordx4 v[22:25], v[4:5], off offset:-2048 nt
.LBB0_778:
	s_or_b64 exec, exec, s[14:15]
	v_readlane_b32 s0, v254, 23
	v_readlane_b32 s1, v254, 24
	v_readlane_b32 s6, v254, 21
	s_and_b64 s[0:1], s[0:1], s[12:13]
	v_readlane_b32 s7, v254, 22
	s_nor_b64 s[0:1], s[6:7], s[0:1]
	v_mov_b32_e32 v26, 0
	v_mov_b32_e32 v27, 0
	v_mov_b32_e32 v28, 0
	v_mov_b32_e32 v29, 0
	s_and_saveexec_b64 s[14:15], s[0:1]
	s_cbranch_execz .LBB0_780
	v_lshl_add_u64 v[4:5], s[10:11], 0, v[130:131]
	v_mov_b64_e32 v[6:7], s[28:29]
	v_mad_u64_u32 v[6:7], s[0:1], v4, s95, v[6:7]
	v_mad_i32_i24 v7, v5, s95, v7
	v_mov_b32_e32 v3, v9
	v_lshl_add_u64 v[4:5], v[6:7], 0, v[2:3]
	s_lshl_b32 s66, s17, 1
	v_lshl_add_u64 v[4:5], v[4:5], 0, s[66:67]
	v_mov_b32_e32 v1, v9
	v_lshl_add_u64 v[4:5], v[4:5], 0, v[0:1]
	v_add_co_u32_e32 v4, vcc, 0xffffc000, v4
	s_nop 1
	v_addc_co_u32_e32 v5, vcc, -1, v5, vcc
	global_load_dwordx4 v[26:29], v[4:5], off offset:-2048 nt
.LBB0_780:
	s_or_b64 exec, exec, s[14:15]
	v_readlane_b32 s0, v254, 27
	v_readlane_b32 s1, v254, 28
	v_readlane_b32 s6, v254, 25
	s_and_b64 s[0:1], s[0:1], s[12:13]
	v_readlane_b32 s7, v254, 26
	s_nor_b64 s[0:1], s[6:7], s[0:1]
	v_mov_b32_e32 v19, 0
	v_mov_b32_e32 v20, 0
	v_mov_b32_e32 v21, 0
	s_and_saveexec_b64 s[14:15], s[0:1]
	s_cbranch_execz .LBB0_782
	v_lshl_add_u64 v[4:5], s[10:11], 0, v[132:133]
	v_mov_b64_e32 v[6:7], s[28:29]
	v_mad_u64_u32 v[6:7], s[0:1], v4, s95, v[6:7]
	v_mad_i32_i24 v7, v5, s95, v7
	v_mov_b32_e32 v3, v9
	v_lshl_add_u64 v[4:5], v[6:7], 0, v[2:3]
	s_lshl_b32 s66, s17, 1
	v_lshl_add_u64 v[4:5], v[4:5], 0, s[66:67]
	v_mov_b32_e32 v1, v9
	v_lshl_add_u64 v[4:5], v[4:5], 0, v[0:1]
	v_add_co_u32_e32 v4, vcc, 0xffffc000, v4
	s_nop 1
	v_addc_co_u32_e32 v5, vcc, -1, v5, vcc
	global_load_dwordx4 v[18:21], v[4:5], off offset:-2048 nt
.LBB0_782:
	s_or_b64 exec, exec, s[14:15]
	v_readlane_b32 s0, v254, 31
	v_readlane_b32 s1, v254, 32
	v_readlane_b32 s6, v254, 29
	s_and_b64 s[0:1], s[0:1], s[12:13]
	v_readlane_b32 s7, v254, 30
	s_nor_b64 s[0:1], s[6:7], s[0:1]
	v_mov_b32_e32 v30, 0
	v_mov_b32_e32 v34, 0
	v_mov_b32_e32 v35, 0
	v_mov_b32_e32 v36, 0
	v_mov_b32_e32 v37, 0
	s_and_saveexec_b64 s[14:15], s[0:1]
	s_cbranch_execz .LBB0_784
	v_lshl_add_u64 v[4:5], s[10:11], 0, v[134:135]
	v_mov_b64_e32 v[6:7], s[28:29]
	v_mad_u64_u32 v[6:7], s[0:1], v4, s95, v[6:7]
	v_mad_i32_i24 v7, v5, s95, v7
	v_mov_b32_e32 v3, v9
	v_lshl_add_u64 v[4:5], v[6:7], 0, v[2:3]
	s_lshl_b32 s66, s17, 1
	v_lshl_add_u64 v[4:5], v[4:5], 0, s[66:67]
	v_mov_b32_e32 v1, v9
	v_lshl_add_u64 v[4:5], v[4:5], 0, v[0:1]
	v_add_co_u32_e32 v4, vcc, 0xffffc000, v4
	s_nop 1
	v_addc_co_u32_e32 v5, vcc, -1, v5, vcc
	global_load_dwordx4 v[34:37], v[4:5], off offset:-2048 nt
.LBB0_784:
	s_or_b64 exec, exec, s[14:15]
	v_readlane_b32 s0, v254, 35
	v_readlane_b32 s1, v254, 36
	v_readlane_b32 s6, v254, 33
	s_and_b64 s[0:1], s[0:1], s[12:13]
	v_readlane_b32 s7, v254, 34
	s_nor_b64 s[0:1], s[6:7], s[0:1]
	v_mov_b32_e32 v31, 0
	v_mov_b32_e32 v32, 0
	v_mov_b32_e32 v33, 0
	s_and_saveexec_b64 s[14:15], s[0:1]
	s_cbranch_execz .LBB0_786
	v_lshl_add_u64 v[4:5], s[10:11], 0, v[136:137]
	v_mov_b64_e32 v[6:7], s[28:29]
	v_mad_u64_u32 v[6:7], s[0:1], v4, s95, v[6:7]
	v_mad_i32_i24 v7, v5, s95, v7
	v_mov_b32_e32 v3, v9
	v_lshl_add_u64 v[4:5], v[6:7], 0, v[2:3]
	s_lshl_b32 s66, s17, 1
	v_lshl_add_u64 v[4:5], v[4:5], 0, s[66:67]
	v_mov_b32_e32 v1, v9
	v_lshl_add_u64 v[4:5], v[4:5], 0, v[0:1]
	v_add_co_u32_e32 v4, vcc, 0xffffc000, v4
	s_nop 1
	v_addc_co_u32_e32 v5, vcc, -1, v5, vcc
	global_load_dwordx4 v[30:33], v[4:5], off offset:-2048 nt
.LBB0_786:
	s_or_b64 exec, exec, s[14:15]
	v_readlane_b32 s0, v254, 39
	v_readlane_b32 s1, v254, 40
	v_readlane_b32 s6, v254, 37
	s_and_b64 s[0:1], s[0:1], s[12:13]
	v_readlane_b32 s7, v254, 38
	s_nor_b64 s[0:1], s[6:7], s[0:1]
	v_mov_b32_e32 v38, 0
	v_mov_b32_e32 v42, 0
	v_mov_b32_e32 v43, 0
	v_mov_b32_e32 v44, 0
	v_mov_b32_e32 v45, 0
	s_and_saveexec_b64 s[14:15], s[0:1]
	s_cbranch_execz .LBB0_788
	v_lshl_add_u64 v[4:5], s[10:11], 0, v[138:139]
	v_mov_b64_e32 v[6:7], s[28:29]
	v_mad_u64_u32 v[6:7], s[0:1], v4, s95, v[6:7]
	v_mad_i32_i24 v7, v5, s95, v7
	v_mov_b32_e32 v3, v9
	v_lshl_add_u64 v[4:5], v[6:7], 0, v[2:3]
	s_lshl_b32 s66, s17, 1
	v_lshl_add_u64 v[4:5], v[4:5], 0, s[66:67]
	v_mov_b32_e32 v1, v9
	v_lshl_add_u64 v[4:5], v[4:5], 0, v[0:1]
	v_add_co_u32_e32 v4, vcc, 0xffffc000, v4
	s_nop 1
	v_addc_co_u32_e32 v5, vcc, -1, v5, vcc
	global_load_dwordx4 v[42:45], v[4:5], off offset:-2048 nt
.LBB0_788:
	s_or_b64 exec, exec, s[14:15]
	v_readlane_b32 s0, v254, 5
	v_readlane_b32 s1, v254, 6
	v_readlane_b32 s6, v254, 41
	s_and_b64 s[0:1], s[0:1], s[12:13]
	v_readlane_b32 s7, v254, 42
	s_nor_b64 s[0:1], s[6:7], s[0:1]
	v_mov_b32_e32 v39, 0
	v_mov_b32_e32 v40, 0
	v_mov_b32_e32 v41, 0
	s_and_saveexec_b64 s[14:15], s[0:1]
	s_cbranch_execz .LBB0_790
	v_lshl_add_u64 v[4:5], s[10:11], 0, v[140:141]
	v_mov_b64_e32 v[6:7], s[28:29]
	v_mad_u64_u32 v[6:7], s[0:1], v4, s95, v[6:7]
	v_mad_i32_i24 v7, v5, s95, v7
	v_mov_b32_e32 v3, v9
	v_lshl_add_u64 v[4:5], v[6:7], 0, v[2:3]
	s_lshl_b32 s66, s17, 1
	v_lshl_add_u64 v[4:5], v[4:5], 0, s[66:67]
	v_mov_b32_e32 v1, v9
	v_lshl_add_u64 v[4:5], v[4:5], 0, v[0:1]
	v_add_co_u32_e32 v4, vcc, 0xffffc000, v4
	s_nop 1
	v_addc_co_u32_e32 v5, vcc, -1, v5, vcc
	global_load_dwordx4 v[38:41], v[4:5], off offset:-2048 nt
.LBB0_790:
	s_or_b64 exec, exec, s[14:15]
	v_readlane_b32 s0, v254, 43
	v_readlane_b32 s1, v254, 44
	v_readlane_b32 s6, v254, 3
	s_and_b64 s[0:1], s[0:1], s[12:13]
	v_readlane_b32 s7, v254, 4
	s_nor_b64 s[0:1], s[6:7], s[0:1]
	v_mov_b32_e32 v46, 0
	v_mov_b32_e32 v50, 0
	v_mov_b32_e32 v51, 0
	v_mov_b32_e32 v52, 0
	v_mov_b32_e32 v53, 0
	s_and_saveexec_b64 s[14:15], s[0:1]
	s_cbranch_execz .LBB0_792
	v_lshl_add_u64 v[4:5], s[10:11], 0, v[142:143]
	v_mov_b64_e32 v[6:7], s[28:29]
	v_mad_u64_u32 v[6:7], s[0:1], v4, s95, v[6:7]
	v_mad_i32_i24 v7, v5, s95, v7
	v_mov_b32_e32 v3, v9
	v_lshl_add_u64 v[4:5], v[6:7], 0, v[2:3]
	s_lshl_b32 s66, s17, 1
	v_lshl_add_u64 v[4:5], v[4:5], 0, s[66:67]
	v_mov_b32_e32 v1, v9
	v_lshl_add_u64 v[4:5], v[4:5], 0, v[0:1]
	v_add_co_u32_e32 v4, vcc, 0xffffc000, v4
	s_nop 1
	v_addc_co_u32_e32 v5, vcc, -1, v5, vcc
	global_load_dwordx4 v[50:53], v[4:5], off offset:-2048 nt
.LBB0_792:
	s_or_b64 exec, exec, s[14:15]
	v_readlane_b32 s0, v254, 47
	v_readlane_b32 s1, v254, 48
	v_readlane_b32 s6, v254, 45
	s_and_b64 s[0:1], s[0:1], s[12:13]
	v_readlane_b32 s7, v254, 46
	s_nor_b64 s[0:1], s[6:7], s[0:1]
	v_mov_b32_e32 v47, 0
	v_mov_b32_e32 v48, 0
	v_mov_b32_e32 v49, 0
	s_and_saveexec_b64 s[12:13], s[0:1]
	s_cbranch_execz .LBB0_794
	v_lshl_add_u64 v[4:5], s[10:11], 0, v[144:145]
	v_mov_b64_e32 v[6:7], s[28:29]
	v_mad_u64_u32 v[6:7], s[0:1], v4, s95, v[6:7]
	v_mad_i32_i24 v7, v5, s95, v7
	v_mov_b32_e32 v3, v9
	v_lshl_add_u64 v[2:3], v[6:7], 0, v[2:3]
	s_lshl_b32 s66, s17, 1
	v_lshl_add_u64 v[2:3], v[2:3], 0, s[66:67]
	v_mov_b32_e32 v1, v9
	v_lshl_add_u64 v[0:1], v[2:3], 0, v[0:1]
	v_add_co_u32_e32 v0, vcc, 0xffffc000, v0
	s_nop 1
	v_addc_co_u32_e32 v1, vcc, -1, v1, vcc
	global_load_dwordx4 v[46:49], v[0:1], off offset:-2048 nt

; DEVI void lds_barrier() { asm volatile("s_waitcnt lgkmcnt(0)\n\ts_barrier" ::: "memory"); }
; #define MIX_PREF(qq, bb) do { _Pragma("unroll") for (int k = 0; k < 2; ++k) { const int i = tid + k * 512; \
;             pv[bb][k] = *(const u32x4*)(a.proj + (tok0 + (i >> 3)) * 3072 + 1024 + h * 256 + (qq) * 64 + (i & 7) * 8); \
;             pc[bb][k] = *(const u32x4*)(a.states + ((size_t)item * 256 + (qq) * 64 + (i >> 4)) * 128 + (i & 15) * 8); } } while (0)
; template <int KIND>
; DEVI void mix_out_phase(unsigned char* smem, const MixArgs a) {
;     ...
;         const int c = item % NCH, bh = item / NCH, h = bh & 3, b = bh >> 2; const size_t tok0 = (size_t)b * SEQ + c * CH;
;         if (KIND == 0) OUT_PREF(item);
;         const size_t tok = tok0 + trow;
;         u32x4 pv[1][2], pc[1][2];
;     ...
;         MIX_PREF(0, 0);
;         lds_barrier();
;         if (KIND == 0) {
; #pragma unroll
;             for (int k = 0; k < 9; ++k) { const int q = tid + k * 512; if (q < 131 * 32) *(u32x4*)(RAW + ((q >> 4) & 1) * (131 * 128) + (q >> 5) * 128 + (q & 15) * 8) = prq[k]; }
.LBB0_796:
	s_or_b64 exec, exec, s[12:13]
	v_lshlrev_b64 v[0:1], 16, v[66:67]
	v_lshl_add_u64 v[10:11], v[124:125], 0, v[0:1]
	v_lshl_add_u64 v[0:1], s[10:11], 0, v[146:147]
	v_mov_b64_e32 v[2:3], s[28:29]
	v_mad_u64_u32 v[4:5], s[0:1], v0, s95, v[2:3]
	v_mad_i32_i24 v5, v1, s95, v5
	s_lshl_b32 s66, s16, 9
	v_lshl_add_u64 v[0:1], v[4:5], 0, s[66:67]
	v_lshl_add_u64 v[98:99], v[0:1], 0, v[8:9]
	v_lshl_add_u64 v[0:1], s[10:11], 0, v[152:153]
	v_mad_u64_u32 v[2:3], s[0:1], v0, s95, v[2:3]
	v_mad_i32_i24 v3, v1, s95, v3
	v_lshl_add_u64 v[12:13], v[10:11], 0, v[150:151]
	v_lshl_add_u64 v[0:1], v[2:3], 0, s[66:67]
	v_lshl_add_u64 v[10:11], v[10:11], 0, v[178:179]
	v_lshl_add_u64 v[100:101], v[0:1], 0, v[8:9]
	global_load_dwordx4 v[4:7], v[98:99], off offset:2048 nt
	global_load_dwordx4 v[0:3], v[100:101], off offset:2048 nt
	global_load_dwordx4 v[14:17], v[12:13], off nt
	s_nop 0
	global_load_dwordx4 v[10:13], v[10:11], off nt
	s_waitcnt lgkmcnt(0)
	s_barrier
	s_mov_b64 s[6:7], exec
	v_readlane_b32 s0, v254, 49
	v_readlane_b32 s1, v254, 50
	s_and_b64 s[0:1], s[6:7], s[0:1]
	s_mov_b64 exec, s[0:1]
	s_cbranch_execz .LBB0_806
	s_waitcnt vmcnt(4)
	ds_write_b128 v214, v[22:25]
	s_or_b64 exec, exec, s[6:7]
	s_and_saveexec_b64 s[6:7], s[86:87]
	s_cbranch_execnz .LBB0_807

; DEVI float bf2f(u16 b) { return __uint_as_float(((unsigned)b) << 16); }
; DEVI unsigned cvt_pk(float lo, float hi) { f32v2_t f = {lo, hi}; bf16v2_t v = __builtin_convertvector(f, bf16v2_t); return __builtin_bit_cast(unsigned, v); }
; DEVI float siluf_(float x) { return x * __builtin_amdgcn_rcpf(1.f + __expf(-x)); }
; DEVI void mlstm_conv8_lds(const u16* raw, const float* convw, int t, int c8, int ch0, float* out) {
;     float accv[8];
; #pragma unroll
;     for (int i = 0; i < 8; ++i) accv[i] = 0.f;
; #pragma unroll
;     for (int j = 0; j < 4; ++j) { const bf16x8 x = *(const bf16x8*)(raw + (t + j) * 128 + c8);
;         const f32x4 w0 = *(const f32x4*)(convw + j * 1024 + ch0), w1 = *(const f32x4*)(convw + j * 1024 + ch0 + 4);
; #pragma unroll
;         for (int i = 0; i < 4; ++i) { accv[i] += w0[i] * bf2f((u16)x[i]); accv[4 + i] += w1[i] * bf2f((u16)x[4 + i]); } }
; #pragma unroll
;     for (int i = 0; i < 8; ++i) out[i] = siluf_(accv[i]);
; }
; template <int KIND>
; DEVI void mix_out_phase(unsigned char* smem, const MixArgs a) {
;     ...
; #pragma unroll 2
;             for (int i = tid; i < 128 * 32; i += 512) { const int t = (i >> 4) & 127, c8 = (i & 15) * 8, isk = i >> 11; float v[8];
;                 mlstm_conv8_lds(RAW + isk * (131 * 128), a.convw, t, c8, isk * 512 + h * 128 + c8, v); const float sc = isk ? 1.f : 0.08838834764831845f;
;                 u32x4 w; w.x = cvt_pk(v[0] * sc, v[1] * sc); w.y = cvt_pk(v[2] * sc, v[3] * sc); w.z = cvt_pk(v[4] * sc, v[5] * sc); w.w = cvt_pk(v[6] * sc, v[7] * sc);
;                 *(u32x4*)((isk ? KS : QS) + t * LP + c8) = w; }
.LBB0_818:
	s_or_b64 exec, exec, s[12:13]
	s_mov_b64 s[12:13], exec
	v_readlane_b32 s0, v254, 13
	v_readlane_b32 s1, v254, 14
	s_and_b64 s[0:1], s[12:13], s[0:1]
	s_mov_b64 exec, s[0:1]
	s_cbranch_execz .LBB0_824
	s_mov_b64 s[18:19], 0x3000
	s_mov_b64 s[6:7], 0x1000
	s_waitcnt vmcnt(4)
	v_mov_b32_e32 v22, v114
	s_mov_b64 s[14:15], exec
	v_readlane_b32 s0, v254, 63
	v_readlane_b32 s1, v250, 0
	s_and_b64 s[0:1], s[14:15], s[0:1]
	s_mov_b64 exec, s[0:1]
	s_cbranch_execz .LBB0_821
	v_or_b32_e32 v18, s17, v223
	v_ashrrev_i32_e32 v19, 31, v18
	v_lshl_add_u64 v[22:23], v[18:19], 2, s[36:37]
	v_add_co_u32_e32 v20, vcc, 0x1000, v22
	ds_read_b128 v[38:41], v235
	global_load_dwordx4 v[42:45], v[22:23], off offset:16 nt
	global_load_dwordx4 v[50:53], v[22:23], off nt
	v_addc_co_u32_e32 v21, vcc, 0, v23, vcc
	v_add_co_u32_e32 v24, vcc, s53, v22
	ds_read_b128 v[30:33], v235 offset:256
	v_lshl_add_u64 v[18:19], v[22:23], 0, s[6:7]
	global_load_dwordx4 v[54:57], v[20:21], off nt
	global_load_dwordx4 v[46:49], v[18:19], off offset:16 nt
	v_addc_co_u32_e32 v25, vcc, 0, v23, vcc
	ds_read_b128 v[34:37], v235 offset:512
	v_lshl_add_u64 v[18:19], v[22:23], 0, s[74:75]
	global_load_dwordx4 v[58:61], v[24:25], off offset:-4096 nt
	global_load_dwordx4 v[26:29], v[18:19], off offset:16 nt
	v_lshl_add_u64 v[22:23], v[22:23], 0, s[18:19]
	ds_read_b128 v[18:21], v235 offset:768
	global_load_dwordx4 v[62:65], v[24:25], off nt
	s_nop 0
	global_load_dwordx4 v[22:25], v[22:23], off offset:16 nt
	s_waitcnt lgkmcnt(3)
	v_and_b32_e32 v69, 0xffff0000, v38
	v_lshlrev_b32_e32 v68, 16, v38
	s_waitcnt vmcnt(6)
	v_pk_fma_f32 v[50:51], v[50:51], v[68:69], 0 op_sel_hi:[1,1,0]
	s_waitcnt lgkmcnt(2)
	v_and_b32_e32 v69, 0xffff0000, v30
	v_lshlrev_b32_e32 v68, 16, v30
	s_waitcnt vmcnt(5)
	v_pk_fma_f32 v[50:51], v[54:55], v[68:69], v[50:51]
	s_waitcnt lgkmcnt(1)
	v_and_b32_e32 v55, 0xffff0000, v34
	v_lshlrev_b32_e32 v54, 16, v34
	s_waitcnt lgkmcnt(0)
	v_lshlrev_b32_e32 v34, 16, v19
	s_waitcnt vmcnt(3)
	v_pk_fma_f32 v[50:51], v[58:59], v[54:55], v[50:51]
	v_and_b32_e32 v55, 0xffff0000, v18
	v_lshlrev_b32_e32 v54, 16, v18
	s_waitcnt vmcnt(1)
	v_pk_fma_f32 v[50:51], v[62:63], v[54:55], v[50:51]
	s_nop 0
	v_mul_f32_e32 v18, 0xbfb8aa3b, v50
	v_exp_f32_e32 v18, v18
	s_nop 0
	v_add_f32_e32 v18, 1.0, v18
	v_rcp_f32_e32 v54, v18
	v_mul_f32_e32 v18, 0xbfb8aa3b, v51
	v_exp_f32_e32 v18, v18
	s_nop 0
	v_add_f32_e32 v18, 1.0, v18
	v_rcp_f32_e32 v55, v18
	s_nop 0
	v_pk_mul_f32 v[50:51], v[50:51], v[54:55]
	s_nop 0
	v_pk_mul_f32 v[50:51], v[180:181], v[50:51]
	s_nop 0
	v_cvt_pk_bf16_f32 v18, v50, v51
	v_and_b32_e32 v51, 0xffff0000, v39
	v_lshlrev_b32_e32 v50, 16, v39
	v_pk_fma_f32 v[38:39], v[52:53], v[50:51], 0 op_sel_hi:[1,1,0]
	v_and_b32_e32 v51, 0xffff0000, v31
	v_lshlrev_b32_e32 v50, 16, v31
	v_pk_fma_f32 v[30:31], v[56:57], v[50:51], v[38:39]
	v_and_b32_e32 v39, 0xffff0000, v35
	v_lshlrev_b32_e32 v38, 16, v35
	v_pk_fma_f32 v[30:31], v[60:61], v[38:39], v[30:31]
	v_and_b32_e32 v35, 0xffff0000, v19
	v_pk_fma_f32 v[30:31], v[64:65], v[34:35], v[30:31]
	s_nop 0
	v_mul_f32_e32 v19, 0xbfb8aa3b, v30
	v_exp_f32_e32 v19, v19
	s_nop 0
	v_add_f32_e32 v19, 1.0, v19
	v_rcp_f32_e32 v34, v19
	v_mul_f32_e32 v19, 0xbfb8aa3b, v31
	v_exp_f32_e32 v19, v19
	s_nop 0
	v_add_f32_e32 v19, 1.0, v19
	v_rcp_f32_e32 v35, v19
	s_nop 0
	v_pk_mul_f32 v[30:31], v[30:31], v[34:35]
	s_nop 0
	v_pk_mul_f32 v[30:31], v[180:181], v[30:31]
	v_and_b32_e32 v35, 0xffff0000, v32
	v_cvt_pk_bf16_f32 v19, v30, v31
	v_and_b32_e32 v31, 0xffff0000, v40
	v_lshlrev_b32_e32 v30, 16, v40
	v_pk_fma_f32 v[30:31], v[42:43], v[30:31], 0 op_sel_hi:[1,1,0]
	v_lshlrev_b32_e32 v34, 16, v32
	v_pk_fma_f32 v[30:31], v[46:47], v[34:35], v[30:31]
	v_and_b32_e32 v35, 0xffff0000, v36
	v_lshlrev_b32_e32 v34, 16, v36
	v_pk_fma_f32 v[26:27], v[26:27], v[34:35], v[30:31]
	v_and_b32_e32 v31, 0xffff0000, v20
	v_lshlrev_b32_e32 v30, 16, v20
	s_waitcnt vmcnt(0)
	v_pk_fma_f32 v[22:23], v[22:23], v[30:31], v[26:27]
	s_nop 0
	v_mul_f32_e32 v20, 0xbfb8aa3b, v22
	v_exp_f32_e32 v20, v20
	s_nop 0
	v_add_f32_e32 v20, 1.0, v20
	v_rcp_f32_e32 v26, v20
	v_mul_f32_e32 v20, 0xbfb8aa3b, v23
	v_exp_f32_e32 v20, v20
	s_nop 0
	v_add_f32_e32 v20, 1.0, v20
	v_rcp_f32_e32 v27, v20
	s_nop 0
	v_pk_mul_f32 v[22:23], v[22:23], v[26:27]
	s_nop 0
	v_pk_mul_f32 v[22:23], v[180:181], v[22:23]
	v_and_b32_e32 v27, 0xffff0000, v33
	v_cvt_pk_bf16_f32 v20, v22, v23
	v_and_b32_e32 v23, 0xffff0000, v41
	v_lshlrev_b32_e32 v22, 16, v41
	v_pk_fma_f32 v[22:23], v[44:45], v[22:23], 0 op_sel_hi:[1,1,0]
	v_lshlrev_b32_e32 v26, 16, v33
	v_pk_fma_f32 v[22:23], v[48:49], v[26:27], v[22:23]
	v_and_b32_e32 v27, 0xffff0000, v37
	v_lshlrev_b32_e32 v26, 16, v37
	v_pk_fma_f32 v[22:23], v[28:29], v[26:27], v[22:23]
	v_and_b32_e32 v27, 0xffff0000, v21
	v_lshlrev_b32_e32 v26, 16, v21
	v_pk_fma_f32 v[22:23], v[24:25], v[26:27], v[22:23]
	s_nop 0
	v_mul_f32_e32 v21, 0xbfb8aa3b, v22
	v_exp_f32_e32 v21, v21
	s_nop 0
	v_add_f32_e32 v21, 1.0, v21
	v_rcp_f32_e32 v24, v21
	v_mul_f32_e32 v21, 0xbfb8aa3b, v23
	v_exp_f32_e32 v21, v21
	s_nop 0
	v_add_f32_e32 v21, 1.0, v21
	v_rcp_f32_e32 v25, v21
	s_nop 0
	v_pk_mul_f32 v[22:23], v[22:23], v[24:25]
	s_nop 0
	v_pk_mul_f32 v[22:23], v[180:181], v[22:23]
	s_nop 0
	v_cvt_pk_bf16_f32 v21, v22, v23
	v_mov_b32_e32 v22, v213
	ds_write_b128 v224, v[18:21]

; DEVI float bf2f(u16 b) { return __uint_as_float(((unsigned)b) << 16); }
; DEVI unsigned cvt_pk(float lo, float hi) { f32v2_t f = {lo, hi}; bf16v2_t v = __builtin_convertvector(f, bf16v2_t); return __builtin_bit_cast(unsigned, v); }
; DEVI float siluf_(float x) { return x * __builtin_amdgcn_rcpf(1.f + __expf(-x)); }
; DEVI void mlstm_conv8_lds(const u16* raw, const float* convw, int t, int c8, int ch0, float* out) {
;     float accv[8];
; #pragma unroll
;     for (int i = 0; i < 8; ++i) accv[i] = 0.f;
; #pragma unroll
;     for (int j = 0; j < 4; ++j) { const bf16x8 x = *(const bf16x8*)(raw + (t + j) * 128 + c8);
;         const f32x4 w0 = *(const f32x4*)(convw + j * 1024 + ch0), w1 = *(const f32x4*)(convw + j * 1024 + ch0 + 4);
; #pragma unroll
;         for (int i = 0; i < 4; ++i) { accv[i] += w0[i] * bf2f((u16)x[i]); accv[4 + i] += w1[i] * bf2f((u16)x[4 + i]); } }
; #pragma unroll
;     for (int i = 0; i < 8; ++i) out[i] = siluf_(accv[i]);
; }
; template <int KIND>
; DEVI void mix_out_phase(unsigned char* smem, const MixArgs a) {
;     ...
; #pragma unroll 2
;             for (int i = tid; i < 128 * 32; i += 512) { const int t = (i >> 4) & 127, c8 = (i & 15) * 8, isk = i >> 11; float v[8];
;                 mlstm_conv8_lds(RAW + isk * (131 * 128), a.convw, t, c8, isk * 512 + h * 128 + c8, v); const float sc = isk ? 1.f : 0.08838834764831845f;
;                 u32x4 w; w.x = cvt_pk(v[0] * sc, v[1] * sc); w.y = cvt_pk(v[2] * sc, v[3] * sc); w.z = cvt_pk(v[4] * sc, v[5] * sc); w.w = cvt_pk(v[6] * sc, v[7] * sc);
;                 *(u32x4*)((isk ? KS : QS) + t * LP + c8) = w; }
.LBB0_823:
	v_ashrrev_i32_e32 v18, 11, v22
	v_mov_b32_e32 v26, s96
	v_and_b32_e32 v25, 0x78, v23
	v_mad_i32_i24 v20, v18, s18, v26
	v_lshlrev_b32_e32 v18, 9, v18
	v_or3_b32 v18, v18, s17, v25
	v_bfe_u32 v27, v22, 4, 7
	v_ashrrev_i32_e32 v19, 31, v18
	v_lshlrev_b32_e32 v24, 1, v25
	v_lshl_add_u64 v[64:65], v[18:19], 2, s[36:37]
	v_lshlrev_b32_e32 v18, 8, v27
	v_add3_u32 v60, v20, v24, v18
	ds_read_b128 v[68:71], v60
	ds_read_b128 v[72:75], v60 offset:256
	ds_read_b128 v[76:79], v60 offset:512
	ds_read_b128 v[80:83], v60 offset:768
	ds_read_b128 v[188:191], v60 offset:8192
	ds_read_b128 v[192:195], v60 offset:8448
	ds_read_b128 v[196:199], v60 offset:8704
	ds_read_b128 v[200:203], v60 offset:8960
	v_readfirstlane_b32 s100, v22
	s_bitcmp1_b32 s100, 10
	s_cbranch_scc1 .Lcw1_skip
	v_lshl_add_u64 v[84:85], v[64:65], 0, s[26:27]
	v_lshl_add_u64 v[86:87], v[64:65], 0, s[74:75]
	v_lshl_add_u64 v[88:89], v[64:65], 0, s[38:39]
	global_load_dwordx4 v[28:31], v[64:65], off nt
	global_load_dwordx4 v[32:35], v[64:65], off offset:16 nt
	global_load_dwordx4 v[36:39], v[84:85], off nt
	global_load_dwordx4 v[40:43], v[84:85], off offset:16 nt
	global_load_dwordx4 v[44:47], v[86:87], off nt
	global_load_dwordx4 v[48:51], v[86:87], off offset:16 nt
	global_load_dwordx4 v[52:55], v[88:89], off nt
	global_load_dwordx4 v[56:59], v[88:89], off offset:16 nt

; DEVI void lds_barrier() { asm volatile("s_waitcnt lgkmcnt(0)\n\ts_barrier" ::: "memory"); }
; DEVI f32x4 mfma16(bf16x8 a, bf16x8 b, f32x4 c) { return __builtin_amdgcn_mfma_f32_16x16x32_bf16(a, b, c, 0, 0, 0); }
; #define MIX_PREF(qq, bb) do { _Pragma("unroll") for (int k = 0; k < 2; ++k) { const int i = tid + k * 512; \
;             pv[bb][k] = *(const u32x4*)(a.proj + (tok0 + (i >> 3)) * 3072 + 1024 + h * 256 + (qq) * 64 + (i & 7) * 8); \
;             pc[bb][k] = *(const u32x4*)(a.states + ((size_t)item * 256 + (qq) * 64 + (i >> 4)) * 128 + (i & 15) * 8); } } while (0)
; template <int KIND>
; DEVI void mix_out_phase(unsigned char* smem, const MixArgs a) {
;     ...
;         bf16x8 gtv[8];
; #pragma unroll
;         for (int i = 0; i < 8; ++i) gtv[i] = *(const bf16x8*)(a.proj + tok * 3072 + 2048 + h * 256 + i * 32 + fq * 8);
;         f32x4 o[16];
; #pragma unroll
;         for (int qv = 0; qv < 4; ++qv) {
;             lds_barrier();
; #pragma unroll
;             for (int k = 0; k < 2; ++k) { const int i = tid + k * 512; *(u32x4*)(VT + (i >> 3) * VQP + (i & 7) * 8) = pv[0][k]; *(u32x4*)(CT + (i >> 4) * LP + (i & 15) * 8) = pc[0][k]; }
;             lds_barrier();
;             if (qv < 3) MIX_PREF(qv + 1, 0);
; #pragma unroll
;             for (int n = 0; n < 4; ++n) { f32x4 ac = (f32x4){0.f, 0.f, 0.f, 0.f};
; #pragma unroll
;                 for (int ks = 0; ks < 4; ++ks) { const bf16x8 cb = *(const bf16x8*)(CT + (32 * (n >> 1) + 8 * (fr >> 2) + 4 * (n & 1) + (fr & 3)) * LP + ks * 32 + fq * 8); ac = mfma16(cb, qa[ks], ac); }
;                 if (KIND == 0) ac = ac * __expf(bt);
.LBB0_838:
	s_or_b64 exec, exec, s[12:13]
	v_lshl_add_u64 v[182:183], s[10:11], 0, v[116:117]
	v_mov_b64_e32 v[18:19], s[28:29]
	v_mad_u64_u32 v[18:19], s[0:1], v182, s95, v[18:19]
	v_mad_i32_i24 v19, v183, s95, v19
	s_lshl_b32 s66, s69, 1
	v_lshl_add_u64 v[18:19], v[18:19], 0, s[66:67]
	v_lshlrev_b32_e32 v20, 1, v126
	v_mov_b32_e32 v21, v9
	v_lshl_add_u64 v[18:19], v[18:19], 0, v[20:21]
	s_mov_b64 s[0:1], 0x1000
	v_lshl_add_u64 v[20:21], v[18:19], 0, s[0:1]
	v_add_co_u32_e32 v18, vcc, s50, v18
	v_lshlrev_b64 v[106:107], 8, v[66:67]
	s_nop 0
	v_addc_co_u32_e32 v19, vcc, 0, v19, vcc
	global_load_dwordx4 v[42:45], v[20:21], off offset:64 nt
	global_load_dwordx4 v[38:41], v[20:21], off offset:128 nt
	global_load_dwordx4 v[34:37], v[20:21], off offset:192 nt
	global_load_dwordx4 v[30:33], v[20:21], off offset:256 nt
	global_load_dwordx4 v[26:29], v[20:21], off offset:320 nt
	global_load_dwordx4 v[22:25], v[20:21], off offset:384 nt
	global_load_dwordx4 v[46:49], v[18:19], off nt
	s_nop 0
	global_load_dwordx4 v[18:21], v[20:21], off offset:448 nt
	s_waitcnt lgkmcnt(0)
	s_barrier
	s_waitcnt vmcnt(11)
	ds_write_b128 v236, v[4:7]
	s_waitcnt vmcnt(9)
	ds_write_b128 v237, v[14:17]
	ds_write_b128 v238, v[0:3]
	s_waitcnt vmcnt(8)
	ds_write_b128 v239, v[10:13]
	s_waitcnt lgkmcnt(0)
	s_barrier
	ds_read_b128 v[0:3], v240
	ds_read_b128 v[4:7], v240 offset:64
	s_waitcnt lgkmcnt(1)
	v_mfma_f32_16x16x32_bf16 v[0:3], v[0:3], v[62:65], 0
	v_or_b32_e32 v14, 64, v106
	v_mov_b32_e32 v15, v107
	v_lshl_add_u64 v[10:11], v[14:15], 0, v[148:149]
	v_lshlrev_b64 v[10:11], 8, v[10:11]
	v_lshl_add_u64 v[14:15], v[14:15], 0, v[176:177]
	v_lshl_add_u64 v[16:17], v[124:125], 0, v[10:11]
	s_waitcnt lgkmcnt(0)
	v_mfma_f32_16x16x32_bf16 v[0:3], v[4:7], v[58:61], v[0:3]
	v_lshlrev_b64 v[4:5], 8, v[14:15]
	ds_read_b128 v[10:13], v240 offset:128
	global_load_dwordx4 v[70:73], v[98:99], off offset:2176 nt
	global_load_dwordx4 v[66:69], v[100:101], off offset:2176 nt
	v_lshl_add_u64 v[14:15], v[124:125], 0, v[4:5]
	ds_read_b128 v[4:7], v240 offset:192
	global_load_dwordx4 v[78:81], v[16:17], off nt
	global_load_dwordx4 v[74:77], v[14:15], off nt
	s_waitcnt lgkmcnt(1)
	v_mfma_f32_16x16x32_bf16 v[0:3], v[10:13], v[54:57], v[0:3]
	v_mul_f32_e32 v10, 0x3fb8aa3b, v82
	v_exp_f32_e32 v186, v10
	s_waitcnt lgkmcnt(0)
	v_mfma_f32_16x16x32_bf16 v[0:3], v[4:7], v[50:53], v[0:3]
	s_nop 7
	v_pk_mul_f32 v[2:3], v[186:187], v[2:3] op_sel_hi:[0,1]
	v_pk_mul_f32 v[0:1], v[186:187], v[0:1] op_sel_hi:[0,1]
	s_and_saveexec_b64 s[10:11], s[46:47]
	s_cbranch_execz .LBB0_842
	s_mov_b64 s[12:13], 0
	v_mov_b32_e32 v4, v231
	v_mov_b32_e32 v5, v230
	v_mov_b32_e32 v6, v229

; DEVI void lds_barrier() { asm volatile("s_waitcnt lgkmcnt(0)\n\ts_barrier" ::: "memory"); }
; DEVI f32x4 mfma16(bf16x8 a, bf16x8 b, f32x4 c) { return __builtin_amdgcn_mfma_f32_16x16x32_bf16(a, b, c, 0, 0, 0); }
; #define MIX_PREF(qq, bb) do { _Pragma("unroll") for (int k = 0; k < 2; ++k) { const int i = tid + k * 512; \
;             pv[bb][k] = *(const u32x4*)(a.proj + (tok0 + (i >> 3)) * 3072 + 1024 + h * 256 + (qq) * 64 + (i & 7) * 8); \
;             pc[bb][k] = *(const u32x4*)(a.states + ((size_t)item * 256 + (qq) * 64 + (i >> 4)) * 128 + (i & 15) * 8); } } while (0)
; template <int KIND>
; DEVI void mix_out_phase(unsigned char* smem, const MixArgs a) {
;     ...
;             lds_barrier();
; #pragma unroll
;             for (int k = 0; k < 2; ++k) { const int i = tid + k * 512; *(u32x4*)(VT + (i >> 3) * VQP + (i & 7) * 8) = pv[0][k]; *(u32x4*)(CT + (i >> 4) * LP + (i & 15) * 8) = pc[0][k]; }
;             lds_barrier();
;             if (qv < 3) MIX_PREF(qv + 1, 0);
; #pragma unroll
;             for (int n = 0; n < 4; ++n) { f32x4 ac = (f32x4){0.f, 0.f, 0.f, 0.f};
; #pragma unroll
;                 for (int ks = 0; ks < 4; ++ks) { const bf16x8 cb = *(const bf16x8*)(CT + (32 * (n >> 1) + 8 * (fr >> 2) + 4 * (n & 1) + (fr & 3)) * LP + ks * 32 + fq * 8); ac = mfma16(cb, qa[ks], ac); }
;                 if (KIND == 0) ac = ac * __expf(bt);
.LBB0_854:
	s_or_b64 exec, exec, s[10:11]
	s_waitcnt lgkmcnt(0)
	s_barrier
	s_waitcnt vmcnt(3)
	ds_write_b128 v236, v[70:73]
	s_waitcnt vmcnt(1)
	ds_write_b128 v237, v[78:81]
	ds_write_b128 v238, v[66:69]
	s_waitcnt vmcnt(0)
	ds_write_b128 v239, v[74:77]
	s_waitcnt lgkmcnt(0)
	s_barrier
	ds_read_b128 v[66:69], v240
	ds_read_b128 v[70:73], v240 offset:64
	v_or_b32_e32 v78, 0x80, v106
	v_mov_b32_e32 v79, v107
	v_lshl_add_u64 v[74:75], v[78:79], 0, v[148:149]
	v_lshlrev_b64 v[74:75], 8, v[74:75]
	v_lshl_add_u64 v[78:79], v[78:79], 0, v[176:177]
	v_lshl_add_u64 v[80:81], v[124:125], 0, v[74:75]
	s_waitcnt lgkmcnt(1)
	v_mfma_f32_16x16x32_bf16 v[66:69], v[66:69], v[62:65], 0
	ds_read_b128 v[74:77], v240 offset:128
	global_load_dwordx4 v[86:89], v[98:99], off offset:2304 nt
	global_load_dwordx4 v[82:85], v[100:101], off offset:2304 nt
	s_waitcnt lgkmcnt(1)
	v_mfma_f32_16x16x32_bf16 v[66:69], v[70:73], v[58:61], v[66:69]
	v_lshlrev_b64 v[70:71], 8, v[78:79]
	v_lshl_add_u64 v[78:79], v[124:125], 0, v[70:71]
	ds_read_b128 v[70:73], v240 offset:192
	global_load_dwordx4 v[94:97], v[80:81], off nt
	global_load_dwordx4 v[90:93], v[78:79], off nt
	s_waitcnt lgkmcnt(1)
	v_mfma_f32_16x16x32_bf16 v[66:69], v[74:77], v[54:57], v[66:69]
	s_waitcnt lgkmcnt(0)
	v_mfma_f32_16x16x32_bf16 v[66:69], v[70:73], v[50:53], v[66:69]
	v_mov_b32_e32 v70, v186
	v_mov_b32_e32 v71, v186
	s_nop 5
	v_pk_mul_f32 v[68:69], v[70:71], v[68:69]
	v_pk_mul_f32 v[66:67], v[186:187], v[66:67]
	s_and_saveexec_b64 s[10:11], s[46:47]
	s_cbranch_execz .LBB0_858
	s_mov_b64 s[12:13], 0
	v_mov_b32_e32 v70, v231
	v_mov_b32_e32 v71, v230
	v_mov_b32_e32 v72, v229

; DEVI void lds_barrier() { asm volatile("s_waitcnt lgkmcnt(0)\n\ts_barrier" ::: "memory"); }
; DEVI f32x4 mfma16(bf16x8 a, bf16x8 b, f32x4 c) { return __builtin_amdgcn_mfma_f32_16x16x32_bf16(a, b, c, 0, 0, 0); }
; #define MIX_PREF(qq, bb) do { _Pragma("unroll") for (int k = 0; k < 2; ++k) { const int i = tid + k * 512; \
;             pv[bb][k] = *(const u32x4*)(a.proj + (tok0 + (i >> 3)) * 3072 + 1024 + h * 256 + (qq) * 64 + (i & 7) * 8); \
;             pc[bb][k] = *(const u32x4*)(a.states + ((size_t)item * 256 + (qq) * 64 + (i >> 4)) * 128 + (i & 15) * 8); } } while (0)
; template <int KIND>
; DEVI void mix_out_phase(unsigned char* smem, const MixArgs a) {
;     ...
;             lds_barrier();
; #pragma unroll
;             for (int k = 0; k < 2; ++k) { const int i = tid + k * 512; *(u32x4*)(VT + (i >> 3) * VQP + (i & 7) * 8) = pv[0][k]; *(u32x4*)(CT + (i >> 4) * LP + (i & 15) * 8) = pc[0][k]; }
;             lds_barrier();
;             if (qv < 3) MIX_PREF(qv + 1, 0);
; #pragma unroll
;             for (int n = 0; n < 4; ++n) { f32x4 ac = (f32x4){0.f, 0.f, 0.f, 0.f};
; #pragma unroll
;                 for (int ks = 0; ks < 4; ++ks) { const bf16x8 cb = *(const bf16x8*)(CT + (32 * (n >> 1) + 8 * (fr >> 2) + 4 * (n & 1) + (fr & 3)) * LP + ks * 32 + fq * 8); ac = mfma16(cb, qa[ks], ac); }
;                 if (KIND == 0) ac = ac * __expf(bt);
.LBB0_870:
	s_or_b64 exec, exec, s[10:11]
	s_waitcnt lgkmcnt(0)
	s_barrier
	s_waitcnt vmcnt(3)
	ds_write_b128 v236, v[86:89]
	s_waitcnt vmcnt(1)
	ds_write_b128 v237, v[94:97]
	ds_write_b128 v238, v[82:85]
	s_waitcnt vmcnt(0)
	ds_write_b128 v239, v[90:93]
	s_waitcnt lgkmcnt(0)
	s_barrier
	ds_read_b128 v[82:85], v240
	ds_read_b128 v[86:89], v240 offset:64
	v_or_b32_e32 v106, 0xc0, v106
	v_lshl_add_u64 v[90:91], v[106:107], 0, v[148:149]
	v_lshlrev_b64 v[90:91], 8, v[90:91]
	v_lshl_add_u64 v[108:109], v[124:125], 0, v[90:91]
	ds_read_b128 v[90:93], v240 offset:128
	global_load_dwordx4 v[102:105], v[98:99], off offset:2432 nt
	global_load_dwordx4 v[94:97], v[100:101], off offset:2432 nt
	s_waitcnt lgkmcnt(2)
	v_mfma_f32_16x16x32_bf16 v[82:85], v[82:85], v[62:65], 0
	v_lshl_add_u64 v[98:99], v[106:107], 0, v[176:177]
	s_waitcnt lgkmcnt(1)
	v_mfma_f32_16x16x32_bf16 v[82:85], v[86:89], v[58:61], v[82:85]
	v_lshlrev_b64 v[86:87], 8, v[98:99]
	v_lshl_add_u64 v[98:99], v[124:125], 0, v[86:87]
	ds_read_b128 v[86:89], v240 offset:192
	global_load_dwordx4 v[110:113], v[108:109], off nt
	s_nop 0
	global_load_dwordx4 v[106:109], v[98:99], off nt
	s_waitcnt lgkmcnt(1)
	v_mfma_f32_16x16x32_bf16 v[82:85], v[90:93], v[54:57], v[82:85]
	s_waitcnt lgkmcnt(0)
	v_mfma_f32_16x16x32_bf16 v[82:85], v[86:89], v[50:53], v[82:85]
	v_mov_b32_e32 v86, v186
	v_mov_b32_e32 v87, v186
	s_nop 5
	v_pk_mul_f32 v[84:85], v[86:87], v[84:85]
	v_pk_mul_f32 v[82:83], v[186:187], v[82:83]
	s_and_saveexec_b64 s[10:11], s[46:47]
	s_cbranch_execz .LBB0_874
	s_mov_b64 s[12:13], 0
	v_mov_b32_e32 v86, v231
	v_mov_b32_e32 v87, v230
	v_mov_b32_e32 v88, v229
